# forward substitution: one wait state added between a packed-FMA result and its first reader (hazard hygiene); otherwise same as the blocked V^T version
# baseline (speedup 1.0000x reference)
.Lfs_start:
	v_readlane_b32 s22, v253, 47
	v_readlane_b32 s23, v253, 48
	v_mov_b32_e32 v233, 0xcc00
	s_lshl_b64 s[0:1], s[14:15], 10
	v_readlane_b32 s11, v253, 49
	s_nop 1
	s_add_u32 s0, s11, s0
	v_readlane_b32 s11, v253, 50
	s_nop 1
	s_addc_u32 s1, s11, s1
	s_lshl_b32 s11, s53, 1
	s_add_u32 s0, s0, s11
	s_addc_u32 s1, s1, 0
	ds_read_u16 v106, v9 offset:0
	ds_read_u16 v107, v9 offset:272
	ds_read_u16 v108, v9 offset:544
	ds_read_u16 v109, v9 offset:816
	ds_read_u16 v110, v9 offset:1088
	ds_read_u16 v111, v9 offset:1360
	ds_read_u16 v112, v9 offset:1632
	ds_read_u16 v113, v9 offset:1904
	ds_read_u16 v114, v9 offset:2176
	ds_read_u16 v115, v9 offset:2448
	ds_read_u16 v116, v9 offset:2720
	ds_read_u16 v117, v9 offset:2992
	ds_read_u16 v118, v9 offset:3264
	ds_read_u16 v119, v9 offset:3536
	ds_read_u16 v120, v9 offset:3808
	ds_read_u16 v121, v9 offset:4080
	ds_read_u16 v122, v9 offset:4352
	ds_read_u16 v123, v9 offset:4624
	ds_read_u16 v124, v9 offset:4896
	ds_read_u16 v125, v9 offset:5168
	ds_read_u16 v126, v9 offset:5440
	ds_read_u16 v127, v9 offset:5712
	ds_read_u16 v128, v9 offset:5984
	ds_read_u16 v129, v9 offset:6256
	ds_read_u16 v130, v9 offset:6528
	ds_read_u16 v131, v9 offset:6800
	ds_read_u16 v132, v9 offset:7072
	ds_read_u16 v133, v9 offset:7344
	ds_read_u16 v134, v9 offset:7616
	ds_read_u16 v135, v9 offset:7888
	ds_read_u16 v136, v9 offset:8160
	ds_read_u16 v137, v9 offset:8432
	ds_read_u16 v138, v9 offset:8704
	ds_read_u16 v139, v9 offset:8976
	ds_read_u16 v140, v9 offset:9248
	ds_read_u16 v141, v9 offset:9520
	ds_read_u16 v142, v9 offset:9792
	ds_read_u16 v143, v9 offset:10064
	ds_read_u16 v144, v9 offset:10336
	ds_read_u16 v145, v9 offset:10608
	ds_read_u16 v146, v9 offset:10880
	ds_read_u16 v147, v9 offset:11152
	ds_read_u16 v148, v9 offset:11424
	ds_read_u16 v149, v9 offset:11696
	ds_read_u16 v150, v9 offset:11968
	ds_read_u16 v151, v9 offset:12240
	ds_read_u16 v152, v9 offset:12512
	ds_read_u16 v153, v9 offset:12784
	ds_read_u16 v154, v9 offset:13056
	ds_read_u16 v155, v9 offset:13328
	ds_read_u16 v180, v9 offset:13600
	ds_read_u16 v181, v9 offset:13872
	ds_read_u16 v182, v9 offset:14144
	ds_read_u16 v183, v9 offset:14416
	ds_read_u16 v184, v9 offset:14688
	ds_read_u16 v185, v9 offset:14960
	ds_read_u16 v186, v9 offset:15232
	ds_read_u16 v187, v9 offset:15504
	ds_read_u16 v188, v9 offset:15776
	ds_read_u16 v189, v9 offset:16048
	ds_read_u16 v190, v9 offset:16320
	ds_read_u16 v191, v9 offset:16592
	ds_read_u16 v192, v9 offset:16864
	ds_read_u16 v193, v9 offset:17136
	ds_read_b128 v[30:33], v233 offset:17664
	ds_read_b128 v[34:37], v233 offset:17680
	ds_read_b128 v[38:41], v233 offset:17696
	ds_read_b128 v[42:45], v233 offset:17712
	ds_read_b128 v[46:49], v233 offset:17728
	ds_read_b128 v[50:53], v233 offset:17744
	ds_read_b128 v[54:57], v233 offset:17760
	ds_read_b128 v[58:61], v233 offset:17776
	ds_read_b128 v[62:65], v233 offset:18176
	ds_read_b128 v[66:69], v233 offset:18192
	ds_read_b128 v[70:73], v233 offset:18208
	ds_read_b128 v[194:197], v233 offset:18224
	ds_read_b128 v[198:201], v233 offset:18240
	ds_read_b128 v[202:205], v233 offset:18256
	ds_read_b128 v[206:209], v233 offset:18272
	ds_read_b128 v[226:229], v233 offset:18288
	s_waitcnt lgkmcnt(0)
	v_cndmask_b32_e64 v62, 1.0, v62, s[22:23]
	v_lshlrev_b32_e32 v106, 16, v106
	v_mul_f32_e32 v30, v30, v62
	v_mul_f32_e32 v106, v30, v106
	v_cndmask_b32_e64 v63, 1.0, v63, s[22:23]
	v_lshlrev_b32_e32 v107, 16, v107
	v_mul_f32_e32 v31, v31, v63
	v_mul_f32_e32 v107, v31, v107
	v_cndmask_b32_e64 v64, 1.0, v64, s[22:23]
	v_lshlrev_b32_e32 v108, 16, v108
	v_mul_f32_e32 v32, v32, v64
	v_mul_f32_e32 v108, v32, v108
	v_cndmask_b32_e64 v65, 1.0, v65, s[22:23]
	v_lshlrev_b32_e32 v109, 16, v109
	v_mul_f32_e32 v33, v33, v65
	v_mul_f32_e32 v109, v33, v109
	v_cndmask_b32_e64 v66, 1.0, v66, s[22:23]
	v_lshlrev_b32_e32 v110, 16, v110
	v_mul_f32_e32 v34, v34, v66
	v_mul_f32_e32 v110, v34, v110
	v_cndmask_b32_e64 v67, 1.0, v67, s[22:23]
	v_lshlrev_b32_e32 v111, 16, v111
	v_mul_f32_e32 v35, v35, v67
	v_mul_f32_e32 v111, v35, v111
	v_cndmask_b32_e64 v68, 1.0, v68, s[22:23]
	v_lshlrev_b32_e32 v112, 16, v112
	v_mul_f32_e32 v36, v36, v68
	v_mul_f32_e32 v112, v36, v112
	v_cndmask_b32_e64 v69, 1.0, v69, s[22:23]
	v_lshlrev_b32_e32 v113, 16, v113
	v_mul_f32_e32 v37, v37, v69
	v_mul_f32_e32 v113, v37, v113
	v_cndmask_b32_e64 v70, 1.0, v70, s[22:23]
	v_lshlrev_b32_e32 v114, 16, v114
	v_mul_f32_e32 v38, v38, v70
	v_mul_f32_e32 v114, v38, v114
	v_cndmask_b32_e64 v71, 1.0, v71, s[22:23]
	v_lshlrev_b32_e32 v115, 16, v115
	v_mul_f32_e32 v39, v39, v71
	v_mul_f32_e32 v115, v39, v115
	v_cndmask_b32_e64 v72, 1.0, v72, s[22:23]
	v_lshlrev_b32_e32 v116, 16, v116
	v_mul_f32_e32 v40, v40, v72
	v_mul_f32_e32 v116, v40, v116
	v_cndmask_b32_e64 v73, 1.0, v73, s[22:23]
	v_lshlrev_b32_e32 v117, 16, v117
	v_mul_f32_e32 v41, v41, v73
	v_mul_f32_e32 v117, v41, v117
	v_cndmask_b32_e64 v194, 1.0, v194, s[22:23]
	v_lshlrev_b32_e32 v118, 16, v118
	v_mul_f32_e32 v42, v42, v194
	v_mul_f32_e32 v118, v42, v118
	v_cndmask_b32_e64 v195, 1.0, v195, s[22:23]
	v_lshlrev_b32_e32 v119, 16, v119
	v_mul_f32_e32 v43, v43, v195
	v_mul_f32_e32 v119, v43, v119
	v_cndmask_b32_e64 v196, 1.0, v196, s[22:23]
	v_lshlrev_b32_e32 v120, 16, v120
	v_mul_f32_e32 v44, v44, v196
	v_mul_f32_e32 v120, v44, v120
	v_cndmask_b32_e64 v197, 1.0, v197, s[22:23]
	v_lshlrev_b32_e32 v121, 16, v121
	v_mul_f32_e32 v45, v45, v197
	v_mul_f32_e32 v121, v45, v121
	v_cndmask_b32_e64 v198, 1.0, v198, s[22:23]
	v_lshlrev_b32_e32 v122, 16, v122
	v_mul_f32_e32 v46, v46, v198
	v_mul_f32_e32 v122, v46, v122
	v_cndmask_b32_e64 v199, 1.0, v199, s[22:23]
	v_lshlrev_b32_e32 v123, 16, v123
	v_mul_f32_e32 v47, v47, v199
	v_mul_f32_e32 v123, v47, v123
	v_cndmask_b32_e64 v200, 1.0, v200, s[22:23]
	v_lshlrev_b32_e32 v124, 16, v124
	v_mul_f32_e32 v48, v48, v200
	v_mul_f32_e32 v124, v48, v124
	v_cndmask_b32_e64 v201, 1.0, v201, s[22:23]
	v_lshlrev_b32_e32 v125, 16, v125
	v_mul_f32_e32 v49, v49, v201
	v_mul_f32_e32 v125, v49, v125
	v_cndmask_b32_e64 v202, 1.0, v202, s[22:23]
	v_lshlrev_b32_e32 v126, 16, v126
	v_mul_f32_e32 v50, v50, v202
	v_mul_f32_e32 v126, v50, v126
	v_cndmask_b32_e64 v203, 1.0, v203, s[22:23]
	v_lshlrev_b32_e32 v127, 16, v127
	v_mul_f32_e32 v51, v51, v203
	v_mul_f32_e32 v127, v51, v127
	v_cndmask_b32_e64 v204, 1.0, v204, s[22:23]
	v_lshlrev_b32_e32 v128, 16, v128
	v_mul_f32_e32 v52, v52, v204
	v_mul_f32_e32 v128, v52, v128
	v_cndmask_b32_e64 v205, 1.0, v205, s[22:23]
	v_lshlrev_b32_e32 v129, 16, v129
	v_mul_f32_e32 v53, v53, v205
	v_mul_f32_e32 v129, v53, v129
	v_cndmask_b32_e64 v206, 1.0, v206, s[22:23]
	v_lshlrev_b32_e32 v130, 16, v130
	v_mul_f32_e32 v54, v54, v206
	v_mul_f32_e32 v130, v54, v130
	v_cndmask_b32_e64 v207, 1.0, v207, s[22:23]
	v_lshlrev_b32_e32 v131, 16, v131
	v_mul_f32_e32 v55, v55, v207
	v_mul_f32_e32 v131, v55, v131
	v_cndmask_b32_e64 v208, 1.0, v208, s[22:23]
	v_lshlrev_b32_e32 v132, 16, v132
	v_mul_f32_e32 v56, v56, v208
	v_mul_f32_e32 v132, v56, v132
	v_cndmask_b32_e64 v209, 1.0, v209, s[22:23]
	v_lshlrev_b32_e32 v133, 16, v133
	v_mul_f32_e32 v57, v57, v209
	v_mul_f32_e32 v133, v57, v133
	v_cndmask_b32_e64 v226, 1.0, v226, s[22:23]
	v_lshlrev_b32_e32 v134, 16, v134
	v_mul_f32_e32 v58, v58, v226
	v_mul_f32_e32 v134, v58, v134
	v_cndmask_b32_e64 v227, 1.0, v227, s[22:23]
	v_lshlrev_b32_e32 v135, 16, v135
	v_mul_f32_e32 v59, v59, v227
	v_mul_f32_e32 v135, v59, v135
	v_cndmask_b32_e64 v228, 1.0, v228, s[22:23]
	v_lshlrev_b32_e32 v136, 16, v136
	v_mul_f32_e32 v60, v60, v228
	v_mul_f32_e32 v136, v60, v136
	v_cndmask_b32_e64 v229, 1.0, v229, s[22:23]
	v_lshlrev_b32_e32 v137, 16, v137
	v_mul_f32_e32 v61, v61, v229
	v_mul_f32_e32 v137, v61, v137
	ds_read_b128 v[30:33], v233 offset:17792
	ds_read_b128 v[34:37], v233 offset:17808
	ds_read_b128 v[38:41], v233 offset:17824
	ds_read_b128 v[42:45], v233 offset:17840
	ds_read_b128 v[46:49], v233 offset:17856
	ds_read_b128 v[50:53], v233 offset:17872
	ds_read_b128 v[54:57], v233 offset:17888
	ds_read_b128 v[58:61], v233 offset:17904
	ds_read_b128 v[62:65], v233 offset:18304
	ds_read_b128 v[66:69], v233 offset:18320
	ds_read_b128 v[70:73], v233 offset:18336
	ds_read_b128 v[194:197], v233 offset:18352
	ds_read_b128 v[198:201], v233 offset:18368
	ds_read_b128 v[202:205], v233 offset:18384
	ds_read_b128 v[206:209], v233 offset:18400
	ds_read_b128 v[226:229], v233 offset:18416
	s_waitcnt lgkmcnt(0)
	v_cndmask_b32_e64 v62, 1.0, v62, s[22:23]
	v_lshlrev_b32_e32 v138, 16, v138
	v_mul_f32_e32 v30, v30, v62
	v_mul_f32_e32 v138, v30, v138
	v_cndmask_b32_e64 v63, 1.0, v63, s[22:23]
	v_lshlrev_b32_e32 v139, 16, v139
	v_mul_f32_e32 v31, v31, v63
	v_mul_f32_e32 v139, v31, v139
	v_cndmask_b32_e64 v64, 1.0, v64, s[22:23]
	v_lshlrev_b32_e32 v140, 16, v140
	v_mul_f32_e32 v32, v32, v64
	v_mul_f32_e32 v140, v32, v140
	v_cndmask_b32_e64 v65, 1.0, v65, s[22:23]
	v_lshlrev_b32_e32 v141, 16, v141
	v_mul_f32_e32 v33, v33, v65
	v_mul_f32_e32 v141, v33, v141
	v_cndmask_b32_e64 v66, 1.0, v66, s[22:23]
	v_lshlrev_b32_e32 v142, 16, v142
	v_mul_f32_e32 v34, v34, v66
	v_mul_f32_e32 v142, v34, v142
	v_cndmask_b32_e64 v67, 1.0, v67, s[22:23]
	v_lshlrev_b32_e32 v143, 16, v143
	v_mul_f32_e32 v35, v35, v67
	v_mul_f32_e32 v143, v35, v143
	v_cndmask_b32_e64 v68, 1.0, v68, s[22:23]
	v_lshlrev_b32_e32 v144, 16, v144
	v_mul_f32_e32 v36, v36, v68
	v_mul_f32_e32 v144, v36, v144
	v_cndmask_b32_e64 v69, 1.0, v69, s[22:23]
	v_lshlrev_b32_e32 v145, 16, v145
	v_mul_f32_e32 v37, v37, v69
	v_mul_f32_e32 v145, v37, v145
	v_cndmask_b32_e64 v70, 1.0, v70, s[22:23]
	v_lshlrev_b32_e32 v146, 16, v146
	v_mul_f32_e32 v38, v38, v70
	v_mul_f32_e32 v146, v38, v146
	v_cndmask_b32_e64 v71, 1.0, v71, s[22:23]
	v_lshlrev_b32_e32 v147, 16, v147
	v_mul_f32_e32 v39, v39, v71
	v_mul_f32_e32 v147, v39, v147
	v_cndmask_b32_e64 v72, 1.0, v72, s[22:23]
	v_lshlrev_b32_e32 v148, 16, v148
	v_mul_f32_e32 v40, v40, v72
	v_mul_f32_e32 v148, v40, v148
	v_cndmask_b32_e64 v73, 1.0, v73, s[22:23]
	v_lshlrev_b32_e32 v149, 16, v149
	v_mul_f32_e32 v41, v41, v73
	v_mul_f32_e32 v149, v41, v149
	v_cndmask_b32_e64 v194, 1.0, v194, s[22:23]
	v_lshlrev_b32_e32 v150, 16, v150
	v_mul_f32_e32 v42, v42, v194
	v_mul_f32_e32 v150, v42, v150
	v_cndmask_b32_e64 v195, 1.0, v195, s[22:23]
	v_lshlrev_b32_e32 v151, 16, v151
	v_mul_f32_e32 v43, v43, v195
	v_mul_f32_e32 v151, v43, v151
	v_cndmask_b32_e64 v196, 1.0, v196, s[22:23]
	v_lshlrev_b32_e32 v152, 16, v152
	v_mul_f32_e32 v44, v44, v196
	v_mul_f32_e32 v152, v44, v152
	v_cndmask_b32_e64 v197, 1.0, v197, s[22:23]
	v_lshlrev_b32_e32 v153, 16, v153
	v_mul_f32_e32 v45, v45, v197
	v_mul_f32_e32 v153, v45, v153
	v_cndmask_b32_e64 v198, 1.0, v198, s[22:23]
	v_lshlrev_b32_e32 v154, 16, v154
	v_mul_f32_e32 v46, v46, v198
	v_mul_f32_e32 v154, v46, v154
	v_cndmask_b32_e64 v199, 1.0, v199, s[22:23]
	v_lshlrev_b32_e32 v155, 16, v155
	v_mul_f32_e32 v47, v47, v199
	v_mul_f32_e32 v155, v47, v155
	v_cndmask_b32_e64 v200, 1.0, v200, s[22:23]
	v_lshlrev_b32_e32 v180, 16, v180
	v_mul_f32_e32 v48, v48, v200
	v_mul_f32_e32 v180, v48, v180
	v_cndmask_b32_e64 v201, 1.0, v201, s[22:23]
	v_lshlrev_b32_e32 v181, 16, v181
	v_mul_f32_e32 v49, v49, v201
	v_mul_f32_e32 v181, v49, v181
	v_cndmask_b32_e64 v202, 1.0, v202, s[22:23]
	v_lshlrev_b32_e32 v182, 16, v182
	v_mul_f32_e32 v50, v50, v202
	v_mul_f32_e32 v182, v50, v182
	v_cndmask_b32_e64 v203, 1.0, v203, s[22:23]
	v_lshlrev_b32_e32 v183, 16, v183
	v_mul_f32_e32 v51, v51, v203
	v_mul_f32_e32 v183, v51, v183
	v_cndmask_b32_e64 v204, 1.0, v204, s[22:23]
	v_lshlrev_b32_e32 v184, 16, v184
	v_mul_f32_e32 v52, v52, v204
	v_mul_f32_e32 v184, v52, v184
	v_cndmask_b32_e64 v205, 1.0, v205, s[22:23]
	v_lshlrev_b32_e32 v185, 16, v185
	v_mul_f32_e32 v53, v53, v205
	v_mul_f32_e32 v185, v53, v185
	v_cndmask_b32_e64 v206, 1.0, v206, s[22:23]
	v_lshlrev_b32_e32 v186, 16, v186
	v_mul_f32_e32 v54, v54, v206
	v_mul_f32_e32 v186, v54, v186
	v_cndmask_b32_e64 v207, 1.0, v207, s[22:23]
	v_lshlrev_b32_e32 v187, 16, v187
	v_mul_f32_e32 v55, v55, v207
	v_mul_f32_e32 v187, v55, v187
	v_cndmask_b32_e64 v208, 1.0, v208, s[22:23]
	v_lshlrev_b32_e32 v188, 16, v188
	v_mul_f32_e32 v56, v56, v208
	v_mul_f32_e32 v188, v56, v188
	v_cndmask_b32_e64 v209, 1.0, v209, s[22:23]
	v_lshlrev_b32_e32 v189, 16, v189
	v_mul_f32_e32 v57, v57, v209
	v_mul_f32_e32 v189, v57, v189
	v_cndmask_b32_e64 v226, 1.0, v226, s[22:23]
	v_lshlrev_b32_e32 v190, 16, v190
	v_mul_f32_e32 v58, v58, v226
	v_mul_f32_e32 v190, v58, v190
	v_cndmask_b32_e64 v227, 1.0, v227, s[22:23]
	v_lshlrev_b32_e32 v191, 16, v191
	v_mul_f32_e32 v59, v59, v227
	v_mul_f32_e32 v191, v59, v191
	v_cndmask_b32_e64 v228, 1.0, v228, s[22:23]
	v_lshlrev_b32_e32 v192, 16, v192
	v_mul_f32_e32 v60, v60, v228
	v_mul_f32_e32 v192, v60, v192
	v_cndmask_b32_e64 v229, 1.0, v229, s[22:23]
	v_lshlrev_b32_e32 v193, 16, v193
	v_mul_f32_e32 v61, v61, v229
	v_mul_f32_e32 v193, v61, v193
	ds_read_b128 v[30:33], v233 offset:0
	ds_read_b128 v[34:37], v233 offset:16
	ds_read_b128 v[38:41], v233 offset:32
	ds_read_b128 v[42:45], v233 offset:48
	ds_read_b128 v[46:49], v233 offset:64
	ds_read_b128 v[50:53], v233 offset:80
	ds_read_b128 v[54:57], v233 offset:96
	ds_read_b128 v[58:61], v233 offset:112
	ds_read_b128 v[62:65], v233 offset:128
	ds_read_b128 v[66:69], v233 offset:144
	ds_read_b128 v[70:73], v233 offset:160
	ds_read_b128 v[194:197], v233 offset:176
	ds_read_b128 v[198:201], v233 offset:192
	ds_read_b128 v[202:205], v233 offset:208
	ds_read_b128 v[206:209], v233 offset:224
	ds_read_b128 v[226:229], v233 offset:240
	s_nop 0
	v_mov_b32_e32 v230, v106
	v_cvt_pk_bf16_f32 v232, v230, v230
	global_store_short v28, v232, s[0:1]
	s_add_u32 s0, s0, 0x400
	s_addc_u32 s1, s1, 0
	s_waitcnt lgkmcnt(14)
	v_pk_fma_f32 v[106:107], v[30:31], v[230:231], v[106:107] op_sel_hi:[1,0,1] neg_lo:[0,1,0] neg_hi:[0,1,0]
	v_pk_fma_f32 v[108:109], v[32:33], v[230:231], v[108:109] op_sel_hi:[1,0,1] neg_lo:[0,1,0] neg_hi:[0,1,0]
	ds_read_b128 v[30:33], v233 offset:272
	v_pk_fma_f32 v[110:111], v[34:35], v[230:231], v[110:111] op_sel_hi:[1,0,1] neg_lo:[0,1,0] neg_hi:[0,1,0]
	v_pk_fma_f32 v[112:113], v[36:37], v[230:231], v[112:113] op_sel_hi:[1,0,1] neg_lo:[0,1,0] neg_hi:[0,1,0]
	ds_read_b128 v[34:37], v233 offset:288
	s_waitcnt lgkmcnt(14)
	v_pk_fma_f32 v[114:115], v[38:39], v[230:231], v[114:115] op_sel_hi:[1,0,1] neg_lo:[0,1,0] neg_hi:[0,1,0]
	v_pk_fma_f32 v[116:117], v[40:41], v[230:231], v[116:117] op_sel_hi:[1,0,1] neg_lo:[0,1,0] neg_hi:[0,1,0]
	ds_read_b128 v[38:41], v233 offset:304
	v_pk_fma_f32 v[118:119], v[42:43], v[230:231], v[118:119] op_sel_hi:[1,0,1] neg_lo:[0,1,0] neg_hi:[0,1,0]
	v_pk_fma_f32 v[120:121], v[44:45], v[230:231], v[120:121] op_sel_hi:[1,0,1] neg_lo:[0,1,0] neg_hi:[0,1,0]
	ds_read_b128 v[42:45], v233 offset:320
	s_waitcnt lgkmcnt(14)
	v_pk_fma_f32 v[122:123], v[46:47], v[230:231], v[122:123] op_sel_hi:[1,0,1] neg_lo:[0,1,0] neg_hi:[0,1,0]
	v_pk_fma_f32 v[124:125], v[48:49], v[230:231], v[124:125] op_sel_hi:[1,0,1] neg_lo:[0,1,0] neg_hi:[0,1,0]
	ds_read_b128 v[46:49], v233 offset:336
	v_pk_fma_f32 v[126:127], v[50:51], v[230:231], v[126:127] op_sel_hi:[1,0,1] neg_lo:[0,1,0] neg_hi:[0,1,0]
	v_pk_fma_f32 v[128:129], v[52:53], v[230:231], v[128:129] op_sel_hi:[1,0,1] neg_lo:[0,1,0] neg_hi:[0,1,0]
	ds_read_b128 v[50:53], v233 offset:352
	s_waitcnt lgkmcnt(14)
	v_pk_fma_f32 v[130:131], v[54:55], v[230:231], v[130:131] op_sel_hi:[1,0,1] neg_lo:[0,1,0] neg_hi:[0,1,0]
	v_pk_fma_f32 v[132:133], v[56:57], v[230:231], v[132:133] op_sel_hi:[1,0,1] neg_lo:[0,1,0] neg_hi:[0,1,0]
	ds_read_b128 v[54:57], v233 offset:368
	v_pk_fma_f32 v[134:135], v[58:59], v[230:231], v[134:135] op_sel_hi:[1,0,1] neg_lo:[0,1,0] neg_hi:[0,1,0]
	v_pk_fma_f32 v[136:137], v[60:61], v[230:231], v[136:137] op_sel_hi:[1,0,1] neg_lo:[0,1,0] neg_hi:[0,1,0]
	ds_read_b128 v[58:61], v233 offset:384
	s_waitcnt lgkmcnt(14)
	v_pk_fma_f32 v[138:139], v[62:63], v[230:231], v[138:139] op_sel_hi:[1,0,1] neg_lo:[0,1,0] neg_hi:[0,1,0]
	v_pk_fma_f32 v[140:141], v[64:65], v[230:231], v[140:141] op_sel_hi:[1,0,1] neg_lo:[0,1,0] neg_hi:[0,1,0]
	ds_read_b128 v[62:65], v233 offset:400
	v_pk_fma_f32 v[142:143], v[66:67], v[230:231], v[142:143] op_sel_hi:[1,0,1] neg_lo:[0,1,0] neg_hi:[0,1,0]
	v_pk_fma_f32 v[144:145], v[68:69], v[230:231], v[144:145] op_sel_hi:[1,0,1] neg_lo:[0,1,0] neg_hi:[0,1,0]
	ds_read_b128 v[66:69], v233 offset:416
	s_waitcnt lgkmcnt(14)
	v_pk_fma_f32 v[146:147], v[70:71], v[230:231], v[146:147] op_sel_hi:[1,0,1] neg_lo:[0,1,0] neg_hi:[0,1,0]
	v_pk_fma_f32 v[148:149], v[72:73], v[230:231], v[148:149] op_sel_hi:[1,0,1] neg_lo:[0,1,0] neg_hi:[0,1,0]
	ds_read_b128 v[70:73], v233 offset:432
	v_pk_fma_f32 v[150:151], v[194:195], v[230:231], v[150:151] op_sel_hi:[1,0,1] neg_lo:[0,1,0] neg_hi:[0,1,0]
	v_pk_fma_f32 v[152:153], v[196:197], v[230:231], v[152:153] op_sel_hi:[1,0,1] neg_lo:[0,1,0] neg_hi:[0,1,0]
	ds_read_b128 v[194:197], v233 offset:448
	s_waitcnt lgkmcnt(14)
	v_pk_fma_f32 v[154:155], v[198:199], v[230:231], v[154:155] op_sel_hi:[1,0,1] neg_lo:[0,1,0] neg_hi:[0,1,0]
	v_pk_fma_f32 v[180:181], v[200:201], v[230:231], v[180:181] op_sel_hi:[1,0,1] neg_lo:[0,1,0] neg_hi:[0,1,0]
	ds_read_b128 v[198:201], v233 offset:464
	v_pk_fma_f32 v[182:183], v[202:203], v[230:231], v[182:183] op_sel_hi:[1,0,1] neg_lo:[0,1,0] neg_hi:[0,1,0]
	v_pk_fma_f32 v[184:185], v[204:205], v[230:231], v[184:185] op_sel_hi:[1,0,1] neg_lo:[0,1,0] neg_hi:[0,1,0]
	ds_read_b128 v[202:205], v233 offset:480
	s_waitcnt lgkmcnt(14)
	v_pk_fma_f32 v[186:187], v[206:207], v[230:231], v[186:187] op_sel_hi:[1,0,1] neg_lo:[0,1,0] neg_hi:[0,1,0]
	v_pk_fma_f32 v[188:189], v[208:209], v[230:231], v[188:189] op_sel_hi:[1,0,1] neg_lo:[0,1,0] neg_hi:[0,1,0]
	ds_read_b128 v[206:209], v233 offset:496
	v_pk_fma_f32 v[190:191], v[226:227], v[230:231], v[190:191] op_sel_hi:[1,0,1] neg_lo:[0,1,0] neg_hi:[0,1,0]
	v_pk_fma_f32 v[192:193], v[228:229], v[230:231], v[192:193] op_sel_hi:[1,0,1] neg_lo:[0,1,0] neg_hi:[0,1,0]
	ds_read_b128 v[226:229], v233 offset:512
	s_nop 0
	v_mov_b32_e32 v230, v107
	v_cvt_pk_bf16_f32 v232, v230, v230
	global_store_short v28, v232, s[0:1]
	s_add_u32 s0, s0, 0x400
	s_addc_u32 s1, s1, 0
	s_waitcnt lgkmcnt(14)
	v_pk_fma_f32 v[108:109], v[32:33], v[230:231], v[108:109] op_sel_hi:[1,0,1] neg_lo:[0,1,0] neg_hi:[0,1,0]
	ds_read_b128 v[30:33], v233 offset:544
	v_pk_fma_f32 v[110:111], v[34:35], v[230:231], v[110:111] op_sel_hi:[1,0,1] neg_lo:[0,1,0] neg_hi:[0,1,0]
	v_pk_fma_f32 v[112:113], v[36:37], v[230:231], v[112:113] op_sel_hi:[1,0,1] neg_lo:[0,1,0] neg_hi:[0,1,0]
	ds_read_b128 v[34:37], v233 offset:560
	s_waitcnt lgkmcnt(14)
	v_pk_fma_f32 v[114:115], v[38:39], v[230:231], v[114:115] op_sel_hi:[1,0,1] neg_lo:[0,1,0] neg_hi:[0,1,0]
	v_pk_fma_f32 v[116:117], v[40:41], v[230:231], v[116:117] op_sel_hi:[1,0,1] neg_lo:[0,1,0] neg_hi:[0,1,0]
	ds_read_b128 v[38:41], v233 offset:576
	v_pk_fma_f32 v[118:119], v[42:43], v[230:231], v[118:119] op_sel_hi:[1,0,1] neg_lo:[0,1,0] neg_hi:[0,1,0]
	v_pk_fma_f32 v[120:121], v[44:45], v[230:231], v[120:121] op_sel_hi:[1,0,1] neg_lo:[0,1,0] neg_hi:[0,1,0]
	ds_read_b128 v[42:45], v233 offset:592
	s_waitcnt lgkmcnt(14)
	v_pk_fma_f32 v[122:123], v[46:47], v[230:231], v[122:123] op_sel_hi:[1,0,1] neg_lo:[0,1,0] neg_hi:[0,1,0]
	v_pk_fma_f32 v[124:125], v[48:49], v[230:231], v[124:125] op_sel_hi:[1,0,1] neg_lo:[0,1,0] neg_hi:[0,1,0]
	ds_read_b128 v[46:49], v233 offset:608
	v_pk_fma_f32 v[126:127], v[50:51], v[230:231], v[126:127] op_sel_hi:[1,0,1] neg_lo:[0,1,0] neg_hi:[0,1,0]
	v_pk_fma_f32 v[128:129], v[52:53], v[230:231], v[128:129] op_sel_hi:[1,0,1] neg_lo:[0,1,0] neg_hi:[0,1,0]
	ds_read_b128 v[50:53], v233 offset:624
	s_waitcnt lgkmcnt(14)
	v_pk_fma_f32 v[130:131], v[54:55], v[230:231], v[130:131] op_sel_hi:[1,0,1] neg_lo:[0,1,0] neg_hi:[0,1,0]
	v_pk_fma_f32 v[132:133], v[56:57], v[230:231], v[132:133] op_sel_hi:[1,0,1] neg_lo:[0,1,0] neg_hi:[0,1,0]
	ds_read_b128 v[54:57], v233 offset:640
	v_pk_fma_f32 v[134:135], v[58:59], v[230:231], v[134:135] op_sel_hi:[1,0,1] neg_lo:[0,1,0] neg_hi:[0,1,0]
	v_pk_fma_f32 v[136:137], v[60:61], v[230:231], v[136:137] op_sel_hi:[1,0,1] neg_lo:[0,1,0] neg_hi:[0,1,0]
	ds_read_b128 v[58:61], v233 offset:656
	s_waitcnt lgkmcnt(14)
	v_pk_fma_f32 v[138:139], v[62:63], v[230:231], v[138:139] op_sel_hi:[1,0,1] neg_lo:[0,1,0] neg_hi:[0,1,0]
	v_pk_fma_f32 v[140:141], v[64:65], v[230:231], v[140:141] op_sel_hi:[1,0,1] neg_lo:[0,1,0] neg_hi:[0,1,0]
	ds_read_b128 v[62:65], v233 offset:672
	v_pk_fma_f32 v[142:143], v[66:67], v[230:231], v[142:143] op_sel_hi:[1,0,1] neg_lo:[0,1,0] neg_hi:[0,1,0]
	v_pk_fma_f32 v[144:145], v[68:69], v[230:231], v[144:145] op_sel_hi:[1,0,1] neg_lo:[0,1,0] neg_hi:[0,1,0]
	ds_read_b128 v[66:69], v233 offset:688
	s_waitcnt lgkmcnt(14)
	v_pk_fma_f32 v[146:147], v[70:71], v[230:231], v[146:147] op_sel_hi:[1,0,1] neg_lo:[0,1,0] neg_hi:[0,1,0]
	v_pk_fma_f32 v[148:149], v[72:73], v[230:231], v[148:149] op_sel_hi:[1,0,1] neg_lo:[0,1,0] neg_hi:[0,1,0]
	ds_read_b128 v[70:73], v233 offset:704
	v_pk_fma_f32 v[150:151], v[194:195], v[230:231], v[150:151] op_sel_hi:[1,0,1] neg_lo:[0,1,0] neg_hi:[0,1,0]
	v_pk_fma_f32 v[152:153], v[196:197], v[230:231], v[152:153] op_sel_hi:[1,0,1] neg_lo:[0,1,0] neg_hi:[0,1,0]
	ds_read_b128 v[194:197], v233 offset:720
	s_waitcnt lgkmcnt(14)
	v_pk_fma_f32 v[154:155], v[198:199], v[230:231], v[154:155] op_sel_hi:[1,0,1] neg_lo:[0,1,0] neg_hi:[0,1,0]
	v_pk_fma_f32 v[180:181], v[200:201], v[230:231], v[180:181] op_sel_hi:[1,0,1] neg_lo:[0,1,0] neg_hi:[0,1,0]
	ds_read_b128 v[198:201], v233 offset:736
	v_pk_fma_f32 v[182:183], v[202:203], v[230:231], v[182:183] op_sel_hi:[1,0,1] neg_lo:[0,1,0] neg_hi:[0,1,0]
	v_pk_fma_f32 v[184:185], v[204:205], v[230:231], v[184:185] op_sel_hi:[1,0,1] neg_lo:[0,1,0] neg_hi:[0,1,0]
	ds_read_b128 v[202:205], v233 offset:752
	s_waitcnt lgkmcnt(14)
	v_pk_fma_f32 v[186:187], v[206:207], v[230:231], v[186:187] op_sel_hi:[1,0,1] neg_lo:[0,1,0] neg_hi:[0,1,0]
	v_pk_fma_f32 v[188:189], v[208:209], v[230:231], v[188:189] op_sel_hi:[1,0,1] neg_lo:[0,1,0] neg_hi:[0,1,0]
	ds_read_b128 v[206:209], v233 offset:768
	v_pk_fma_f32 v[190:191], v[226:227], v[230:231], v[190:191] op_sel_hi:[1,0,1] neg_lo:[0,1,0] neg_hi:[0,1,0]
	v_pk_fma_f32 v[192:193], v[228:229], v[230:231], v[192:193] op_sel_hi:[1,0,1] neg_lo:[0,1,0] neg_hi:[0,1,0]
	ds_read_b128 v[226:229], v233 offset:784
	s_nop 0
	v_mov_b32_e32 v230, v108
	v_cvt_pk_bf16_f32 v232, v230, v230
	global_store_short v28, v232, s[0:1]
	s_add_u32 s0, s0, 0x400
	s_addc_u32 s1, s1, 0
	s_waitcnt lgkmcnt(14)
	v_pk_fma_f32 v[108:109], v[32:33], v[230:231], v[108:109] op_sel_hi:[1,0,1] neg_lo:[0,1,0] neg_hi:[0,1,0]
	v_pk_fma_f32 v[110:111], v[34:35], v[230:231], v[110:111] op_sel_hi:[1,0,1] neg_lo:[0,1,0] neg_hi:[0,1,0]
	v_pk_fma_f32 v[112:113], v[36:37], v[230:231], v[112:113] op_sel_hi:[1,0,1] neg_lo:[0,1,0] neg_hi:[0,1,0]
	ds_read_b128 v[34:37], v233 offset:832
	s_waitcnt lgkmcnt(13)
	v_pk_fma_f32 v[114:115], v[38:39], v[230:231], v[114:115] op_sel_hi:[1,0,1] neg_lo:[0,1,0] neg_hi:[0,1,0]
	v_pk_fma_f32 v[116:117], v[40:41], v[230:231], v[116:117] op_sel_hi:[1,0,1] neg_lo:[0,1,0] neg_hi:[0,1,0]
	ds_read_b128 v[38:41], v233 offset:848
	v_pk_fma_f32 v[118:119], v[42:43], v[230:231], v[118:119] op_sel_hi:[1,0,1] neg_lo:[0,1,0] neg_hi:[0,1,0]
	v_pk_fma_f32 v[120:121], v[44:45], v[230:231], v[120:121] op_sel_hi:[1,0,1] neg_lo:[0,1,0] neg_hi:[0,1,0]
	ds_read_b128 v[42:45], v233 offset:864
	s_waitcnt lgkmcnt(13)
	v_pk_fma_f32 v[122:123], v[46:47], v[230:231], v[122:123] op_sel_hi:[1,0,1] neg_lo:[0,1,0] neg_hi:[0,1,0]
	v_pk_fma_f32 v[124:125], v[48:49], v[230:231], v[124:125] op_sel_hi:[1,0,1] neg_lo:[0,1,0] neg_hi:[0,1,0]
	ds_read_b128 v[46:49], v233 offset:880
	v_pk_fma_f32 v[126:127], v[50:51], v[230:231], v[126:127] op_sel_hi:[1,0,1] neg_lo:[0,1,0] neg_hi:[0,1,0]
	v_pk_fma_f32 v[128:129], v[52:53], v[230:231], v[128:129] op_sel_hi:[1,0,1] neg_lo:[0,1,0] neg_hi:[0,1,0]
	ds_read_b128 v[50:53], v233 offset:896
	s_waitcnt lgkmcnt(13)
	v_pk_fma_f32 v[130:131], v[54:55], v[230:231], v[130:131] op_sel_hi:[1,0,1] neg_lo:[0,1,0] neg_hi:[0,1,0]
	v_pk_fma_f32 v[132:133], v[56:57], v[230:231], v[132:133] op_sel_hi:[1,0,1] neg_lo:[0,1,0] neg_hi:[0,1,0]
	ds_read_b128 v[54:57], v233 offset:912
	v_pk_fma_f32 v[134:135], v[58:59], v[230:231], v[134:135] op_sel_hi:[1,0,1] neg_lo:[0,1,0] neg_hi:[0,1,0]
	v_pk_fma_f32 v[136:137], v[60:61], v[230:231], v[136:137] op_sel_hi:[1,0,1] neg_lo:[0,1,0] neg_hi:[0,1,0]
	ds_read_b128 v[58:61], v233 offset:928
	s_waitcnt lgkmcnt(13)
	v_pk_fma_f32 v[138:139], v[62:63], v[230:231], v[138:139] op_sel_hi:[1,0,1] neg_lo:[0,1,0] neg_hi:[0,1,0]
	v_pk_fma_f32 v[140:141], v[64:65], v[230:231], v[140:141] op_sel_hi:[1,0,1] neg_lo:[0,1,0] neg_hi:[0,1,0]
	ds_read_b128 v[62:65], v233 offset:944
	v_pk_fma_f32 v[142:143], v[66:67], v[230:231], v[142:143] op_sel_hi:[1,0,1] neg_lo:[0,1,0] neg_hi:[0,1,0]
	v_pk_fma_f32 v[144:145], v[68:69], v[230:231], v[144:145] op_sel_hi:[1,0,1] neg_lo:[0,1,0] neg_hi:[0,1,0]
	ds_read_b128 v[66:69], v233 offset:960
	s_waitcnt lgkmcnt(13)
	v_pk_fma_f32 v[146:147], v[70:71], v[230:231], v[146:147] op_sel_hi:[1,0,1] neg_lo:[0,1,0] neg_hi:[0,1,0]
	v_pk_fma_f32 v[148:149], v[72:73], v[230:231], v[148:149] op_sel_hi:[1,0,1] neg_lo:[0,1,0] neg_hi:[0,1,0]
	ds_read_b128 v[70:73], v233 offset:976
	v_pk_fma_f32 v[150:151], v[194:195], v[230:231], v[150:151] op_sel_hi:[1,0,1] neg_lo:[0,1,0] neg_hi:[0,1,0]
	v_pk_fma_f32 v[152:153], v[196:197], v[230:231], v[152:153] op_sel_hi:[1,0,1] neg_lo:[0,1,0] neg_hi:[0,1,0]
	ds_read_b128 v[194:197], v233 offset:992
	s_waitcnt lgkmcnt(13)
	v_pk_fma_f32 v[154:155], v[198:199], v[230:231], v[154:155] op_sel_hi:[1,0,1] neg_lo:[0,1,0] neg_hi:[0,1,0]
	v_pk_fma_f32 v[180:181], v[200:201], v[230:231], v[180:181] op_sel_hi:[1,0,1] neg_lo:[0,1,0] neg_hi:[0,1,0]
	ds_read_b128 v[198:201], v233 offset:1008
	v_pk_fma_f32 v[182:183], v[202:203], v[230:231], v[182:183] op_sel_hi:[1,0,1] neg_lo:[0,1,0] neg_hi:[0,1,0]
	v_pk_fma_f32 v[184:185], v[204:205], v[230:231], v[184:185] op_sel_hi:[1,0,1] neg_lo:[0,1,0] neg_hi:[0,1,0]
	ds_read_b128 v[202:205], v233 offset:1024
	s_waitcnt lgkmcnt(13)
	v_pk_fma_f32 v[186:187], v[206:207], v[230:231], v[186:187] op_sel_hi:[1,0,1] neg_lo:[0,1,0] neg_hi:[0,1,0]
	v_pk_fma_f32 v[188:189], v[208:209], v[230:231], v[188:189] op_sel_hi:[1,0,1] neg_lo:[0,1,0] neg_hi:[0,1,0]
	ds_read_b128 v[206:209], v233 offset:1040
	v_pk_fma_f32 v[190:191], v[226:227], v[230:231], v[190:191] op_sel_hi:[1,0,1] neg_lo:[0,1,0] neg_hi:[0,1,0]
	v_pk_fma_f32 v[192:193], v[228:229], v[230:231], v[192:193] op_sel_hi:[1,0,1] neg_lo:[0,1,0] neg_hi:[0,1,0]
	ds_read_b128 v[226:229], v233 offset:1056
	s_nop 0
	v_mov_b32_e32 v230, v109
	v_cvt_pk_bf16_f32 v232, v230, v230
	global_store_short v28, v232, s[0:1]
	s_add_u32 s0, s0, 0x400
	s_addc_u32 s1, s1, 0
	s_waitcnt lgkmcnt(13)
	v_pk_fma_f32 v[110:111], v[34:35], v[230:231], v[110:111] op_sel_hi:[1,0,1] neg_lo:[0,1,0] neg_hi:[0,1,0]
	v_pk_fma_f32 v[112:113], v[36:37], v[230:231], v[112:113] op_sel_hi:[1,0,1] neg_lo:[0,1,0] neg_hi:[0,1,0]
	ds_read_b128 v[34:37], v233 offset:1104
	v_pk_fma_f32 v[114:115], v[38:39], v[230:231], v[114:115] op_sel_hi:[1,0,1] neg_lo:[0,1,0] neg_hi:[0,1,0]
	v_pk_fma_f32 v[116:117], v[40:41], v[230:231], v[116:117] op_sel_hi:[1,0,1] neg_lo:[0,1,0] neg_hi:[0,1,0]
	ds_read_b128 v[38:41], v233 offset:1120
	s_waitcnt lgkmcnt(13)
	v_pk_fma_f32 v[118:119], v[42:43], v[230:231], v[118:119] op_sel_hi:[1,0,1] neg_lo:[0,1,0] neg_hi:[0,1,0]
	v_pk_fma_f32 v[120:121], v[44:45], v[230:231], v[120:121] op_sel_hi:[1,0,1] neg_lo:[0,1,0] neg_hi:[0,1,0]
	ds_read_b128 v[42:45], v233 offset:1136
	v_pk_fma_f32 v[122:123], v[46:47], v[230:231], v[122:123] op_sel_hi:[1,0,1] neg_lo:[0,1,0] neg_hi:[0,1,0]
	v_pk_fma_f32 v[124:125], v[48:49], v[230:231], v[124:125] op_sel_hi:[1,0,1] neg_lo:[0,1,0] neg_hi:[0,1,0]
	ds_read_b128 v[46:49], v233 offset:1152
	s_waitcnt lgkmcnt(13)
	v_pk_fma_f32 v[126:127], v[50:51], v[230:231], v[126:127] op_sel_hi:[1,0,1] neg_lo:[0,1,0] neg_hi:[0,1,0]
	v_pk_fma_f32 v[128:129], v[52:53], v[230:231], v[128:129] op_sel_hi:[1,0,1] neg_lo:[0,1,0] neg_hi:[0,1,0]
	ds_read_b128 v[50:53], v233 offset:1168
	v_pk_fma_f32 v[130:131], v[54:55], v[230:231], v[130:131] op_sel_hi:[1,0,1] neg_lo:[0,1,0] neg_hi:[0,1,0]
	v_pk_fma_f32 v[132:133], v[56:57], v[230:231], v[132:133] op_sel_hi:[1,0,1] neg_lo:[0,1,0] neg_hi:[0,1,0]
	ds_read_b128 v[54:57], v233 offset:1184
	s_waitcnt lgkmcnt(13)
	v_pk_fma_f32 v[134:135], v[58:59], v[230:231], v[134:135] op_sel_hi:[1,0,1] neg_lo:[0,1,0] neg_hi:[0,1,0]
	v_pk_fma_f32 v[136:137], v[60:61], v[230:231], v[136:137] op_sel_hi:[1,0,1] neg_lo:[0,1,0] neg_hi:[0,1,0]
	ds_read_b128 v[58:61], v233 offset:1200
	v_pk_fma_f32 v[138:139], v[62:63], v[230:231], v[138:139] op_sel_hi:[1,0,1] neg_lo:[0,1,0] neg_hi:[0,1,0]
	v_pk_fma_f32 v[140:141], v[64:65], v[230:231], v[140:141] op_sel_hi:[1,0,1] neg_lo:[0,1,0] neg_hi:[0,1,0]
	ds_read_b128 v[62:65], v233 offset:1216
	s_waitcnt lgkmcnt(13)
	v_pk_fma_f32 v[142:143], v[66:67], v[230:231], v[142:143] op_sel_hi:[1,0,1] neg_lo:[0,1,0] neg_hi:[0,1,0]
	v_pk_fma_f32 v[144:145], v[68:69], v[230:231], v[144:145] op_sel_hi:[1,0,1] neg_lo:[0,1,0] neg_hi:[0,1,0]
	ds_read_b128 v[66:69], v233 offset:1232
	v_pk_fma_f32 v[146:147], v[70:71], v[230:231], v[146:147] op_sel_hi:[1,0,1] neg_lo:[0,1,0] neg_hi:[0,1,0]
	v_pk_fma_f32 v[148:149], v[72:73], v[230:231], v[148:149] op_sel_hi:[1,0,1] neg_lo:[0,1,0] neg_hi:[0,1,0]
	ds_read_b128 v[70:73], v233 offset:1248
	s_waitcnt lgkmcnt(13)
	v_pk_fma_f32 v[150:151], v[194:195], v[230:231], v[150:151] op_sel_hi:[1,0,1] neg_lo:[0,1,0] neg_hi:[0,1,0]
	v_pk_fma_f32 v[152:153], v[196:197], v[230:231], v[152:153] op_sel_hi:[1,0,1] neg_lo:[0,1,0] neg_hi:[0,1,0]
	ds_read_b128 v[194:197], v233 offset:1264
	v_pk_fma_f32 v[154:155], v[198:199], v[230:231], v[154:155] op_sel_hi:[1,0,1] neg_lo:[0,1,0] neg_hi:[0,1,0]
	v_pk_fma_f32 v[180:181], v[200:201], v[230:231], v[180:181] op_sel_hi:[1,0,1] neg_lo:[0,1,0] neg_hi:[0,1,0]
	ds_read_b128 v[198:201], v233 offset:1280
	s_waitcnt lgkmcnt(13)
	v_pk_fma_f32 v[182:183], v[202:203], v[230:231], v[182:183] op_sel_hi:[1,0,1] neg_lo:[0,1,0] neg_hi:[0,1,0]
	v_pk_fma_f32 v[184:185], v[204:205], v[230:231], v[184:185] op_sel_hi:[1,0,1] neg_lo:[0,1,0] neg_hi:[0,1,0]
	ds_read_b128 v[202:205], v233 offset:1296
	v_pk_fma_f32 v[186:187], v[206:207], v[230:231], v[186:187] op_sel_hi:[1,0,1] neg_lo:[0,1,0] neg_hi:[0,1,0]
	v_pk_fma_f32 v[188:189], v[208:209], v[230:231], v[188:189] op_sel_hi:[1,0,1] neg_lo:[0,1,0] neg_hi:[0,1,0]
	ds_read_b128 v[206:209], v233 offset:1312
	s_waitcnt lgkmcnt(14)
	v_pk_fma_f32 v[190:191], v[226:227], v[230:231], v[190:191] op_sel_hi:[1,0,1] neg_lo:[0,1,0] neg_hi:[0,1,0]
	v_pk_fma_f32 v[192:193], v[228:229], v[230:231], v[192:193] op_sel_hi:[1,0,1] neg_lo:[0,1,0] neg_hi:[0,1,0]
	ds_read_b128 v[226:229], v233 offset:1328
	s_nop 0
	v_mov_b32_e32 v230, v110
	v_cvt_pk_bf16_f32 v232, v230, v230
	global_store_short v28, v232, s[0:1]
	s_add_u32 s0, s0, 0x400
	s_addc_u32 s1, s1, 0
	s_waitcnt lgkmcnt(13)
	v_pk_fma_f32 v[110:111], v[34:35], v[230:231], v[110:111] op_sel_hi:[1,0,1] neg_lo:[0,1,0] neg_hi:[0,1,0]
	v_pk_fma_f32 v[112:113], v[36:37], v[230:231], v[112:113] op_sel_hi:[1,0,1] neg_lo:[0,1,0] neg_hi:[0,1,0]
	ds_read_b128 v[34:37], v233 offset:1376
	v_pk_fma_f32 v[114:115], v[38:39], v[230:231], v[114:115] op_sel_hi:[1,0,1] neg_lo:[0,1,0] neg_hi:[0,1,0]
	v_pk_fma_f32 v[116:117], v[40:41], v[230:231], v[116:117] op_sel_hi:[1,0,1] neg_lo:[0,1,0] neg_hi:[0,1,0]
	ds_read_b128 v[38:41], v233 offset:1392
	s_waitcnt lgkmcnt(13)
	v_pk_fma_f32 v[118:119], v[42:43], v[230:231], v[118:119] op_sel_hi:[1,0,1] neg_lo:[0,1,0] neg_hi:[0,1,0]
	v_pk_fma_f32 v[120:121], v[44:45], v[230:231], v[120:121] op_sel_hi:[1,0,1] neg_lo:[0,1,0] neg_hi:[0,1,0]
	ds_read_b128 v[42:45], v233 offset:1408
	v_pk_fma_f32 v[122:123], v[46:47], v[230:231], v[122:123] op_sel_hi:[1,0,1] neg_lo:[0,1,0] neg_hi:[0,1,0]
	v_pk_fma_f32 v[124:125], v[48:49], v[230:231], v[124:125] op_sel_hi:[1,0,1] neg_lo:[0,1,0] neg_hi:[0,1,0]
	ds_read_b128 v[46:49], v233 offset:1424
	s_waitcnt lgkmcnt(13)
	v_pk_fma_f32 v[126:127], v[50:51], v[230:231], v[126:127] op_sel_hi:[1,0,1] neg_lo:[0,1,0] neg_hi:[0,1,0]
	v_pk_fma_f32 v[128:129], v[52:53], v[230:231], v[128:129] op_sel_hi:[1,0,1] neg_lo:[0,1,0] neg_hi:[0,1,0]
	ds_read_b128 v[50:53], v233 offset:1440
	v_pk_fma_f32 v[130:131], v[54:55], v[230:231], v[130:131] op_sel_hi:[1,0,1] neg_lo:[0,1,0] neg_hi:[0,1,0]
	v_pk_fma_f32 v[132:133], v[56:57], v[230:231], v[132:133] op_sel_hi:[1,0,1] neg_lo:[0,1,0] neg_hi:[0,1,0]
	ds_read_b128 v[54:57], v233 offset:1456
	s_waitcnt lgkmcnt(13)
	v_pk_fma_f32 v[134:135], v[58:59], v[230:231], v[134:135] op_sel_hi:[1,0,1] neg_lo:[0,1,0] neg_hi:[0,1,0]
	v_pk_fma_f32 v[136:137], v[60:61], v[230:231], v[136:137] op_sel_hi:[1,0,1] neg_lo:[0,1,0] neg_hi:[0,1,0]
	ds_read_b128 v[58:61], v233 offset:1472
	v_pk_fma_f32 v[138:139], v[62:63], v[230:231], v[138:139] op_sel_hi:[1,0,1] neg_lo:[0,1,0] neg_hi:[0,1,0]
	v_pk_fma_f32 v[140:141], v[64:65], v[230:231], v[140:141] op_sel_hi:[1,0,1] neg_lo:[0,1,0] neg_hi:[0,1,0]
	ds_read_b128 v[62:65], v233 offset:1488
	s_waitcnt lgkmcnt(13)
	v_pk_fma_f32 v[142:143], v[66:67], v[230:231], v[142:143] op_sel_hi:[1,0,1] neg_lo:[0,1,0] neg_hi:[0,1,0]
	v_pk_fma_f32 v[144:145], v[68:69], v[230:231], v[144:145] op_sel_hi:[1,0,1] neg_lo:[0,1,0] neg_hi:[0,1,0]
	ds_read_b128 v[66:69], v233 offset:1504
	v_pk_fma_f32 v[146:147], v[70:71], v[230:231], v[146:147] op_sel_hi:[1,0,1] neg_lo:[0,1,0] neg_hi:[0,1,0]
	v_pk_fma_f32 v[148:149], v[72:73], v[230:231], v[148:149] op_sel_hi:[1,0,1] neg_lo:[0,1,0] neg_hi:[0,1,0]
	ds_read_b128 v[70:73], v233 offset:1520
	s_waitcnt lgkmcnt(13)
	v_pk_fma_f32 v[150:151], v[194:195], v[230:231], v[150:151] op_sel_hi:[1,0,1] neg_lo:[0,1,0] neg_hi:[0,1,0]
	v_pk_fma_f32 v[152:153], v[196:197], v[230:231], v[152:153] op_sel_hi:[1,0,1] neg_lo:[0,1,0] neg_hi:[0,1,0]
	ds_read_b128 v[194:197], v233 offset:1536
	v_pk_fma_f32 v[154:155], v[198:199], v[230:231], v[154:155] op_sel_hi:[1,0,1] neg_lo:[0,1,0] neg_hi:[0,1,0]
	v_pk_fma_f32 v[180:181], v[200:201], v[230:231], v[180:181] op_sel_hi:[1,0,1] neg_lo:[0,1,0] neg_hi:[0,1,0]
	ds_read_b128 v[198:201], v233 offset:1552
	s_waitcnt lgkmcnt(13)
	v_pk_fma_f32 v[182:183], v[202:203], v[230:231], v[182:183] op_sel_hi:[1,0,1] neg_lo:[0,1,0] neg_hi:[0,1,0]
	v_pk_fma_f32 v[184:185], v[204:205], v[230:231], v[184:185] op_sel_hi:[1,0,1] neg_lo:[0,1,0] neg_hi:[0,1,0]
	ds_read_b128 v[202:205], v233 offset:1568
	v_pk_fma_f32 v[186:187], v[206:207], v[230:231], v[186:187] op_sel_hi:[1,0,1] neg_lo:[0,1,0] neg_hi:[0,1,0]
	v_pk_fma_f32 v[188:189], v[208:209], v[230:231], v[188:189] op_sel_hi:[1,0,1] neg_lo:[0,1,0] neg_hi:[0,1,0]
	ds_read_b128 v[206:209], v233 offset:1584
	s_waitcnt lgkmcnt(14)
	v_pk_fma_f32 v[190:191], v[226:227], v[230:231], v[190:191] op_sel_hi:[1,0,1] neg_lo:[0,1,0] neg_hi:[0,1,0]
	v_pk_fma_f32 v[192:193], v[228:229], v[230:231], v[192:193] op_sel_hi:[1,0,1] neg_lo:[0,1,0] neg_hi:[0,1,0]
	ds_read_b128 v[226:229], v233 offset:1600
	s_nop 0
	v_mov_b32_e32 v230, v111
	v_cvt_pk_bf16_f32 v232, v230, v230
	global_store_short v28, v232, s[0:1]
	s_add_u32 s0, s0, 0x400
	s_addc_u32 s1, s1, 0
	s_waitcnt lgkmcnt(13)
	v_pk_fma_f32 v[112:113], v[36:37], v[230:231], v[112:113] op_sel_hi:[1,0,1] neg_lo:[0,1,0] neg_hi:[0,1,0]
	ds_read_b128 v[34:37], v233 offset:1648
	v_pk_fma_f32 v[114:115], v[38:39], v[230:231], v[114:115] op_sel_hi:[1,0,1] neg_lo:[0,1,0] neg_hi:[0,1,0]
	v_pk_fma_f32 v[116:117], v[40:41], v[230:231], v[116:117] op_sel_hi:[1,0,1] neg_lo:[0,1,0] neg_hi:[0,1,0]
	ds_read_b128 v[38:41], v233 offset:1664
	s_waitcnt lgkmcnt(13)
	v_pk_fma_f32 v[118:119], v[42:43], v[230:231], v[118:119] op_sel_hi:[1,0,1] neg_lo:[0,1,0] neg_hi:[0,1,0]
	v_pk_fma_f32 v[120:121], v[44:45], v[230:231], v[120:121] op_sel_hi:[1,0,1] neg_lo:[0,1,0] neg_hi:[0,1,0]
	ds_read_b128 v[42:45], v233 offset:1680
	v_pk_fma_f32 v[122:123], v[46:47], v[230:231], v[122:123] op_sel_hi:[1,0,1] neg_lo:[0,1,0] neg_hi:[0,1,0]
	v_pk_fma_f32 v[124:125], v[48:49], v[230:231], v[124:125] op_sel_hi:[1,0,1] neg_lo:[0,1,0] neg_hi:[0,1,0]
	ds_read_b128 v[46:49], v233 offset:1696
	s_waitcnt lgkmcnt(13)
	v_pk_fma_f32 v[126:127], v[50:51], v[230:231], v[126:127] op_sel_hi:[1,0,1] neg_lo:[0,1,0] neg_hi:[0,1,0]
	v_pk_fma_f32 v[128:129], v[52:53], v[230:231], v[128:129] op_sel_hi:[1,0,1] neg_lo:[0,1,0] neg_hi:[0,1,0]
	ds_read_b128 v[50:53], v233 offset:1712
	v_pk_fma_f32 v[130:131], v[54:55], v[230:231], v[130:131] op_sel_hi:[1,0,1] neg_lo:[0,1,0] neg_hi:[0,1,0]
	v_pk_fma_f32 v[132:133], v[56:57], v[230:231], v[132:133] op_sel_hi:[1,0,1] neg_lo:[0,1,0] neg_hi:[0,1,0]
	ds_read_b128 v[54:57], v233 offset:1728
	s_waitcnt lgkmcnt(13)
	v_pk_fma_f32 v[134:135], v[58:59], v[230:231], v[134:135] op_sel_hi:[1,0,1] neg_lo:[0,1,0] neg_hi:[0,1,0]
	v_pk_fma_f32 v[136:137], v[60:61], v[230:231], v[136:137] op_sel_hi:[1,0,1] neg_lo:[0,1,0] neg_hi:[0,1,0]
	ds_read_b128 v[58:61], v233 offset:1744
	v_pk_fma_f32 v[138:139], v[62:63], v[230:231], v[138:139] op_sel_hi:[1,0,1] neg_lo:[0,1,0] neg_hi:[0,1,0]
	v_pk_fma_f32 v[140:141], v[64:65], v[230:231], v[140:141] op_sel_hi:[1,0,1] neg_lo:[0,1,0] neg_hi:[0,1,0]
	ds_read_b128 v[62:65], v233 offset:1760
	s_waitcnt lgkmcnt(13)
	v_pk_fma_f32 v[142:143], v[66:67], v[230:231], v[142:143] op_sel_hi:[1,0,1] neg_lo:[0,1,0] neg_hi:[0,1,0]
	v_pk_fma_f32 v[144:145], v[68:69], v[230:231], v[144:145] op_sel_hi:[1,0,1] neg_lo:[0,1,0] neg_hi:[0,1,0]
	ds_read_b128 v[66:69], v233 offset:1776
	v_pk_fma_f32 v[146:147], v[70:71], v[230:231], v[146:147] op_sel_hi:[1,0,1] neg_lo:[0,1,0] neg_hi:[0,1,0]
	v_pk_fma_f32 v[148:149], v[72:73], v[230:231], v[148:149] op_sel_hi:[1,0,1] neg_lo:[0,1,0] neg_hi:[0,1,0]
	ds_read_b128 v[70:73], v233 offset:1792
	s_waitcnt lgkmcnt(13)
	v_pk_fma_f32 v[150:151], v[194:195], v[230:231], v[150:151] op_sel_hi:[1,0,1] neg_lo:[0,1,0] neg_hi:[0,1,0]
	v_pk_fma_f32 v[152:153], v[196:197], v[230:231], v[152:153] op_sel_hi:[1,0,1] neg_lo:[0,1,0] neg_hi:[0,1,0]
	ds_read_b128 v[194:197], v233 offset:1808
	v_pk_fma_f32 v[154:155], v[198:199], v[230:231], v[154:155] op_sel_hi:[1,0,1] neg_lo:[0,1,0] neg_hi:[0,1,0]
	v_pk_fma_f32 v[180:181], v[200:201], v[230:231], v[180:181] op_sel_hi:[1,0,1] neg_lo:[0,1,0] neg_hi:[0,1,0]
	ds_read_b128 v[198:201], v233 offset:1824
	s_waitcnt lgkmcnt(13)
	v_pk_fma_f32 v[182:183], v[202:203], v[230:231], v[182:183] op_sel_hi:[1,0,1] neg_lo:[0,1,0] neg_hi:[0,1,0]
	v_pk_fma_f32 v[184:185], v[204:205], v[230:231], v[184:185] op_sel_hi:[1,0,1] neg_lo:[0,1,0] neg_hi:[0,1,0]
	ds_read_b128 v[202:205], v233 offset:1840
	v_pk_fma_f32 v[186:187], v[206:207], v[230:231], v[186:187] op_sel_hi:[1,0,1] neg_lo:[0,1,0] neg_hi:[0,1,0]
	v_pk_fma_f32 v[188:189], v[208:209], v[230:231], v[188:189] op_sel_hi:[1,0,1] neg_lo:[0,1,0] neg_hi:[0,1,0]
	ds_read_b128 v[206:209], v233 offset:1856
	s_waitcnt lgkmcnt(14)
	v_pk_fma_f32 v[190:191], v[226:227], v[230:231], v[190:191] op_sel_hi:[1,0,1] neg_lo:[0,1,0] neg_hi:[0,1,0]
	v_pk_fma_f32 v[192:193], v[228:229], v[230:231], v[192:193] op_sel_hi:[1,0,1] neg_lo:[0,1,0] neg_hi:[0,1,0]
	ds_read_b128 v[226:229], v233 offset:1872
	s_nop 0
	v_mov_b32_e32 v230, v112
	v_cvt_pk_bf16_f32 v232, v230, v230
	global_store_short v28, v232, s[0:1]
	s_add_u32 s0, s0, 0x400
	s_addc_u32 s1, s1, 0
	s_waitcnt lgkmcnt(13)
	v_pk_fma_f32 v[112:113], v[36:37], v[230:231], v[112:113] op_sel_hi:[1,0,1] neg_lo:[0,1,0] neg_hi:[0,1,0]
	v_pk_fma_f32 v[114:115], v[38:39], v[230:231], v[114:115] op_sel_hi:[1,0,1] neg_lo:[0,1,0] neg_hi:[0,1,0]
	v_pk_fma_f32 v[116:117], v[40:41], v[230:231], v[116:117] op_sel_hi:[1,0,1] neg_lo:[0,1,0] neg_hi:[0,1,0]
	ds_read_b128 v[38:41], v233 offset:1936
	s_waitcnt lgkmcnt(12)
	v_pk_fma_f32 v[118:119], v[42:43], v[230:231], v[118:119] op_sel_hi:[1,0,1] neg_lo:[0,1,0] neg_hi:[0,1,0]
	v_pk_fma_f32 v[120:121], v[44:45], v[230:231], v[120:121] op_sel_hi:[1,0,1] neg_lo:[0,1,0] neg_hi:[0,1,0]
	ds_read_b128 v[42:45], v233 offset:1952
	v_pk_fma_f32 v[122:123], v[46:47], v[230:231], v[122:123] op_sel_hi:[1,0,1] neg_lo:[0,1,0] neg_hi:[0,1,0]
	v_pk_fma_f32 v[124:125], v[48:49], v[230:231], v[124:125] op_sel_hi:[1,0,1] neg_lo:[0,1,0] neg_hi:[0,1,0]
	ds_read_b128 v[46:49], v233 offset:1968
	s_waitcnt lgkmcnt(12)
	v_pk_fma_f32 v[126:127], v[50:51], v[230:231], v[126:127] op_sel_hi:[1,0,1] neg_lo:[0,1,0] neg_hi:[0,1,0]
	v_pk_fma_f32 v[128:129], v[52:53], v[230:231], v[128:129] op_sel_hi:[1,0,1] neg_lo:[0,1,0] neg_hi:[0,1,0]
	ds_read_b128 v[50:53], v233 offset:1984
	v_pk_fma_f32 v[130:131], v[54:55], v[230:231], v[130:131] op_sel_hi:[1,0,1] neg_lo:[0,1,0] neg_hi:[0,1,0]
	v_pk_fma_f32 v[132:133], v[56:57], v[230:231], v[132:133] op_sel_hi:[1,0,1] neg_lo:[0,1,0] neg_hi:[0,1,0]
	ds_read_b128 v[54:57], v233 offset:2000
	s_waitcnt lgkmcnt(12)
	v_pk_fma_f32 v[134:135], v[58:59], v[230:231], v[134:135] op_sel_hi:[1,0,1] neg_lo:[0,1,0] neg_hi:[0,1,0]
	v_pk_fma_f32 v[136:137], v[60:61], v[230:231], v[136:137] op_sel_hi:[1,0,1] neg_lo:[0,1,0] neg_hi:[0,1,0]
	ds_read_b128 v[58:61], v233 offset:2016
	v_pk_fma_f32 v[138:139], v[62:63], v[230:231], v[138:139] op_sel_hi:[1,0,1] neg_lo:[0,1,0] neg_hi:[0,1,0]
	v_pk_fma_f32 v[140:141], v[64:65], v[230:231], v[140:141] op_sel_hi:[1,0,1] neg_lo:[0,1,0] neg_hi:[0,1,0]
	ds_read_b128 v[62:65], v233 offset:2032
	s_waitcnt lgkmcnt(12)
	v_pk_fma_f32 v[142:143], v[66:67], v[230:231], v[142:143] op_sel_hi:[1,0,1] neg_lo:[0,1,0] neg_hi:[0,1,0]
	v_pk_fma_f32 v[144:145], v[68:69], v[230:231], v[144:145] op_sel_hi:[1,0,1] neg_lo:[0,1,0] neg_hi:[0,1,0]
	ds_read_b128 v[66:69], v233 offset:2048
	v_pk_fma_f32 v[146:147], v[70:71], v[230:231], v[146:147] op_sel_hi:[1,0,1] neg_lo:[0,1,0] neg_hi:[0,1,0]
	v_pk_fma_f32 v[148:149], v[72:73], v[230:231], v[148:149] op_sel_hi:[1,0,1] neg_lo:[0,1,0] neg_hi:[0,1,0]
	ds_read_b128 v[70:73], v233 offset:2064
	s_waitcnt lgkmcnt(12)
	v_pk_fma_f32 v[150:151], v[194:195], v[230:231], v[150:151] op_sel_hi:[1,0,1] neg_lo:[0,1,0] neg_hi:[0,1,0]
	v_pk_fma_f32 v[152:153], v[196:197], v[230:231], v[152:153] op_sel_hi:[1,0,1] neg_lo:[0,1,0] neg_hi:[0,1,0]
	ds_read_b128 v[194:197], v233 offset:2080
	v_pk_fma_f32 v[154:155], v[198:199], v[230:231], v[154:155] op_sel_hi:[1,0,1] neg_lo:[0,1,0] neg_hi:[0,1,0]
	v_pk_fma_f32 v[180:181], v[200:201], v[230:231], v[180:181] op_sel_hi:[1,0,1] neg_lo:[0,1,0] neg_hi:[0,1,0]
	ds_read_b128 v[198:201], v233 offset:2096
	s_waitcnt lgkmcnt(12)
	v_pk_fma_f32 v[182:183], v[202:203], v[230:231], v[182:183] op_sel_hi:[1,0,1] neg_lo:[0,1,0] neg_hi:[0,1,0]
	v_pk_fma_f32 v[184:185], v[204:205], v[230:231], v[184:185] op_sel_hi:[1,0,1] neg_lo:[0,1,0] neg_hi:[0,1,0]
	ds_read_b128 v[202:205], v233 offset:2112
	v_pk_fma_f32 v[186:187], v[206:207], v[230:231], v[186:187] op_sel_hi:[1,0,1] neg_lo:[0,1,0] neg_hi:[0,1,0]
	v_pk_fma_f32 v[188:189], v[208:209], v[230:231], v[188:189] op_sel_hi:[1,0,1] neg_lo:[0,1,0] neg_hi:[0,1,0]
	ds_read_b128 v[206:209], v233 offset:2128
	s_waitcnt lgkmcnt(13)
	v_pk_fma_f32 v[190:191], v[226:227], v[230:231], v[190:191] op_sel_hi:[1,0,1] neg_lo:[0,1,0] neg_hi:[0,1,0]
	v_pk_fma_f32 v[192:193], v[228:229], v[230:231], v[192:193] op_sel_hi:[1,0,1] neg_lo:[0,1,0] neg_hi:[0,1,0]
	ds_read_b128 v[226:229], v233 offset:2144
	s_nop 0
	v_mov_b32_e32 v230, v113
	v_cvt_pk_bf16_f32 v232, v230, v230
	global_store_short v28, v232, s[0:1]
	s_add_u32 s0, s0, 0x400
	s_addc_u32 s1, s1, 0
	s_waitcnt lgkmcnt(12)
	v_pk_fma_f32 v[114:115], v[38:39], v[230:231], v[114:115] op_sel_hi:[1,0,1] neg_lo:[0,1,0] neg_hi:[0,1,0]
	v_pk_fma_f32 v[116:117], v[40:41], v[230:231], v[116:117] op_sel_hi:[1,0,1] neg_lo:[0,1,0] neg_hi:[0,1,0]
	ds_read_b128 v[38:41], v233 offset:2208
	v_pk_fma_f32 v[118:119], v[42:43], v[230:231], v[118:119] op_sel_hi:[1,0,1] neg_lo:[0,1,0] neg_hi:[0,1,0]
	v_pk_fma_f32 v[120:121], v[44:45], v[230:231], v[120:121] op_sel_hi:[1,0,1] neg_lo:[0,1,0] neg_hi:[0,1,0]
	ds_read_b128 v[42:45], v233 offset:2224
	s_waitcnt lgkmcnt(12)
	v_pk_fma_f32 v[122:123], v[46:47], v[230:231], v[122:123] op_sel_hi:[1,0,1] neg_lo:[0,1,0] neg_hi:[0,1,0]
	v_pk_fma_f32 v[124:125], v[48:49], v[230:231], v[124:125] op_sel_hi:[1,0,1] neg_lo:[0,1,0] neg_hi:[0,1,0]
	ds_read_b128 v[46:49], v233 offset:2240
	v_pk_fma_f32 v[126:127], v[50:51], v[230:231], v[126:127] op_sel_hi:[1,0,1] neg_lo:[0,1,0] neg_hi:[0,1,0]
	v_pk_fma_f32 v[128:129], v[52:53], v[230:231], v[128:129] op_sel_hi:[1,0,1] neg_lo:[0,1,0] neg_hi:[0,1,0]
	ds_read_b128 v[50:53], v233 offset:2256
	s_waitcnt lgkmcnt(12)
	v_pk_fma_f32 v[130:131], v[54:55], v[230:231], v[130:131] op_sel_hi:[1,0,1] neg_lo:[0,1,0] neg_hi:[0,1,0]
	v_pk_fma_f32 v[132:133], v[56:57], v[230:231], v[132:133] op_sel_hi:[1,0,1] neg_lo:[0,1,0] neg_hi:[0,1,0]
	ds_read_b128 v[54:57], v233 offset:2272
	v_pk_fma_f32 v[134:135], v[58:59], v[230:231], v[134:135] op_sel_hi:[1,0,1] neg_lo:[0,1,0] neg_hi:[0,1,0]
	v_pk_fma_f32 v[136:137], v[60:61], v[230:231], v[136:137] op_sel_hi:[1,0,1] neg_lo:[0,1,0] neg_hi:[0,1,0]
	ds_read_b128 v[58:61], v233 offset:2288
	s_waitcnt lgkmcnt(12)
	v_pk_fma_f32 v[138:139], v[62:63], v[230:231], v[138:139] op_sel_hi:[1,0,1] neg_lo:[0,1,0] neg_hi:[0,1,0]
	v_pk_fma_f32 v[140:141], v[64:65], v[230:231], v[140:141] op_sel_hi:[1,0,1] neg_lo:[0,1,0] neg_hi:[0,1,0]
	ds_read_b128 v[62:65], v233 offset:2304
	v_pk_fma_f32 v[142:143], v[66:67], v[230:231], v[142:143] op_sel_hi:[1,0,1] neg_lo:[0,1,0] neg_hi:[0,1,0]
	v_pk_fma_f32 v[144:145], v[68:69], v[230:231], v[144:145] op_sel_hi:[1,0,1] neg_lo:[0,1,0] neg_hi:[0,1,0]
	ds_read_b128 v[66:69], v233 offset:2320
	s_waitcnt lgkmcnt(12)
	v_pk_fma_f32 v[146:147], v[70:71], v[230:231], v[146:147] op_sel_hi:[1,0,1] neg_lo:[0,1,0] neg_hi:[0,1,0]
	v_pk_fma_f32 v[148:149], v[72:73], v[230:231], v[148:149] op_sel_hi:[1,0,1] neg_lo:[0,1,0] neg_hi:[0,1,0]
	ds_read_b128 v[70:73], v233 offset:2336
	v_pk_fma_f32 v[150:151], v[194:195], v[230:231], v[150:151] op_sel_hi:[1,0,1] neg_lo:[0,1,0] neg_hi:[0,1,0]
	v_pk_fma_f32 v[152:153], v[196:197], v[230:231], v[152:153] op_sel_hi:[1,0,1] neg_lo:[0,1,0] neg_hi:[0,1,0]
	ds_read_b128 v[194:197], v233 offset:2352
	s_waitcnt lgkmcnt(12)
	v_pk_fma_f32 v[154:155], v[198:199], v[230:231], v[154:155] op_sel_hi:[1,0,1] neg_lo:[0,1,0] neg_hi:[0,1,0]
	v_pk_fma_f32 v[180:181], v[200:201], v[230:231], v[180:181] op_sel_hi:[1,0,1] neg_lo:[0,1,0] neg_hi:[0,1,0]
	ds_read_b128 v[198:201], v233 offset:2368
	v_pk_fma_f32 v[182:183], v[202:203], v[230:231], v[182:183] op_sel_hi:[1,0,1] neg_lo:[0,1,0] neg_hi:[0,1,0]
	v_pk_fma_f32 v[184:185], v[204:205], v[230:231], v[184:185] op_sel_hi:[1,0,1] neg_lo:[0,1,0] neg_hi:[0,1,0]
	ds_read_b128 v[202:205], v233 offset:2384
	s_waitcnt lgkmcnt(12)
	v_pk_fma_f32 v[186:187], v[206:207], v[230:231], v[186:187] op_sel_hi:[1,0,1] neg_lo:[0,1,0] neg_hi:[0,1,0]
	v_pk_fma_f32 v[188:189], v[208:209], v[230:231], v[188:189] op_sel_hi:[1,0,1] neg_lo:[0,1,0] neg_hi:[0,1,0]
	ds_read_b128 v[206:209], v233 offset:2400
	v_pk_fma_f32 v[190:191], v[226:227], v[230:231], v[190:191] op_sel_hi:[1,0,1] neg_lo:[0,1,0] neg_hi:[0,1,0]
	v_pk_fma_f32 v[192:193], v[228:229], v[230:231], v[192:193] op_sel_hi:[1,0,1] neg_lo:[0,1,0] neg_hi:[0,1,0]
	ds_read_b128 v[226:229], v233 offset:2416
	s_nop 0
	v_mov_b32_e32 v230, v114
	v_cvt_pk_bf16_f32 v232, v230, v230
	global_store_short v28, v232, s[0:1]
	s_add_u32 s0, s0, 0x400
	s_addc_u32 s1, s1, 0
	s_waitcnt lgkmcnt(12)
	v_pk_fma_f32 v[114:115], v[38:39], v[230:231], v[114:115] op_sel_hi:[1,0,1] neg_lo:[0,1,0] neg_hi:[0,1,0]
	v_pk_fma_f32 v[116:117], v[40:41], v[230:231], v[116:117] op_sel_hi:[1,0,1] neg_lo:[0,1,0] neg_hi:[0,1,0]
	ds_read_b128 v[38:41], v233 offset:2480
	v_pk_fma_f32 v[118:119], v[42:43], v[230:231], v[118:119] op_sel_hi:[1,0,1] neg_lo:[0,1,0] neg_hi:[0,1,0]
	v_pk_fma_f32 v[120:121], v[44:45], v[230:231], v[120:121] op_sel_hi:[1,0,1] neg_lo:[0,1,0] neg_hi:[0,1,0]
	ds_read_b128 v[42:45], v233 offset:2496
	s_waitcnt lgkmcnt(12)
	v_pk_fma_f32 v[122:123], v[46:47], v[230:231], v[122:123] op_sel_hi:[1,0,1] neg_lo:[0,1,0] neg_hi:[0,1,0]
	v_pk_fma_f32 v[124:125], v[48:49], v[230:231], v[124:125] op_sel_hi:[1,0,1] neg_lo:[0,1,0] neg_hi:[0,1,0]
	ds_read_b128 v[46:49], v233 offset:2512
	v_pk_fma_f32 v[126:127], v[50:51], v[230:231], v[126:127] op_sel_hi:[1,0,1] neg_lo:[0,1,0] neg_hi:[0,1,0]
	v_pk_fma_f32 v[128:129], v[52:53], v[230:231], v[128:129] op_sel_hi:[1,0,1] neg_lo:[0,1,0] neg_hi:[0,1,0]
	ds_read_b128 v[50:53], v233 offset:2528
	s_waitcnt lgkmcnt(12)
	v_pk_fma_f32 v[130:131], v[54:55], v[230:231], v[130:131] op_sel_hi:[1,0,1] neg_lo:[0,1,0] neg_hi:[0,1,0]
	v_pk_fma_f32 v[132:133], v[56:57], v[230:231], v[132:133] op_sel_hi:[1,0,1] neg_lo:[0,1,0] neg_hi:[0,1,0]
	ds_read_b128 v[54:57], v233 offset:2544
	v_pk_fma_f32 v[134:135], v[58:59], v[230:231], v[134:135] op_sel_hi:[1,0,1] neg_lo:[0,1,0] neg_hi:[0,1,0]
	v_pk_fma_f32 v[136:137], v[60:61], v[230:231], v[136:137] op_sel_hi:[1,0,1] neg_lo:[0,1,0] neg_hi:[0,1,0]
	ds_read_b128 v[58:61], v233 offset:2560
	s_waitcnt lgkmcnt(12)
	v_pk_fma_f32 v[138:139], v[62:63], v[230:231], v[138:139] op_sel_hi:[1,0,1] neg_lo:[0,1,0] neg_hi:[0,1,0]
	v_pk_fma_f32 v[140:141], v[64:65], v[230:231], v[140:141] op_sel_hi:[1,0,1] neg_lo:[0,1,0] neg_hi:[0,1,0]
	ds_read_b128 v[62:65], v233 offset:2576
	v_pk_fma_f32 v[142:143], v[66:67], v[230:231], v[142:143] op_sel_hi:[1,0,1] neg_lo:[0,1,0] neg_hi:[0,1,0]
	v_pk_fma_f32 v[144:145], v[68:69], v[230:231], v[144:145] op_sel_hi:[1,0,1] neg_lo:[0,1,0] neg_hi:[0,1,0]
	ds_read_b128 v[66:69], v233 offset:2592
	s_waitcnt lgkmcnt(12)
	v_pk_fma_f32 v[146:147], v[70:71], v[230:231], v[146:147] op_sel_hi:[1,0,1] neg_lo:[0,1,0] neg_hi:[0,1,0]
	v_pk_fma_f32 v[148:149], v[72:73], v[230:231], v[148:149] op_sel_hi:[1,0,1] neg_lo:[0,1,0] neg_hi:[0,1,0]
	ds_read_b128 v[70:73], v233 offset:2608
	v_pk_fma_f32 v[150:151], v[194:195], v[230:231], v[150:151] op_sel_hi:[1,0,1] neg_lo:[0,1,0] neg_hi:[0,1,0]
	v_pk_fma_f32 v[152:153], v[196:197], v[230:231], v[152:153] op_sel_hi:[1,0,1] neg_lo:[0,1,0] neg_hi:[0,1,0]
	ds_read_b128 v[194:197], v233 offset:2624
	s_waitcnt lgkmcnt(12)
	v_pk_fma_f32 v[154:155], v[198:199], v[230:231], v[154:155] op_sel_hi:[1,0,1] neg_lo:[0,1,0] neg_hi:[0,1,0]
	v_pk_fma_f32 v[180:181], v[200:201], v[230:231], v[180:181] op_sel_hi:[1,0,1] neg_lo:[0,1,0] neg_hi:[0,1,0]
	ds_read_b128 v[198:201], v233 offset:2640
	v_pk_fma_f32 v[182:183], v[202:203], v[230:231], v[182:183] op_sel_hi:[1,0,1] neg_lo:[0,1,0] neg_hi:[0,1,0]
	v_pk_fma_f32 v[184:185], v[204:205], v[230:231], v[184:185] op_sel_hi:[1,0,1] neg_lo:[0,1,0] neg_hi:[0,1,0]
	ds_read_b128 v[202:205], v233 offset:2656
	s_waitcnt lgkmcnt(12)
	v_pk_fma_f32 v[186:187], v[206:207], v[230:231], v[186:187] op_sel_hi:[1,0,1] neg_lo:[0,1,0] neg_hi:[0,1,0]
	v_pk_fma_f32 v[188:189], v[208:209], v[230:231], v[188:189] op_sel_hi:[1,0,1] neg_lo:[0,1,0] neg_hi:[0,1,0]
	ds_read_b128 v[206:209], v233 offset:2672
	v_pk_fma_f32 v[190:191], v[226:227], v[230:231], v[190:191] op_sel_hi:[1,0,1] neg_lo:[0,1,0] neg_hi:[0,1,0]
	v_pk_fma_f32 v[192:193], v[228:229], v[230:231], v[192:193] op_sel_hi:[1,0,1] neg_lo:[0,1,0] neg_hi:[0,1,0]
	ds_read_b128 v[226:229], v233 offset:2688
	s_nop 0
	v_mov_b32_e32 v230, v115
	v_cvt_pk_bf16_f32 v232, v230, v230
	global_store_short v28, v232, s[0:1]
	s_add_u32 s0, s0, 0x400
	s_addc_u32 s1, s1, 0
	s_waitcnt lgkmcnt(12)
	v_pk_fma_f32 v[116:117], v[40:41], v[230:231], v[116:117] op_sel_hi:[1,0,1] neg_lo:[0,1,0] neg_hi:[0,1,0]
	ds_read_b128 v[38:41], v233 offset:2752
	v_pk_fma_f32 v[118:119], v[42:43], v[230:231], v[118:119] op_sel_hi:[1,0,1] neg_lo:[0,1,0] neg_hi:[0,1,0]
	v_pk_fma_f32 v[120:121], v[44:45], v[230:231], v[120:121] op_sel_hi:[1,0,1] neg_lo:[0,1,0] neg_hi:[0,1,0]
	ds_read_b128 v[42:45], v233 offset:2768
	s_waitcnt lgkmcnt(12)
	v_pk_fma_f32 v[122:123], v[46:47], v[230:231], v[122:123] op_sel_hi:[1,0,1] neg_lo:[0,1,0] neg_hi:[0,1,0]
	v_pk_fma_f32 v[124:125], v[48:49], v[230:231], v[124:125] op_sel_hi:[1,0,1] neg_lo:[0,1,0] neg_hi:[0,1,0]
	ds_read_b128 v[46:49], v233 offset:2784
	v_pk_fma_f32 v[126:127], v[50:51], v[230:231], v[126:127] op_sel_hi:[1,0,1] neg_lo:[0,1,0] neg_hi:[0,1,0]
	v_pk_fma_f32 v[128:129], v[52:53], v[230:231], v[128:129] op_sel_hi:[1,0,1] neg_lo:[0,1,0] neg_hi:[0,1,0]
	ds_read_b128 v[50:53], v233 offset:2800
	s_waitcnt lgkmcnt(12)
	v_pk_fma_f32 v[130:131], v[54:55], v[230:231], v[130:131] op_sel_hi:[1,0,1] neg_lo:[0,1,0] neg_hi:[0,1,0]
	v_pk_fma_f32 v[132:133], v[56:57], v[230:231], v[132:133] op_sel_hi:[1,0,1] neg_lo:[0,1,0] neg_hi:[0,1,0]
	ds_read_b128 v[54:57], v233 offset:2816
	v_pk_fma_f32 v[134:135], v[58:59], v[230:231], v[134:135] op_sel_hi:[1,0,1] neg_lo:[0,1,0] neg_hi:[0,1,0]
	v_pk_fma_f32 v[136:137], v[60:61], v[230:231], v[136:137] op_sel_hi:[1,0,1] neg_lo:[0,1,0] neg_hi:[0,1,0]
	ds_read_b128 v[58:61], v233 offset:2832
	s_waitcnt lgkmcnt(12)
	v_pk_fma_f32 v[138:139], v[62:63], v[230:231], v[138:139] op_sel_hi:[1,0,1] neg_lo:[0,1,0] neg_hi:[0,1,0]
	v_pk_fma_f32 v[140:141], v[64:65], v[230:231], v[140:141] op_sel_hi:[1,0,1] neg_lo:[0,1,0] neg_hi:[0,1,0]
	ds_read_b128 v[62:65], v233 offset:2848
	v_pk_fma_f32 v[142:143], v[66:67], v[230:231], v[142:143] op_sel_hi:[1,0,1] neg_lo:[0,1,0] neg_hi:[0,1,0]
	v_pk_fma_f32 v[144:145], v[68:69], v[230:231], v[144:145] op_sel_hi:[1,0,1] neg_lo:[0,1,0] neg_hi:[0,1,0]
	ds_read_b128 v[66:69], v233 offset:2864
	s_waitcnt lgkmcnt(12)
	v_pk_fma_f32 v[146:147], v[70:71], v[230:231], v[146:147] op_sel_hi:[1,0,1] neg_lo:[0,1,0] neg_hi:[0,1,0]
	v_pk_fma_f32 v[148:149], v[72:73], v[230:231], v[148:149] op_sel_hi:[1,0,1] neg_lo:[0,1,0] neg_hi:[0,1,0]
	ds_read_b128 v[70:73], v233 offset:2880
	v_pk_fma_f32 v[150:151], v[194:195], v[230:231], v[150:151] op_sel_hi:[1,0,1] neg_lo:[0,1,0] neg_hi:[0,1,0]
	v_pk_fma_f32 v[152:153], v[196:197], v[230:231], v[152:153] op_sel_hi:[1,0,1] neg_lo:[0,1,0] neg_hi:[0,1,0]
	ds_read_b128 v[194:197], v233 offset:2896
	s_waitcnt lgkmcnt(12)
	v_pk_fma_f32 v[154:155], v[198:199], v[230:231], v[154:155] op_sel_hi:[1,0,1] neg_lo:[0,1,0] neg_hi:[0,1,0]
	v_pk_fma_f32 v[180:181], v[200:201], v[230:231], v[180:181] op_sel_hi:[1,0,1] neg_lo:[0,1,0] neg_hi:[0,1,0]
	ds_read_b128 v[198:201], v233 offset:2912
	v_pk_fma_f32 v[182:183], v[202:203], v[230:231], v[182:183] op_sel_hi:[1,0,1] neg_lo:[0,1,0] neg_hi:[0,1,0]
	v_pk_fma_f32 v[184:185], v[204:205], v[230:231], v[184:185] op_sel_hi:[1,0,1] neg_lo:[0,1,0] neg_hi:[0,1,0]
	ds_read_b128 v[202:205], v233 offset:2928
	s_waitcnt lgkmcnt(12)
	v_pk_fma_f32 v[186:187], v[206:207], v[230:231], v[186:187] op_sel_hi:[1,0,1] neg_lo:[0,1,0] neg_hi:[0,1,0]
	v_pk_fma_f32 v[188:189], v[208:209], v[230:231], v[188:189] op_sel_hi:[1,0,1] neg_lo:[0,1,0] neg_hi:[0,1,0]
	ds_read_b128 v[206:209], v233 offset:2944
	v_pk_fma_f32 v[190:191], v[226:227], v[230:231], v[190:191] op_sel_hi:[1,0,1] neg_lo:[0,1,0] neg_hi:[0,1,0]
	v_pk_fma_f32 v[192:193], v[228:229], v[230:231], v[192:193] op_sel_hi:[1,0,1] neg_lo:[0,1,0] neg_hi:[0,1,0]
	ds_read_b128 v[226:229], v233 offset:2960
	s_nop 0
	v_mov_b32_e32 v230, v116
	v_cvt_pk_bf16_f32 v232, v230, v230
	global_store_short v28, v232, s[0:1]
	s_add_u32 s0, s0, 0x400
	s_addc_u32 s1, s1, 0
	s_waitcnt lgkmcnt(12)
	v_pk_fma_f32 v[116:117], v[40:41], v[230:231], v[116:117] op_sel_hi:[1,0,1] neg_lo:[0,1,0] neg_hi:[0,1,0]
	v_pk_fma_f32 v[118:119], v[42:43], v[230:231], v[118:119] op_sel_hi:[1,0,1] neg_lo:[0,1,0] neg_hi:[0,1,0]
	v_pk_fma_f32 v[120:121], v[44:45], v[230:231], v[120:121] op_sel_hi:[1,0,1] neg_lo:[0,1,0] neg_hi:[0,1,0]
	ds_read_b128 v[42:45], v233 offset:3040
	s_waitcnt lgkmcnt(11)
	v_pk_fma_f32 v[122:123], v[46:47], v[230:231], v[122:123] op_sel_hi:[1,0,1] neg_lo:[0,1,0] neg_hi:[0,1,0]
	v_pk_fma_f32 v[124:125], v[48:49], v[230:231], v[124:125] op_sel_hi:[1,0,1] neg_lo:[0,1,0] neg_hi:[0,1,0]
	ds_read_b128 v[46:49], v233 offset:3056
	v_pk_fma_f32 v[126:127], v[50:51], v[230:231], v[126:127] op_sel_hi:[1,0,1] neg_lo:[0,1,0] neg_hi:[0,1,0]
	v_pk_fma_f32 v[128:129], v[52:53], v[230:231], v[128:129] op_sel_hi:[1,0,1] neg_lo:[0,1,0] neg_hi:[0,1,0]
	ds_read_b128 v[50:53], v233 offset:3072
	s_waitcnt lgkmcnt(11)
	v_pk_fma_f32 v[130:131], v[54:55], v[230:231], v[130:131] op_sel_hi:[1,0,1] neg_lo:[0,1,0] neg_hi:[0,1,0]
	v_pk_fma_f32 v[132:133], v[56:57], v[230:231], v[132:133] op_sel_hi:[1,0,1] neg_lo:[0,1,0] neg_hi:[0,1,0]
	ds_read_b128 v[54:57], v233 offset:3088
	v_pk_fma_f32 v[134:135], v[58:59], v[230:231], v[134:135] op_sel_hi:[1,0,1] neg_lo:[0,1,0] neg_hi:[0,1,0]
	v_pk_fma_f32 v[136:137], v[60:61], v[230:231], v[136:137] op_sel_hi:[1,0,1] neg_lo:[0,1,0] neg_hi:[0,1,0]
	ds_read_b128 v[58:61], v233 offset:3104
	s_waitcnt lgkmcnt(11)
	v_pk_fma_f32 v[138:139], v[62:63], v[230:231], v[138:139] op_sel_hi:[1,0,1] neg_lo:[0,1,0] neg_hi:[0,1,0]
	v_pk_fma_f32 v[140:141], v[64:65], v[230:231], v[140:141] op_sel_hi:[1,0,1] neg_lo:[0,1,0] neg_hi:[0,1,0]
	ds_read_b128 v[62:65], v233 offset:3120
	v_pk_fma_f32 v[142:143], v[66:67], v[230:231], v[142:143] op_sel_hi:[1,0,1] neg_lo:[0,1,0] neg_hi:[0,1,0]
	v_pk_fma_f32 v[144:145], v[68:69], v[230:231], v[144:145] op_sel_hi:[1,0,1] neg_lo:[0,1,0] neg_hi:[0,1,0]
	ds_read_b128 v[66:69], v233 offset:3136
	s_waitcnt lgkmcnt(11)
	v_pk_fma_f32 v[146:147], v[70:71], v[230:231], v[146:147] op_sel_hi:[1,0,1] neg_lo:[0,1,0] neg_hi:[0,1,0]
	v_pk_fma_f32 v[148:149], v[72:73], v[230:231], v[148:149] op_sel_hi:[1,0,1] neg_lo:[0,1,0] neg_hi:[0,1,0]
	ds_read_b128 v[70:73], v233 offset:3152
	v_pk_fma_f32 v[150:151], v[194:195], v[230:231], v[150:151] op_sel_hi:[1,0,1] neg_lo:[0,1,0] neg_hi:[0,1,0]
	v_pk_fma_f32 v[152:153], v[196:197], v[230:231], v[152:153] op_sel_hi:[1,0,1] neg_lo:[0,1,0] neg_hi:[0,1,0]
	ds_read_b128 v[194:197], v233 offset:3168
	s_waitcnt lgkmcnt(11)
	v_pk_fma_f32 v[154:155], v[198:199], v[230:231], v[154:155] op_sel_hi:[1,0,1] neg_lo:[0,1,0] neg_hi:[0,1,0]
	v_pk_fma_f32 v[180:181], v[200:201], v[230:231], v[180:181] op_sel_hi:[1,0,1] neg_lo:[0,1,0] neg_hi:[0,1,0]
	ds_read_b128 v[198:201], v233 offset:3184
	v_pk_fma_f32 v[182:183], v[202:203], v[230:231], v[182:183] op_sel_hi:[1,0,1] neg_lo:[0,1,0] neg_hi:[0,1,0]
	v_pk_fma_f32 v[184:185], v[204:205], v[230:231], v[184:185] op_sel_hi:[1,0,1] neg_lo:[0,1,0] neg_hi:[0,1,0]
	ds_read_b128 v[202:205], v233 offset:3200
	s_waitcnt lgkmcnt(11)
	v_pk_fma_f32 v[186:187], v[206:207], v[230:231], v[186:187] op_sel_hi:[1,0,1] neg_lo:[0,1,0] neg_hi:[0,1,0]
	v_pk_fma_f32 v[188:189], v[208:209], v[230:231], v[188:189] op_sel_hi:[1,0,1] neg_lo:[0,1,0] neg_hi:[0,1,0]
	ds_read_b128 v[206:209], v233 offset:3216
	v_pk_fma_f32 v[190:191], v[226:227], v[230:231], v[190:191] op_sel_hi:[1,0,1] neg_lo:[0,1,0] neg_hi:[0,1,0]
	v_pk_fma_f32 v[192:193], v[228:229], v[230:231], v[192:193] op_sel_hi:[1,0,1] neg_lo:[0,1,0] neg_hi:[0,1,0]
	ds_read_b128 v[226:229], v233 offset:3232
	s_nop 0
	v_mov_b32_e32 v230, v117
	v_cvt_pk_bf16_f32 v232, v230, v230
	global_store_short v28, v232, s[0:1]
	s_add_u32 s0, s0, 0x400
	s_addc_u32 s1, s1, 0
	s_waitcnt lgkmcnt(11)
	v_pk_fma_f32 v[118:119], v[42:43], v[230:231], v[118:119] op_sel_hi:[1,0,1] neg_lo:[0,1,0] neg_hi:[0,1,0]
	v_pk_fma_f32 v[120:121], v[44:45], v[230:231], v[120:121] op_sel_hi:[1,0,1] neg_lo:[0,1,0] neg_hi:[0,1,0]
	ds_read_b128 v[42:45], v233 offset:3312
	v_pk_fma_f32 v[122:123], v[46:47], v[230:231], v[122:123] op_sel_hi:[1,0,1] neg_lo:[0,1,0] neg_hi:[0,1,0]
	v_pk_fma_f32 v[124:125], v[48:49], v[230:231], v[124:125] op_sel_hi:[1,0,1] neg_lo:[0,1,0] neg_hi:[0,1,0]
	ds_read_b128 v[46:49], v233 offset:3328
	s_waitcnt lgkmcnt(11)
	v_pk_fma_f32 v[126:127], v[50:51], v[230:231], v[126:127] op_sel_hi:[1,0,1] neg_lo:[0,1,0] neg_hi:[0,1,0]
	v_pk_fma_f32 v[128:129], v[52:53], v[230:231], v[128:129] op_sel_hi:[1,0,1] neg_lo:[0,1,0] neg_hi:[0,1,0]
	ds_read_b128 v[50:53], v233 offset:3344
	v_pk_fma_f32 v[130:131], v[54:55], v[230:231], v[130:131] op_sel_hi:[1,0,1] neg_lo:[0,1,0] neg_hi:[0,1,0]
	v_pk_fma_f32 v[132:133], v[56:57], v[230:231], v[132:133] op_sel_hi:[1,0,1] neg_lo:[0,1,0] neg_hi:[0,1,0]
	ds_read_b128 v[54:57], v233 offset:3360
	s_waitcnt lgkmcnt(11)
	v_pk_fma_f32 v[134:135], v[58:59], v[230:231], v[134:135] op_sel_hi:[1,0,1] neg_lo:[0,1,0] neg_hi:[0,1,0]
	v_pk_fma_f32 v[136:137], v[60:61], v[230:231], v[136:137] op_sel_hi:[1,0,1] neg_lo:[0,1,0] neg_hi:[0,1,0]
	ds_read_b128 v[58:61], v233 offset:3376
	v_pk_fma_f32 v[138:139], v[62:63], v[230:231], v[138:139] op_sel_hi:[1,0,1] neg_lo:[0,1,0] neg_hi:[0,1,0]
	v_pk_fma_f32 v[140:141], v[64:65], v[230:231], v[140:141] op_sel_hi:[1,0,1] neg_lo:[0,1,0] neg_hi:[0,1,0]
	ds_read_b128 v[62:65], v233 offset:3392
	s_waitcnt lgkmcnt(11)
	v_pk_fma_f32 v[142:143], v[66:67], v[230:231], v[142:143] op_sel_hi:[1,0,1] neg_lo:[0,1,0] neg_hi:[0,1,0]
	v_pk_fma_f32 v[144:145], v[68:69], v[230:231], v[144:145] op_sel_hi:[1,0,1] neg_lo:[0,1,0] neg_hi:[0,1,0]
	ds_read_b128 v[66:69], v233 offset:3408
	v_pk_fma_f32 v[146:147], v[70:71], v[230:231], v[146:147] op_sel_hi:[1,0,1] neg_lo:[0,1,0] neg_hi:[0,1,0]
	v_pk_fma_f32 v[148:149], v[72:73], v[230:231], v[148:149] op_sel_hi:[1,0,1] neg_lo:[0,1,0] neg_hi:[0,1,0]
	ds_read_b128 v[70:73], v233 offset:3424
	s_waitcnt lgkmcnt(11)
	v_pk_fma_f32 v[150:151], v[194:195], v[230:231], v[150:151] op_sel_hi:[1,0,1] neg_lo:[0,1,0] neg_hi:[0,1,0]
	v_pk_fma_f32 v[152:153], v[196:197], v[230:231], v[152:153] op_sel_hi:[1,0,1] neg_lo:[0,1,0] neg_hi:[0,1,0]
	ds_read_b128 v[194:197], v233 offset:3440
	v_pk_fma_f32 v[154:155], v[198:199], v[230:231], v[154:155] op_sel_hi:[1,0,1] neg_lo:[0,1,0] neg_hi:[0,1,0]
	v_pk_fma_f32 v[180:181], v[200:201], v[230:231], v[180:181] op_sel_hi:[1,0,1] neg_lo:[0,1,0] neg_hi:[0,1,0]
	ds_read_b128 v[198:201], v233 offset:3456
	s_waitcnt lgkmcnt(11)
	v_pk_fma_f32 v[182:183], v[202:203], v[230:231], v[182:183] op_sel_hi:[1,0,1] neg_lo:[0,1,0] neg_hi:[0,1,0]
	v_pk_fma_f32 v[184:185], v[204:205], v[230:231], v[184:185] op_sel_hi:[1,0,1] neg_lo:[0,1,0] neg_hi:[0,1,0]
	ds_read_b128 v[202:205], v233 offset:3472
	v_pk_fma_f32 v[186:187], v[206:207], v[230:231], v[186:187] op_sel_hi:[1,0,1] neg_lo:[0,1,0] neg_hi:[0,1,0]
	v_pk_fma_f32 v[188:189], v[208:209], v[230:231], v[188:189] op_sel_hi:[1,0,1] neg_lo:[0,1,0] neg_hi:[0,1,0]
	ds_read_b128 v[206:209], v233 offset:3488
	s_waitcnt lgkmcnt(12)
	v_pk_fma_f32 v[190:191], v[226:227], v[230:231], v[190:191] op_sel_hi:[1,0,1] neg_lo:[0,1,0] neg_hi:[0,1,0]
	v_pk_fma_f32 v[192:193], v[228:229], v[230:231], v[192:193] op_sel_hi:[1,0,1] neg_lo:[0,1,0] neg_hi:[0,1,0]
	ds_read_b128 v[226:229], v233 offset:3504
	s_nop 0
	v_mov_b32_e32 v230, v118
	v_cvt_pk_bf16_f32 v232, v230, v230
	global_store_short v28, v232, s[0:1]
	s_add_u32 s0, s0, 0x400
	s_addc_u32 s1, s1, 0
	s_waitcnt lgkmcnt(11)
	v_pk_fma_f32 v[118:119], v[42:43], v[230:231], v[118:119] op_sel_hi:[1,0,1] neg_lo:[0,1,0] neg_hi:[0,1,0]
	v_pk_fma_f32 v[120:121], v[44:45], v[230:231], v[120:121] op_sel_hi:[1,0,1] neg_lo:[0,1,0] neg_hi:[0,1,0]
	ds_read_b128 v[42:45], v233 offset:3584
	v_pk_fma_f32 v[122:123], v[46:47], v[230:231], v[122:123] op_sel_hi:[1,0,1] neg_lo:[0,1,0] neg_hi:[0,1,0]
	v_pk_fma_f32 v[124:125], v[48:49], v[230:231], v[124:125] op_sel_hi:[1,0,1] neg_lo:[0,1,0] neg_hi:[0,1,0]
	ds_read_b128 v[46:49], v233 offset:3600
	s_waitcnt lgkmcnt(11)
	v_pk_fma_f32 v[126:127], v[50:51], v[230:231], v[126:127] op_sel_hi:[1,0,1] neg_lo:[0,1,0] neg_hi:[0,1,0]
	v_pk_fma_f32 v[128:129], v[52:53], v[230:231], v[128:129] op_sel_hi:[1,0,1] neg_lo:[0,1,0] neg_hi:[0,1,0]
	ds_read_b128 v[50:53], v233 offset:3616
	v_pk_fma_f32 v[130:131], v[54:55], v[230:231], v[130:131] op_sel_hi:[1,0,1] neg_lo:[0,1,0] neg_hi:[0,1,0]
	v_pk_fma_f32 v[132:133], v[56:57], v[230:231], v[132:133] op_sel_hi:[1,0,1] neg_lo:[0,1,0] neg_hi:[0,1,0]
	ds_read_b128 v[54:57], v233 offset:3632
	s_waitcnt lgkmcnt(11)
	v_pk_fma_f32 v[134:135], v[58:59], v[230:231], v[134:135] op_sel_hi:[1,0,1] neg_lo:[0,1,0] neg_hi:[0,1,0]
	v_pk_fma_f32 v[136:137], v[60:61], v[230:231], v[136:137] op_sel_hi:[1,0,1] neg_lo:[0,1,0] neg_hi:[0,1,0]
	ds_read_b128 v[58:61], v233 offset:3648
	v_pk_fma_f32 v[138:139], v[62:63], v[230:231], v[138:139] op_sel_hi:[1,0,1] neg_lo:[0,1,0] neg_hi:[0,1,0]
	v_pk_fma_f32 v[140:141], v[64:65], v[230:231], v[140:141] op_sel_hi:[1,0,1] neg_lo:[0,1,0] neg_hi:[0,1,0]
	ds_read_b128 v[62:65], v233 offset:3664
	s_waitcnt lgkmcnt(11)
	v_pk_fma_f32 v[142:143], v[66:67], v[230:231], v[142:143] op_sel_hi:[1,0,1] neg_lo:[0,1,0] neg_hi:[0,1,0]
	v_pk_fma_f32 v[144:145], v[68:69], v[230:231], v[144:145] op_sel_hi:[1,0,1] neg_lo:[0,1,0] neg_hi:[0,1,0]
	ds_read_b128 v[66:69], v233 offset:3680
	v_pk_fma_f32 v[146:147], v[70:71], v[230:231], v[146:147] op_sel_hi:[1,0,1] neg_lo:[0,1,0] neg_hi:[0,1,0]
	v_pk_fma_f32 v[148:149], v[72:73], v[230:231], v[148:149] op_sel_hi:[1,0,1] neg_lo:[0,1,0] neg_hi:[0,1,0]
	ds_read_b128 v[70:73], v233 offset:3696
	s_waitcnt lgkmcnt(11)
	v_pk_fma_f32 v[150:151], v[194:195], v[230:231], v[150:151] op_sel_hi:[1,0,1] neg_lo:[0,1,0] neg_hi:[0,1,0]
	v_pk_fma_f32 v[152:153], v[196:197], v[230:231], v[152:153] op_sel_hi:[1,0,1] neg_lo:[0,1,0] neg_hi:[0,1,0]
	ds_read_b128 v[194:197], v233 offset:3712
	v_pk_fma_f32 v[154:155], v[198:199], v[230:231], v[154:155] op_sel_hi:[1,0,1] neg_lo:[0,1,0] neg_hi:[0,1,0]
	v_pk_fma_f32 v[180:181], v[200:201], v[230:231], v[180:181] op_sel_hi:[1,0,1] neg_lo:[0,1,0] neg_hi:[0,1,0]
	ds_read_b128 v[198:201], v233 offset:3728
	s_waitcnt lgkmcnt(11)
	v_pk_fma_f32 v[182:183], v[202:203], v[230:231], v[182:183] op_sel_hi:[1,0,1] neg_lo:[0,1,0] neg_hi:[0,1,0]
	v_pk_fma_f32 v[184:185], v[204:205], v[230:231], v[184:185] op_sel_hi:[1,0,1] neg_lo:[0,1,0] neg_hi:[0,1,0]
	ds_read_b128 v[202:205], v233 offset:3744
	v_pk_fma_f32 v[186:187], v[206:207], v[230:231], v[186:187] op_sel_hi:[1,0,1] neg_lo:[0,1,0] neg_hi:[0,1,0]
	v_pk_fma_f32 v[188:189], v[208:209], v[230:231], v[188:189] op_sel_hi:[1,0,1] neg_lo:[0,1,0] neg_hi:[0,1,0]
	ds_read_b128 v[206:209], v233 offset:3760
	s_waitcnt lgkmcnt(12)
	v_pk_fma_f32 v[190:191], v[226:227], v[230:231], v[190:191] op_sel_hi:[1,0,1] neg_lo:[0,1,0] neg_hi:[0,1,0]
	v_pk_fma_f32 v[192:193], v[228:229], v[230:231], v[192:193] op_sel_hi:[1,0,1] neg_lo:[0,1,0] neg_hi:[0,1,0]
	ds_read_b128 v[226:229], v233 offset:3776
	s_nop 0
	v_mov_b32_e32 v230, v119
	v_cvt_pk_bf16_f32 v232, v230, v230
	global_store_short v28, v232, s[0:1]
	s_add_u32 s0, s0, 0x400
	s_addc_u32 s1, s1, 0
	s_waitcnt lgkmcnt(11)
	v_pk_fma_f32 v[120:121], v[44:45], v[230:231], v[120:121] op_sel_hi:[1,0,1] neg_lo:[0,1,0] neg_hi:[0,1,0]
	ds_read_b128 v[42:45], v233 offset:3856
	v_pk_fma_f32 v[122:123], v[46:47], v[230:231], v[122:123] op_sel_hi:[1,0,1] neg_lo:[0,1,0] neg_hi:[0,1,0]
	v_pk_fma_f32 v[124:125], v[48:49], v[230:231], v[124:125] op_sel_hi:[1,0,1] neg_lo:[0,1,0] neg_hi:[0,1,0]
	ds_read_b128 v[46:49], v233 offset:3872
	s_waitcnt lgkmcnt(11)
	v_pk_fma_f32 v[126:127], v[50:51], v[230:231], v[126:127] op_sel_hi:[1,0,1] neg_lo:[0,1,0] neg_hi:[0,1,0]
	v_pk_fma_f32 v[128:129], v[52:53], v[230:231], v[128:129] op_sel_hi:[1,0,1] neg_lo:[0,1,0] neg_hi:[0,1,0]
	ds_read_b128 v[50:53], v233 offset:3888
	v_pk_fma_f32 v[130:131], v[54:55], v[230:231], v[130:131] op_sel_hi:[1,0,1] neg_lo:[0,1,0] neg_hi:[0,1,0]
	v_pk_fma_f32 v[132:133], v[56:57], v[230:231], v[132:133] op_sel_hi:[1,0,1] neg_lo:[0,1,0] neg_hi:[0,1,0]
	ds_read_b128 v[54:57], v233 offset:3904
	s_waitcnt lgkmcnt(11)
	v_pk_fma_f32 v[134:135], v[58:59], v[230:231], v[134:135] op_sel_hi:[1,0,1] neg_lo:[0,1,0] neg_hi:[0,1,0]
	v_pk_fma_f32 v[136:137], v[60:61], v[230:231], v[136:137] op_sel_hi:[1,0,1] neg_lo:[0,1,0] neg_hi:[0,1,0]
	ds_read_b128 v[58:61], v233 offset:3920
	v_pk_fma_f32 v[138:139], v[62:63], v[230:231], v[138:139] op_sel_hi:[1,0,1] neg_lo:[0,1,0] neg_hi:[0,1,0]
	v_pk_fma_f32 v[140:141], v[64:65], v[230:231], v[140:141] op_sel_hi:[1,0,1] neg_lo:[0,1,0] neg_hi:[0,1,0]
	ds_read_b128 v[62:65], v233 offset:3936
	s_waitcnt lgkmcnt(11)
	v_pk_fma_f32 v[142:143], v[66:67], v[230:231], v[142:143] op_sel_hi:[1,0,1] neg_lo:[0,1,0] neg_hi:[0,1,0]
	v_pk_fma_f32 v[144:145], v[68:69], v[230:231], v[144:145] op_sel_hi:[1,0,1] neg_lo:[0,1,0] neg_hi:[0,1,0]
	ds_read_b128 v[66:69], v233 offset:3952
	v_pk_fma_f32 v[146:147], v[70:71], v[230:231], v[146:147] op_sel_hi:[1,0,1] neg_lo:[0,1,0] neg_hi:[0,1,0]
	v_pk_fma_f32 v[148:149], v[72:73], v[230:231], v[148:149] op_sel_hi:[1,0,1] neg_lo:[0,1,0] neg_hi:[0,1,0]
	ds_read_b128 v[70:73], v233 offset:3968
	s_waitcnt lgkmcnt(11)
	v_pk_fma_f32 v[150:151], v[194:195], v[230:231], v[150:151] op_sel_hi:[1,0,1] neg_lo:[0,1,0] neg_hi:[0,1,0]
	v_pk_fma_f32 v[152:153], v[196:197], v[230:231], v[152:153] op_sel_hi:[1,0,1] neg_lo:[0,1,0] neg_hi:[0,1,0]
	ds_read_b128 v[194:197], v233 offset:3984
	v_pk_fma_f32 v[154:155], v[198:199], v[230:231], v[154:155] op_sel_hi:[1,0,1] neg_lo:[0,1,0] neg_hi:[0,1,0]
	v_pk_fma_f32 v[180:181], v[200:201], v[230:231], v[180:181] op_sel_hi:[1,0,1] neg_lo:[0,1,0] neg_hi:[0,1,0]
	ds_read_b128 v[198:201], v233 offset:4000
	s_waitcnt lgkmcnt(11)
	v_pk_fma_f32 v[182:183], v[202:203], v[230:231], v[182:183] op_sel_hi:[1,0,1] neg_lo:[0,1,0] neg_hi:[0,1,0]
	v_pk_fma_f32 v[184:185], v[204:205], v[230:231], v[184:185] op_sel_hi:[1,0,1] neg_lo:[0,1,0] neg_hi:[0,1,0]
	ds_read_b128 v[202:205], v233 offset:4016
	v_pk_fma_f32 v[186:187], v[206:207], v[230:231], v[186:187] op_sel_hi:[1,0,1] neg_lo:[0,1,0] neg_hi:[0,1,0]
	v_pk_fma_f32 v[188:189], v[208:209], v[230:231], v[188:189] op_sel_hi:[1,0,1] neg_lo:[0,1,0] neg_hi:[0,1,0]
	ds_read_b128 v[206:209], v233 offset:4032
	s_waitcnt lgkmcnt(12)
	v_pk_fma_f32 v[190:191], v[226:227], v[230:231], v[190:191] op_sel_hi:[1,0,1] neg_lo:[0,1,0] neg_hi:[0,1,0]
	v_pk_fma_f32 v[192:193], v[228:229], v[230:231], v[192:193] op_sel_hi:[1,0,1] neg_lo:[0,1,0] neg_hi:[0,1,0]
	ds_read_b128 v[226:229], v233 offset:4048
	s_nop 0
	v_mov_b32_e32 v230, v120
	v_cvt_pk_bf16_f32 v232, v230, v230
	global_store_short v28, v232, s[0:1]
	s_add_u32 s0, s0, 0x400
	s_addc_u32 s1, s1, 0
	s_waitcnt lgkmcnt(11)
	v_pk_fma_f32 v[120:121], v[44:45], v[230:231], v[120:121] op_sel_hi:[1,0,1] neg_lo:[0,1,0] neg_hi:[0,1,0]
	v_pk_fma_f32 v[122:123], v[46:47], v[230:231], v[122:123] op_sel_hi:[1,0,1] neg_lo:[0,1,0] neg_hi:[0,1,0]
	v_pk_fma_f32 v[124:125], v[48:49], v[230:231], v[124:125] op_sel_hi:[1,0,1] neg_lo:[0,1,0] neg_hi:[0,1,0]
	ds_read_b128 v[46:49], v233 offset:4144
	s_waitcnt lgkmcnt(10)
	v_pk_fma_f32 v[126:127], v[50:51], v[230:231], v[126:127] op_sel_hi:[1,0,1] neg_lo:[0,1,0] neg_hi:[0,1,0]
	v_pk_fma_f32 v[128:129], v[52:53], v[230:231], v[128:129] op_sel_hi:[1,0,1] neg_lo:[0,1,0] neg_hi:[0,1,0]
	ds_read_b128 v[50:53], v233 offset:4160
	v_pk_fma_f32 v[130:131], v[54:55], v[230:231], v[130:131] op_sel_hi:[1,0,1] neg_lo:[0,1,0] neg_hi:[0,1,0]
	v_pk_fma_f32 v[132:133], v[56:57], v[230:231], v[132:133] op_sel_hi:[1,0,1] neg_lo:[0,1,0] neg_hi:[0,1,0]
	ds_read_b128 v[54:57], v233 offset:4176
	s_waitcnt lgkmcnt(10)
	v_pk_fma_f32 v[134:135], v[58:59], v[230:231], v[134:135] op_sel_hi:[1,0,1] neg_lo:[0,1,0] neg_hi:[0,1,0]
	v_pk_fma_f32 v[136:137], v[60:61], v[230:231], v[136:137] op_sel_hi:[1,0,1] neg_lo:[0,1,0] neg_hi:[0,1,0]
	ds_read_b128 v[58:61], v233 offset:4192
	v_pk_fma_f32 v[138:139], v[62:63], v[230:231], v[138:139] op_sel_hi:[1,0,1] neg_lo:[0,1,0] neg_hi:[0,1,0]
	v_pk_fma_f32 v[140:141], v[64:65], v[230:231], v[140:141] op_sel_hi:[1,0,1] neg_lo:[0,1,0] neg_hi:[0,1,0]
	ds_read_b128 v[62:65], v233 offset:4208
	s_waitcnt lgkmcnt(10)
	v_pk_fma_f32 v[142:143], v[66:67], v[230:231], v[142:143] op_sel_hi:[1,0,1] neg_lo:[0,1,0] neg_hi:[0,1,0]
	v_pk_fma_f32 v[144:145], v[68:69], v[230:231], v[144:145] op_sel_hi:[1,0,1] neg_lo:[0,1,0] neg_hi:[0,1,0]
	ds_read_b128 v[66:69], v233 offset:4224
	v_pk_fma_f32 v[146:147], v[70:71], v[230:231], v[146:147] op_sel_hi:[1,0,1] neg_lo:[0,1,0] neg_hi:[0,1,0]
	v_pk_fma_f32 v[148:149], v[72:73], v[230:231], v[148:149] op_sel_hi:[1,0,1] neg_lo:[0,1,0] neg_hi:[0,1,0]
	ds_read_b128 v[70:73], v233 offset:4240
	s_waitcnt lgkmcnt(10)
	v_pk_fma_f32 v[150:151], v[194:195], v[230:231], v[150:151] op_sel_hi:[1,0,1] neg_lo:[0,1,0] neg_hi:[0,1,0]
	v_pk_fma_f32 v[152:153], v[196:197], v[230:231], v[152:153] op_sel_hi:[1,0,1] neg_lo:[0,1,0] neg_hi:[0,1,0]
	ds_read_b128 v[194:197], v233 offset:4256
	v_pk_fma_f32 v[154:155], v[198:199], v[230:231], v[154:155] op_sel_hi:[1,0,1] neg_lo:[0,1,0] neg_hi:[0,1,0]
	v_pk_fma_f32 v[180:181], v[200:201], v[230:231], v[180:181] op_sel_hi:[1,0,1] neg_lo:[0,1,0] neg_hi:[0,1,0]
	ds_read_b128 v[198:201], v233 offset:4272
	s_waitcnt lgkmcnt(10)
	v_pk_fma_f32 v[182:183], v[202:203], v[230:231], v[182:183] op_sel_hi:[1,0,1] neg_lo:[0,1,0] neg_hi:[0,1,0]
	v_pk_fma_f32 v[184:185], v[204:205], v[230:231], v[184:185] op_sel_hi:[1,0,1] neg_lo:[0,1,0] neg_hi:[0,1,0]
	ds_read_b128 v[202:205], v233 offset:4288
	v_pk_fma_f32 v[186:187], v[206:207], v[230:231], v[186:187] op_sel_hi:[1,0,1] neg_lo:[0,1,0] neg_hi:[0,1,0]
	v_pk_fma_f32 v[188:189], v[208:209], v[230:231], v[188:189] op_sel_hi:[1,0,1] neg_lo:[0,1,0] neg_hi:[0,1,0]
	ds_read_b128 v[206:209], v233 offset:4304
	s_waitcnt lgkmcnt(11)
	v_pk_fma_f32 v[190:191], v[226:227], v[230:231], v[190:191] op_sel_hi:[1,0,1] neg_lo:[0,1,0] neg_hi:[0,1,0]
	v_pk_fma_f32 v[192:193], v[228:229], v[230:231], v[192:193] op_sel_hi:[1,0,1] neg_lo:[0,1,0] neg_hi:[0,1,0]
	ds_read_b128 v[226:229], v233 offset:4320
	s_nop 0
	v_mov_b32_e32 v230, v121
	v_cvt_pk_bf16_f32 v232, v230, v230
	global_store_short v28, v232, s[0:1]
	s_add_u32 s0, s0, 0x400
	s_addc_u32 s1, s1, 0
	s_waitcnt lgkmcnt(10)
	v_pk_fma_f32 v[122:123], v[46:47], v[230:231], v[122:123] op_sel_hi:[1,0,1] neg_lo:[0,1,0] neg_hi:[0,1,0]
	v_pk_fma_f32 v[124:125], v[48:49], v[230:231], v[124:125] op_sel_hi:[1,0,1] neg_lo:[0,1,0] neg_hi:[0,1,0]
	ds_read_b128 v[46:49], v233 offset:4416
	v_pk_fma_f32 v[126:127], v[50:51], v[230:231], v[126:127] op_sel_hi:[1,0,1] neg_lo:[0,1,0] neg_hi:[0,1,0]
	v_pk_fma_f32 v[128:129], v[52:53], v[230:231], v[128:129] op_sel_hi:[1,0,1] neg_lo:[0,1,0] neg_hi:[0,1,0]
	ds_read_b128 v[50:53], v233 offset:4432
	s_waitcnt lgkmcnt(10)
	v_pk_fma_f32 v[130:131], v[54:55], v[230:231], v[130:131] op_sel_hi:[1,0,1] neg_lo:[0,1,0] neg_hi:[0,1,0]
	v_pk_fma_f32 v[132:133], v[56:57], v[230:231], v[132:133] op_sel_hi:[1,0,1] neg_lo:[0,1,0] neg_hi:[0,1,0]
	ds_read_b128 v[54:57], v233 offset:4448
	v_pk_fma_f32 v[134:135], v[58:59], v[230:231], v[134:135] op_sel_hi:[1,0,1] neg_lo:[0,1,0] neg_hi:[0,1,0]
	v_pk_fma_f32 v[136:137], v[60:61], v[230:231], v[136:137] op_sel_hi:[1,0,1] neg_lo:[0,1,0] neg_hi:[0,1,0]
	ds_read_b128 v[58:61], v233 offset:4464
	s_waitcnt lgkmcnt(10)
	v_pk_fma_f32 v[138:139], v[62:63], v[230:231], v[138:139] op_sel_hi:[1,0,1] neg_lo:[0,1,0] neg_hi:[0,1,0]
	v_pk_fma_f32 v[140:141], v[64:65], v[230:231], v[140:141] op_sel_hi:[1,0,1] neg_lo:[0,1,0] neg_hi:[0,1,0]
	ds_read_b128 v[62:65], v233 offset:4480
	v_pk_fma_f32 v[142:143], v[66:67], v[230:231], v[142:143] op_sel_hi:[1,0,1] neg_lo:[0,1,0] neg_hi:[0,1,0]
	v_pk_fma_f32 v[144:145], v[68:69], v[230:231], v[144:145] op_sel_hi:[1,0,1] neg_lo:[0,1,0] neg_hi:[0,1,0]
	ds_read_b128 v[66:69], v233 offset:4496
	s_waitcnt lgkmcnt(10)
	v_pk_fma_f32 v[146:147], v[70:71], v[230:231], v[146:147] op_sel_hi:[1,0,1] neg_lo:[0,1,0] neg_hi:[0,1,0]
	v_pk_fma_f32 v[148:149], v[72:73], v[230:231], v[148:149] op_sel_hi:[1,0,1] neg_lo:[0,1,0] neg_hi:[0,1,0]
	ds_read_b128 v[70:73], v233 offset:4512
	v_pk_fma_f32 v[150:151], v[194:195], v[230:231], v[150:151] op_sel_hi:[1,0,1] neg_lo:[0,1,0] neg_hi:[0,1,0]
	v_pk_fma_f32 v[152:153], v[196:197], v[230:231], v[152:153] op_sel_hi:[1,0,1] neg_lo:[0,1,0] neg_hi:[0,1,0]
	ds_read_b128 v[194:197], v233 offset:4528
	s_waitcnt lgkmcnt(10)
	v_pk_fma_f32 v[154:155], v[198:199], v[230:231], v[154:155] op_sel_hi:[1,0,1] neg_lo:[0,1,0] neg_hi:[0,1,0]
	v_pk_fma_f32 v[180:181], v[200:201], v[230:231], v[180:181] op_sel_hi:[1,0,1] neg_lo:[0,1,0] neg_hi:[0,1,0]
	ds_read_b128 v[198:201], v233 offset:4544
	v_pk_fma_f32 v[182:183], v[202:203], v[230:231], v[182:183] op_sel_hi:[1,0,1] neg_lo:[0,1,0] neg_hi:[0,1,0]
	v_pk_fma_f32 v[184:185], v[204:205], v[230:231], v[184:185] op_sel_hi:[1,0,1] neg_lo:[0,1,0] neg_hi:[0,1,0]
	ds_read_b128 v[202:205], v233 offset:4560
	s_waitcnt lgkmcnt(10)
	v_pk_fma_f32 v[186:187], v[206:207], v[230:231], v[186:187] op_sel_hi:[1,0,1] neg_lo:[0,1,0] neg_hi:[0,1,0]
	v_pk_fma_f32 v[188:189], v[208:209], v[230:231], v[188:189] op_sel_hi:[1,0,1] neg_lo:[0,1,0] neg_hi:[0,1,0]
	ds_read_b128 v[206:209], v233 offset:4576
	v_pk_fma_f32 v[190:191], v[226:227], v[230:231], v[190:191] op_sel_hi:[1,0,1] neg_lo:[0,1,0] neg_hi:[0,1,0]
	v_pk_fma_f32 v[192:193], v[228:229], v[230:231], v[192:193] op_sel_hi:[1,0,1] neg_lo:[0,1,0] neg_hi:[0,1,0]
	ds_read_b128 v[226:229], v233 offset:4592
	s_nop 0
	v_mov_b32_e32 v230, v122
	v_cvt_pk_bf16_f32 v232, v230, v230
	global_store_short v28, v232, s[0:1]
	s_add_u32 s0, s0, 0x400
	s_addc_u32 s1, s1, 0
	s_waitcnt lgkmcnt(10)
	v_pk_fma_f32 v[122:123], v[46:47], v[230:231], v[122:123] op_sel_hi:[1,0,1] neg_lo:[0,1,0] neg_hi:[0,1,0]
	v_pk_fma_f32 v[124:125], v[48:49], v[230:231], v[124:125] op_sel_hi:[1,0,1] neg_lo:[0,1,0] neg_hi:[0,1,0]
	ds_read_b128 v[46:49], v233 offset:4688
	v_pk_fma_f32 v[126:127], v[50:51], v[230:231], v[126:127] op_sel_hi:[1,0,1] neg_lo:[0,1,0] neg_hi:[0,1,0]
	v_pk_fma_f32 v[128:129], v[52:53], v[230:231], v[128:129] op_sel_hi:[1,0,1] neg_lo:[0,1,0] neg_hi:[0,1,0]
	ds_read_b128 v[50:53], v233 offset:4704
	s_waitcnt lgkmcnt(10)
	v_pk_fma_f32 v[130:131], v[54:55], v[230:231], v[130:131] op_sel_hi:[1,0,1] neg_lo:[0,1,0] neg_hi:[0,1,0]
	v_pk_fma_f32 v[132:133], v[56:57], v[230:231], v[132:133] op_sel_hi:[1,0,1] neg_lo:[0,1,0] neg_hi:[0,1,0]
	ds_read_b128 v[54:57], v233 offset:4720
	v_pk_fma_f32 v[134:135], v[58:59], v[230:231], v[134:135] op_sel_hi:[1,0,1] neg_lo:[0,1,0] neg_hi:[0,1,0]
	v_pk_fma_f32 v[136:137], v[60:61], v[230:231], v[136:137] op_sel_hi:[1,0,1] neg_lo:[0,1,0] neg_hi:[0,1,0]
	ds_read_b128 v[58:61], v233 offset:4736
	s_waitcnt lgkmcnt(10)
	v_pk_fma_f32 v[138:139], v[62:63], v[230:231], v[138:139] op_sel_hi:[1,0,1] neg_lo:[0,1,0] neg_hi:[0,1,0]
	v_pk_fma_f32 v[140:141], v[64:65], v[230:231], v[140:141] op_sel_hi:[1,0,1] neg_lo:[0,1,0] neg_hi:[0,1,0]
	ds_read_b128 v[62:65], v233 offset:4752
	v_pk_fma_f32 v[142:143], v[66:67], v[230:231], v[142:143] op_sel_hi:[1,0,1] neg_lo:[0,1,0] neg_hi:[0,1,0]
	v_pk_fma_f32 v[144:145], v[68:69], v[230:231], v[144:145] op_sel_hi:[1,0,1] neg_lo:[0,1,0] neg_hi:[0,1,0]
	ds_read_b128 v[66:69], v233 offset:4768
	s_waitcnt lgkmcnt(10)
	v_pk_fma_f32 v[146:147], v[70:71], v[230:231], v[146:147] op_sel_hi:[1,0,1] neg_lo:[0,1,0] neg_hi:[0,1,0]
	v_pk_fma_f32 v[148:149], v[72:73], v[230:231], v[148:149] op_sel_hi:[1,0,1] neg_lo:[0,1,0] neg_hi:[0,1,0]
	ds_read_b128 v[70:73], v233 offset:4784
	v_pk_fma_f32 v[150:151], v[194:195], v[230:231], v[150:151] op_sel_hi:[1,0,1] neg_lo:[0,1,0] neg_hi:[0,1,0]
	v_pk_fma_f32 v[152:153], v[196:197], v[230:231], v[152:153] op_sel_hi:[1,0,1] neg_lo:[0,1,0] neg_hi:[0,1,0]
	ds_read_b128 v[194:197], v233 offset:4800
	s_waitcnt lgkmcnt(10)
	v_pk_fma_f32 v[154:155], v[198:199], v[230:231], v[154:155] op_sel_hi:[1,0,1] neg_lo:[0,1,0] neg_hi:[0,1,0]
	v_pk_fma_f32 v[180:181], v[200:201], v[230:231], v[180:181] op_sel_hi:[1,0,1] neg_lo:[0,1,0] neg_hi:[0,1,0]
	ds_read_b128 v[198:201], v233 offset:4816
	v_pk_fma_f32 v[182:183], v[202:203], v[230:231], v[182:183] op_sel_hi:[1,0,1] neg_lo:[0,1,0] neg_hi:[0,1,0]
	v_pk_fma_f32 v[184:185], v[204:205], v[230:231], v[184:185] op_sel_hi:[1,0,1] neg_lo:[0,1,0] neg_hi:[0,1,0]
	ds_read_b128 v[202:205], v233 offset:4832
	s_waitcnt lgkmcnt(10)
	v_pk_fma_f32 v[186:187], v[206:207], v[230:231], v[186:187] op_sel_hi:[1,0,1] neg_lo:[0,1,0] neg_hi:[0,1,0]
	v_pk_fma_f32 v[188:189], v[208:209], v[230:231], v[188:189] op_sel_hi:[1,0,1] neg_lo:[0,1,0] neg_hi:[0,1,0]
	ds_read_b128 v[206:209], v233 offset:4848
	v_pk_fma_f32 v[190:191], v[226:227], v[230:231], v[190:191] op_sel_hi:[1,0,1] neg_lo:[0,1,0] neg_hi:[0,1,0]
	v_pk_fma_f32 v[192:193], v[228:229], v[230:231], v[192:193] op_sel_hi:[1,0,1] neg_lo:[0,1,0] neg_hi:[0,1,0]
	ds_read_b128 v[226:229], v233 offset:4864
	s_nop 0
	v_mov_b32_e32 v230, v123
	v_cvt_pk_bf16_f32 v232, v230, v230
	global_store_short v28, v232, s[0:1]
	s_add_u32 s0, s0, 0x400
	s_addc_u32 s1, s1, 0
	s_waitcnt lgkmcnt(10)
	v_pk_fma_f32 v[124:125], v[48:49], v[230:231], v[124:125] op_sel_hi:[1,0,1] neg_lo:[0,1,0] neg_hi:[0,1,0]
	ds_read_b128 v[46:49], v233 offset:4960
	v_pk_fma_f32 v[126:127], v[50:51], v[230:231], v[126:127] op_sel_hi:[1,0,1] neg_lo:[0,1,0] neg_hi:[0,1,0]
	v_pk_fma_f32 v[128:129], v[52:53], v[230:231], v[128:129] op_sel_hi:[1,0,1] neg_lo:[0,1,0] neg_hi:[0,1,0]
	ds_read_b128 v[50:53], v233 offset:4976
	s_waitcnt lgkmcnt(10)
	v_pk_fma_f32 v[130:131], v[54:55], v[230:231], v[130:131] op_sel_hi:[1,0,1] neg_lo:[0,1,0] neg_hi:[0,1,0]
	v_pk_fma_f32 v[132:133], v[56:57], v[230:231], v[132:133] op_sel_hi:[1,0,1] neg_lo:[0,1,0] neg_hi:[0,1,0]
	ds_read_b128 v[54:57], v233 offset:4992
	v_pk_fma_f32 v[134:135], v[58:59], v[230:231], v[134:135] op_sel_hi:[1,0,1] neg_lo:[0,1,0] neg_hi:[0,1,0]
	v_pk_fma_f32 v[136:137], v[60:61], v[230:231], v[136:137] op_sel_hi:[1,0,1] neg_lo:[0,1,0] neg_hi:[0,1,0]
	ds_read_b128 v[58:61], v233 offset:5008
	s_waitcnt lgkmcnt(10)
	v_pk_fma_f32 v[138:139], v[62:63], v[230:231], v[138:139] op_sel_hi:[1,0,1] neg_lo:[0,1,0] neg_hi:[0,1,0]
	v_pk_fma_f32 v[140:141], v[64:65], v[230:231], v[140:141] op_sel_hi:[1,0,1] neg_lo:[0,1,0] neg_hi:[0,1,0]
	ds_read_b128 v[62:65], v233 offset:5024
	v_pk_fma_f32 v[142:143], v[66:67], v[230:231], v[142:143] op_sel_hi:[1,0,1] neg_lo:[0,1,0] neg_hi:[0,1,0]
	v_pk_fma_f32 v[144:145], v[68:69], v[230:231], v[144:145] op_sel_hi:[1,0,1] neg_lo:[0,1,0] neg_hi:[0,1,0]
	ds_read_b128 v[66:69], v233 offset:5040
	s_waitcnt lgkmcnt(10)
	v_pk_fma_f32 v[146:147], v[70:71], v[230:231], v[146:147] op_sel_hi:[1,0,1] neg_lo:[0,1,0] neg_hi:[0,1,0]
	v_pk_fma_f32 v[148:149], v[72:73], v[230:231], v[148:149] op_sel_hi:[1,0,1] neg_lo:[0,1,0] neg_hi:[0,1,0]
	ds_read_b128 v[70:73], v233 offset:5056
	v_pk_fma_f32 v[150:151], v[194:195], v[230:231], v[150:151] op_sel_hi:[1,0,1] neg_lo:[0,1,0] neg_hi:[0,1,0]
	v_pk_fma_f32 v[152:153], v[196:197], v[230:231], v[152:153] op_sel_hi:[1,0,1] neg_lo:[0,1,0] neg_hi:[0,1,0]
	ds_read_b128 v[194:197], v233 offset:5072
	s_waitcnt lgkmcnt(10)
	v_pk_fma_f32 v[154:155], v[198:199], v[230:231], v[154:155] op_sel_hi:[1,0,1] neg_lo:[0,1,0] neg_hi:[0,1,0]
	v_pk_fma_f32 v[180:181], v[200:201], v[230:231], v[180:181] op_sel_hi:[1,0,1] neg_lo:[0,1,0] neg_hi:[0,1,0]
	ds_read_b128 v[198:201], v233 offset:5088
	v_pk_fma_f32 v[182:183], v[202:203], v[230:231], v[182:183] op_sel_hi:[1,0,1] neg_lo:[0,1,0] neg_hi:[0,1,0]
	v_pk_fma_f32 v[184:185], v[204:205], v[230:231], v[184:185] op_sel_hi:[1,0,1] neg_lo:[0,1,0] neg_hi:[0,1,0]
	ds_read_b128 v[202:205], v233 offset:5104
	s_waitcnt lgkmcnt(10)
	v_pk_fma_f32 v[186:187], v[206:207], v[230:231], v[186:187] op_sel_hi:[1,0,1] neg_lo:[0,1,0] neg_hi:[0,1,0]
	v_pk_fma_f32 v[188:189], v[208:209], v[230:231], v[188:189] op_sel_hi:[1,0,1] neg_lo:[0,1,0] neg_hi:[0,1,0]
	ds_read_b128 v[206:209], v233 offset:5120
	v_pk_fma_f32 v[190:191], v[226:227], v[230:231], v[190:191] op_sel_hi:[1,0,1] neg_lo:[0,1,0] neg_hi:[0,1,0]
	v_pk_fma_f32 v[192:193], v[228:229], v[230:231], v[192:193] op_sel_hi:[1,0,1] neg_lo:[0,1,0] neg_hi:[0,1,0]
	ds_read_b128 v[226:229], v233 offset:5136
	s_nop 0
	v_mov_b32_e32 v230, v124
	v_cvt_pk_bf16_f32 v232, v230, v230
	global_store_short v28, v232, s[0:1]
	s_add_u32 s0, s0, 0x400
	s_addc_u32 s1, s1, 0
	s_waitcnt lgkmcnt(10)
	v_pk_fma_f32 v[124:125], v[48:49], v[230:231], v[124:125] op_sel_hi:[1,0,1] neg_lo:[0,1,0] neg_hi:[0,1,0]
	v_pk_fma_f32 v[126:127], v[50:51], v[230:231], v[126:127] op_sel_hi:[1,0,1] neg_lo:[0,1,0] neg_hi:[0,1,0]
	v_pk_fma_f32 v[128:129], v[52:53], v[230:231], v[128:129] op_sel_hi:[1,0,1] neg_lo:[0,1,0] neg_hi:[0,1,0]
	ds_read_b128 v[50:53], v233 offset:5248
	s_waitcnt lgkmcnt(9)
	v_pk_fma_f32 v[130:131], v[54:55], v[230:231], v[130:131] op_sel_hi:[1,0,1] neg_lo:[0,1,0] neg_hi:[0,1,0]
	v_pk_fma_f32 v[132:133], v[56:57], v[230:231], v[132:133] op_sel_hi:[1,0,1] neg_lo:[0,1,0] neg_hi:[0,1,0]
	ds_read_b128 v[54:57], v233 offset:5264
	v_pk_fma_f32 v[134:135], v[58:59], v[230:231], v[134:135] op_sel_hi:[1,0,1] neg_lo:[0,1,0] neg_hi:[0,1,0]
	v_pk_fma_f32 v[136:137], v[60:61], v[230:231], v[136:137] op_sel_hi:[1,0,1] neg_lo:[0,1,0] neg_hi:[0,1,0]
	ds_read_b128 v[58:61], v233 offset:5280
	s_waitcnt lgkmcnt(9)
	v_pk_fma_f32 v[138:139], v[62:63], v[230:231], v[138:139] op_sel_hi:[1,0,1] neg_lo:[0,1,0] neg_hi:[0,1,0]
	v_pk_fma_f32 v[140:141], v[64:65], v[230:231], v[140:141] op_sel_hi:[1,0,1] neg_lo:[0,1,0] neg_hi:[0,1,0]
	ds_read_b128 v[62:65], v233 offset:5296
	v_pk_fma_f32 v[142:143], v[66:67], v[230:231], v[142:143] op_sel_hi:[1,0,1] neg_lo:[0,1,0] neg_hi:[0,1,0]
	v_pk_fma_f32 v[144:145], v[68:69], v[230:231], v[144:145] op_sel_hi:[1,0,1] neg_lo:[0,1,0] neg_hi:[0,1,0]
	ds_read_b128 v[66:69], v233 offset:5312
	s_waitcnt lgkmcnt(9)
	v_pk_fma_f32 v[146:147], v[70:71], v[230:231], v[146:147] op_sel_hi:[1,0,1] neg_lo:[0,1,0] neg_hi:[0,1,0]
	v_pk_fma_f32 v[148:149], v[72:73], v[230:231], v[148:149] op_sel_hi:[1,0,1] neg_lo:[0,1,0] neg_hi:[0,1,0]
	ds_read_b128 v[70:73], v233 offset:5328
	v_pk_fma_f32 v[150:151], v[194:195], v[230:231], v[150:151] op_sel_hi:[1,0,1] neg_lo:[0,1,0] neg_hi:[0,1,0]
	v_pk_fma_f32 v[152:153], v[196:197], v[230:231], v[152:153] op_sel_hi:[1,0,1] neg_lo:[0,1,0] neg_hi:[0,1,0]
	ds_read_b128 v[194:197], v233 offset:5344
	s_waitcnt lgkmcnt(9)
	v_pk_fma_f32 v[154:155], v[198:199], v[230:231], v[154:155] op_sel_hi:[1,0,1] neg_lo:[0,1,0] neg_hi:[0,1,0]
	v_pk_fma_f32 v[180:181], v[200:201], v[230:231], v[180:181] op_sel_hi:[1,0,1] neg_lo:[0,1,0] neg_hi:[0,1,0]
	ds_read_b128 v[198:201], v233 offset:5360
	v_pk_fma_f32 v[182:183], v[202:203], v[230:231], v[182:183] op_sel_hi:[1,0,1] neg_lo:[0,1,0] neg_hi:[0,1,0]
	v_pk_fma_f32 v[184:185], v[204:205], v[230:231], v[184:185] op_sel_hi:[1,0,1] neg_lo:[0,1,0] neg_hi:[0,1,0]
	ds_read_b128 v[202:205], v233 offset:5376
	s_waitcnt lgkmcnt(9)
	v_pk_fma_f32 v[186:187], v[206:207], v[230:231], v[186:187] op_sel_hi:[1,0,1] neg_lo:[0,1,0] neg_hi:[0,1,0]
	v_pk_fma_f32 v[188:189], v[208:209], v[230:231], v[188:189] op_sel_hi:[1,0,1] neg_lo:[0,1,0] neg_hi:[0,1,0]
	ds_read_b128 v[206:209], v233 offset:5392
	v_pk_fma_f32 v[190:191], v[226:227], v[230:231], v[190:191] op_sel_hi:[1,0,1] neg_lo:[0,1,0] neg_hi:[0,1,0]
	v_pk_fma_f32 v[192:193], v[228:229], v[230:231], v[192:193] op_sel_hi:[1,0,1] neg_lo:[0,1,0] neg_hi:[0,1,0]
	ds_read_b128 v[226:229], v233 offset:5408
	s_nop 0
	v_mov_b32_e32 v230, v125
	v_cvt_pk_bf16_f32 v232, v230, v230
	global_store_short v28, v232, s[0:1]
	s_add_u32 s0, s0, 0x400
	s_addc_u32 s1, s1, 0
	s_waitcnt lgkmcnt(9)
	v_pk_fma_f32 v[126:127], v[50:51], v[230:231], v[126:127] op_sel_hi:[1,0,1] neg_lo:[0,1,0] neg_hi:[0,1,0]
	v_pk_fma_f32 v[128:129], v[52:53], v[230:231], v[128:129] op_sel_hi:[1,0,1] neg_lo:[0,1,0] neg_hi:[0,1,0]
	ds_read_b128 v[50:53], v233 offset:5520
	v_pk_fma_f32 v[130:131], v[54:55], v[230:231], v[130:131] op_sel_hi:[1,0,1] neg_lo:[0,1,0] neg_hi:[0,1,0]
	v_pk_fma_f32 v[132:133], v[56:57], v[230:231], v[132:133] op_sel_hi:[1,0,1] neg_lo:[0,1,0] neg_hi:[0,1,0]
	ds_read_b128 v[54:57], v233 offset:5536
	s_waitcnt lgkmcnt(9)
	v_pk_fma_f32 v[134:135], v[58:59], v[230:231], v[134:135] op_sel_hi:[1,0,1] neg_lo:[0,1,0] neg_hi:[0,1,0]
	v_pk_fma_f32 v[136:137], v[60:61], v[230:231], v[136:137] op_sel_hi:[1,0,1] neg_lo:[0,1,0] neg_hi:[0,1,0]
	ds_read_b128 v[58:61], v233 offset:5552
	v_pk_fma_f32 v[138:139], v[62:63], v[230:231], v[138:139] op_sel_hi:[1,0,1] neg_lo:[0,1,0] neg_hi:[0,1,0]
	v_pk_fma_f32 v[140:141], v[64:65], v[230:231], v[140:141] op_sel_hi:[1,0,1] neg_lo:[0,1,0] neg_hi:[0,1,0]
	ds_read_b128 v[62:65], v233 offset:5568
	s_waitcnt lgkmcnt(9)
	v_pk_fma_f32 v[142:143], v[66:67], v[230:231], v[142:143] op_sel_hi:[1,0,1] neg_lo:[0,1,0] neg_hi:[0,1,0]
	v_pk_fma_f32 v[144:145], v[68:69], v[230:231], v[144:145] op_sel_hi:[1,0,1] neg_lo:[0,1,0] neg_hi:[0,1,0]
	ds_read_b128 v[66:69], v233 offset:5584
	v_pk_fma_f32 v[146:147], v[70:71], v[230:231], v[146:147] op_sel_hi:[1,0,1] neg_lo:[0,1,0] neg_hi:[0,1,0]
	v_pk_fma_f32 v[148:149], v[72:73], v[230:231], v[148:149] op_sel_hi:[1,0,1] neg_lo:[0,1,0] neg_hi:[0,1,0]
	ds_read_b128 v[70:73], v233 offset:5600
	s_waitcnt lgkmcnt(9)
	v_pk_fma_f32 v[150:151], v[194:195], v[230:231], v[150:151] op_sel_hi:[1,0,1] neg_lo:[0,1,0] neg_hi:[0,1,0]
	v_pk_fma_f32 v[152:153], v[196:197], v[230:231], v[152:153] op_sel_hi:[1,0,1] neg_lo:[0,1,0] neg_hi:[0,1,0]
	ds_read_b128 v[194:197], v233 offset:5616
	v_pk_fma_f32 v[154:155], v[198:199], v[230:231], v[154:155] op_sel_hi:[1,0,1] neg_lo:[0,1,0] neg_hi:[0,1,0]
	v_pk_fma_f32 v[180:181], v[200:201], v[230:231], v[180:181] op_sel_hi:[1,0,1] neg_lo:[0,1,0] neg_hi:[0,1,0]
	ds_read_b128 v[198:201], v233 offset:5632
	s_waitcnt lgkmcnt(9)
	v_pk_fma_f32 v[182:183], v[202:203], v[230:231], v[182:183] op_sel_hi:[1,0,1] neg_lo:[0,1,0] neg_hi:[0,1,0]
	v_pk_fma_f32 v[184:185], v[204:205], v[230:231], v[184:185] op_sel_hi:[1,0,1] neg_lo:[0,1,0] neg_hi:[0,1,0]
	ds_read_b128 v[202:205], v233 offset:5648
	v_pk_fma_f32 v[186:187], v[206:207], v[230:231], v[186:187] op_sel_hi:[1,0,1] neg_lo:[0,1,0] neg_hi:[0,1,0]
	v_pk_fma_f32 v[188:189], v[208:209], v[230:231], v[188:189] op_sel_hi:[1,0,1] neg_lo:[0,1,0] neg_hi:[0,1,0]
	ds_read_b128 v[206:209], v233 offset:5664
	s_waitcnt lgkmcnt(10)
	v_pk_fma_f32 v[190:191], v[226:227], v[230:231], v[190:191] op_sel_hi:[1,0,1] neg_lo:[0,1,0] neg_hi:[0,1,0]
	v_pk_fma_f32 v[192:193], v[228:229], v[230:231], v[192:193] op_sel_hi:[1,0,1] neg_lo:[0,1,0] neg_hi:[0,1,0]
	ds_read_b128 v[226:229], v233 offset:5680
	s_nop 0
	v_mov_b32_e32 v230, v126
	v_cvt_pk_bf16_f32 v232, v230, v230
	global_store_short v28, v232, s[0:1]
	s_add_u32 s0, s0, 0x400
	s_addc_u32 s1, s1, 0
	s_waitcnt lgkmcnt(9)
	v_pk_fma_f32 v[126:127], v[50:51], v[230:231], v[126:127] op_sel_hi:[1,0,1] neg_lo:[0,1,0] neg_hi:[0,1,0]
	v_pk_fma_f32 v[128:129], v[52:53], v[230:231], v[128:129] op_sel_hi:[1,0,1] neg_lo:[0,1,0] neg_hi:[0,1,0]
	ds_read_b128 v[50:53], v233 offset:5792
	v_pk_fma_f32 v[130:131], v[54:55], v[230:231], v[130:131] op_sel_hi:[1,0,1] neg_lo:[0,1,0] neg_hi:[0,1,0]
	v_pk_fma_f32 v[132:133], v[56:57], v[230:231], v[132:133] op_sel_hi:[1,0,1] neg_lo:[0,1,0] neg_hi:[0,1,0]
	ds_read_b128 v[54:57], v233 offset:5808
	s_waitcnt lgkmcnt(9)
	v_pk_fma_f32 v[134:135], v[58:59], v[230:231], v[134:135] op_sel_hi:[1,0,1] neg_lo:[0,1,0] neg_hi:[0,1,0]
	v_pk_fma_f32 v[136:137], v[60:61], v[230:231], v[136:137] op_sel_hi:[1,0,1] neg_lo:[0,1,0] neg_hi:[0,1,0]
	ds_read_b128 v[58:61], v233 offset:5824
	v_pk_fma_f32 v[138:139], v[62:63], v[230:231], v[138:139] op_sel_hi:[1,0,1] neg_lo:[0,1,0] neg_hi:[0,1,0]
	v_pk_fma_f32 v[140:141], v[64:65], v[230:231], v[140:141] op_sel_hi:[1,0,1] neg_lo:[0,1,0] neg_hi:[0,1,0]
	ds_read_b128 v[62:65], v233 offset:5840
	s_waitcnt lgkmcnt(9)
	v_pk_fma_f32 v[142:143], v[66:67], v[230:231], v[142:143] op_sel_hi:[1,0,1] neg_lo:[0,1,0] neg_hi:[0,1,0]
	v_pk_fma_f32 v[144:145], v[68:69], v[230:231], v[144:145] op_sel_hi:[1,0,1] neg_lo:[0,1,0] neg_hi:[0,1,0]
	ds_read_b128 v[66:69], v233 offset:5856
	v_pk_fma_f32 v[146:147], v[70:71], v[230:231], v[146:147] op_sel_hi:[1,0,1] neg_lo:[0,1,0] neg_hi:[0,1,0]
	v_pk_fma_f32 v[148:149], v[72:73], v[230:231], v[148:149] op_sel_hi:[1,0,1] neg_lo:[0,1,0] neg_hi:[0,1,0]
	ds_read_b128 v[70:73], v233 offset:5872
	s_waitcnt lgkmcnt(9)
	v_pk_fma_f32 v[150:151], v[194:195], v[230:231], v[150:151] op_sel_hi:[1,0,1] neg_lo:[0,1,0] neg_hi:[0,1,0]
	v_pk_fma_f32 v[152:153], v[196:197], v[230:231], v[152:153] op_sel_hi:[1,0,1] neg_lo:[0,1,0] neg_hi:[0,1,0]
	ds_read_b128 v[194:197], v233 offset:5888
	v_pk_fma_f32 v[154:155], v[198:199], v[230:231], v[154:155] op_sel_hi:[1,0,1] neg_lo:[0,1,0] neg_hi:[0,1,0]
	v_pk_fma_f32 v[180:181], v[200:201], v[230:231], v[180:181] op_sel_hi:[1,0,1] neg_lo:[0,1,0] neg_hi:[0,1,0]
	ds_read_b128 v[198:201], v233 offset:5904
	s_waitcnt lgkmcnt(9)
	v_pk_fma_f32 v[182:183], v[202:203], v[230:231], v[182:183] op_sel_hi:[1,0,1] neg_lo:[0,1,0] neg_hi:[0,1,0]
	v_pk_fma_f32 v[184:185], v[204:205], v[230:231], v[184:185] op_sel_hi:[1,0,1] neg_lo:[0,1,0] neg_hi:[0,1,0]
	ds_read_b128 v[202:205], v233 offset:5920
	v_pk_fma_f32 v[186:187], v[206:207], v[230:231], v[186:187] op_sel_hi:[1,0,1] neg_lo:[0,1,0] neg_hi:[0,1,0]
	v_pk_fma_f32 v[188:189], v[208:209], v[230:231], v[188:189] op_sel_hi:[1,0,1] neg_lo:[0,1,0] neg_hi:[0,1,0]
	ds_read_b128 v[206:209], v233 offset:5936
	s_waitcnt lgkmcnt(10)
	v_pk_fma_f32 v[190:191], v[226:227], v[230:231], v[190:191] op_sel_hi:[1,0,1] neg_lo:[0,1,0] neg_hi:[0,1,0]
	v_pk_fma_f32 v[192:193], v[228:229], v[230:231], v[192:193] op_sel_hi:[1,0,1] neg_lo:[0,1,0] neg_hi:[0,1,0]
	ds_read_b128 v[226:229], v233 offset:5952
	s_nop 0
	v_mov_b32_e32 v230, v127
	v_cvt_pk_bf16_f32 v232, v230, v230
	global_store_short v28, v232, s[0:1]
	s_add_u32 s0, s0, 0x400
	s_addc_u32 s1, s1, 0
	s_waitcnt lgkmcnt(9)
	v_pk_fma_f32 v[128:129], v[52:53], v[230:231], v[128:129] op_sel_hi:[1,0,1] neg_lo:[0,1,0] neg_hi:[0,1,0]
	ds_read_b128 v[50:53], v233 offset:6064
	v_pk_fma_f32 v[130:131], v[54:55], v[230:231], v[130:131] op_sel_hi:[1,0,1] neg_lo:[0,1,0] neg_hi:[0,1,0]
	v_pk_fma_f32 v[132:133], v[56:57], v[230:231], v[132:133] op_sel_hi:[1,0,1] neg_lo:[0,1,0] neg_hi:[0,1,0]
	ds_read_b128 v[54:57], v233 offset:6080
	s_waitcnt lgkmcnt(9)
	v_pk_fma_f32 v[134:135], v[58:59], v[230:231], v[134:135] op_sel_hi:[1,0,1] neg_lo:[0,1,0] neg_hi:[0,1,0]
	v_pk_fma_f32 v[136:137], v[60:61], v[230:231], v[136:137] op_sel_hi:[1,0,1] neg_lo:[0,1,0] neg_hi:[0,1,0]
	ds_read_b128 v[58:61], v233 offset:6096
	v_pk_fma_f32 v[138:139], v[62:63], v[230:231], v[138:139] op_sel_hi:[1,0,1] neg_lo:[0,1,0] neg_hi:[0,1,0]
	v_pk_fma_f32 v[140:141], v[64:65], v[230:231], v[140:141] op_sel_hi:[1,0,1] neg_lo:[0,1,0] neg_hi:[0,1,0]
	ds_read_b128 v[62:65], v233 offset:6112
	s_waitcnt lgkmcnt(9)
	v_pk_fma_f32 v[142:143], v[66:67], v[230:231], v[142:143] op_sel_hi:[1,0,1] neg_lo:[0,1,0] neg_hi:[0,1,0]
	v_pk_fma_f32 v[144:145], v[68:69], v[230:231], v[144:145] op_sel_hi:[1,0,1] neg_lo:[0,1,0] neg_hi:[0,1,0]
	ds_read_b128 v[66:69], v233 offset:6128
	v_pk_fma_f32 v[146:147], v[70:71], v[230:231], v[146:147] op_sel_hi:[1,0,1] neg_lo:[0,1,0] neg_hi:[0,1,0]
	v_pk_fma_f32 v[148:149], v[72:73], v[230:231], v[148:149] op_sel_hi:[1,0,1] neg_lo:[0,1,0] neg_hi:[0,1,0]
	ds_read_b128 v[70:73], v233 offset:6144
	s_waitcnt lgkmcnt(9)
	v_pk_fma_f32 v[150:151], v[194:195], v[230:231], v[150:151] op_sel_hi:[1,0,1] neg_lo:[0,1,0] neg_hi:[0,1,0]
	v_pk_fma_f32 v[152:153], v[196:197], v[230:231], v[152:153] op_sel_hi:[1,0,1] neg_lo:[0,1,0] neg_hi:[0,1,0]
	ds_read_b128 v[194:197], v233 offset:6160
	v_pk_fma_f32 v[154:155], v[198:199], v[230:231], v[154:155] op_sel_hi:[1,0,1] neg_lo:[0,1,0] neg_hi:[0,1,0]
	v_pk_fma_f32 v[180:181], v[200:201], v[230:231], v[180:181] op_sel_hi:[1,0,1] neg_lo:[0,1,0] neg_hi:[0,1,0]
	ds_read_b128 v[198:201], v233 offset:6176
	s_waitcnt lgkmcnt(9)
	v_pk_fma_f32 v[182:183], v[202:203], v[230:231], v[182:183] op_sel_hi:[1,0,1] neg_lo:[0,1,0] neg_hi:[0,1,0]
	v_pk_fma_f32 v[184:185], v[204:205], v[230:231], v[184:185] op_sel_hi:[1,0,1] neg_lo:[0,1,0] neg_hi:[0,1,0]
	ds_read_b128 v[202:205], v233 offset:6192
	v_pk_fma_f32 v[186:187], v[206:207], v[230:231], v[186:187] op_sel_hi:[1,0,1] neg_lo:[0,1,0] neg_hi:[0,1,0]
	v_pk_fma_f32 v[188:189], v[208:209], v[230:231], v[188:189] op_sel_hi:[1,0,1] neg_lo:[0,1,0] neg_hi:[0,1,0]
	ds_read_b128 v[206:209], v233 offset:6208
	s_waitcnt lgkmcnt(10)
	v_pk_fma_f32 v[190:191], v[226:227], v[230:231], v[190:191] op_sel_hi:[1,0,1] neg_lo:[0,1,0] neg_hi:[0,1,0]
	v_pk_fma_f32 v[192:193], v[228:229], v[230:231], v[192:193] op_sel_hi:[1,0,1] neg_lo:[0,1,0] neg_hi:[0,1,0]
	ds_read_b128 v[226:229], v233 offset:6224
	s_nop 0
	v_mov_b32_e32 v230, v128
	v_cvt_pk_bf16_f32 v232, v230, v230
	global_store_short v28, v232, s[0:1]
	s_add_u32 s0, s0, 0x400
	s_addc_u32 s1, s1, 0
	s_waitcnt lgkmcnt(9)
	v_pk_fma_f32 v[128:129], v[52:53], v[230:231], v[128:129] op_sel_hi:[1,0,1] neg_lo:[0,1,0] neg_hi:[0,1,0]
	v_pk_fma_f32 v[130:131], v[54:55], v[230:231], v[130:131] op_sel_hi:[1,0,1] neg_lo:[0,1,0] neg_hi:[0,1,0]
	v_pk_fma_f32 v[132:133], v[56:57], v[230:231], v[132:133] op_sel_hi:[1,0,1] neg_lo:[0,1,0] neg_hi:[0,1,0]
	ds_read_b128 v[54:57], v233 offset:6352
	s_waitcnt lgkmcnt(8)
	v_pk_fma_f32 v[134:135], v[58:59], v[230:231], v[134:135] op_sel_hi:[1,0,1] neg_lo:[0,1,0] neg_hi:[0,1,0]
	v_pk_fma_f32 v[136:137], v[60:61], v[230:231], v[136:137] op_sel_hi:[1,0,1] neg_lo:[0,1,0] neg_hi:[0,1,0]
	ds_read_b128 v[58:61], v233 offset:6368
	v_pk_fma_f32 v[138:139], v[62:63], v[230:231], v[138:139] op_sel_hi:[1,0,1] neg_lo:[0,1,0] neg_hi:[0,1,0]
	v_pk_fma_f32 v[140:141], v[64:65], v[230:231], v[140:141] op_sel_hi:[1,0,1] neg_lo:[0,1,0] neg_hi:[0,1,0]
	ds_read_b128 v[62:65], v233 offset:6384
	s_waitcnt lgkmcnt(8)
	v_pk_fma_f32 v[142:143], v[66:67], v[230:231], v[142:143] op_sel_hi:[1,0,1] neg_lo:[0,1,0] neg_hi:[0,1,0]
	v_pk_fma_f32 v[144:145], v[68:69], v[230:231], v[144:145] op_sel_hi:[1,0,1] neg_lo:[0,1,0] neg_hi:[0,1,0]
	ds_read_b128 v[66:69], v233 offset:6400
	v_pk_fma_f32 v[146:147], v[70:71], v[230:231], v[146:147] op_sel_hi:[1,0,1] neg_lo:[0,1,0] neg_hi:[0,1,0]
	v_pk_fma_f32 v[148:149], v[72:73], v[230:231], v[148:149] op_sel_hi:[1,0,1] neg_lo:[0,1,0] neg_hi:[0,1,0]
	ds_read_b128 v[70:73], v233 offset:6416
	s_waitcnt lgkmcnt(8)
	v_pk_fma_f32 v[150:151], v[194:195], v[230:231], v[150:151] op_sel_hi:[1,0,1] neg_lo:[0,1,0] neg_hi:[0,1,0]
	v_pk_fma_f32 v[152:153], v[196:197], v[230:231], v[152:153] op_sel_hi:[1,0,1] neg_lo:[0,1,0] neg_hi:[0,1,0]
	ds_read_b128 v[194:197], v233 offset:6432
	v_pk_fma_f32 v[154:155], v[198:199], v[230:231], v[154:155] op_sel_hi:[1,0,1] neg_lo:[0,1,0] neg_hi:[0,1,0]
	v_pk_fma_f32 v[180:181], v[200:201], v[230:231], v[180:181] op_sel_hi:[1,0,1] neg_lo:[0,1,0] neg_hi:[0,1,0]
	ds_read_b128 v[198:201], v233 offset:6448
	s_waitcnt lgkmcnt(8)
	v_pk_fma_f32 v[182:183], v[202:203], v[230:231], v[182:183] op_sel_hi:[1,0,1] neg_lo:[0,1,0] neg_hi:[0,1,0]
	v_pk_fma_f32 v[184:185], v[204:205], v[230:231], v[184:185] op_sel_hi:[1,0,1] neg_lo:[0,1,0] neg_hi:[0,1,0]
	ds_read_b128 v[202:205], v233 offset:6464
	v_pk_fma_f32 v[186:187], v[206:207], v[230:231], v[186:187] op_sel_hi:[1,0,1] neg_lo:[0,1,0] neg_hi:[0,1,0]
	v_pk_fma_f32 v[188:189], v[208:209], v[230:231], v[188:189] op_sel_hi:[1,0,1] neg_lo:[0,1,0] neg_hi:[0,1,0]
	ds_read_b128 v[206:209], v233 offset:6480
	s_waitcnt lgkmcnt(9)
	v_pk_fma_f32 v[190:191], v[226:227], v[230:231], v[190:191] op_sel_hi:[1,0,1] neg_lo:[0,1,0] neg_hi:[0,1,0]
	v_pk_fma_f32 v[192:193], v[228:229], v[230:231], v[192:193] op_sel_hi:[1,0,1] neg_lo:[0,1,0] neg_hi:[0,1,0]
	ds_read_b128 v[226:229], v233 offset:6496
	s_nop 0
	v_mov_b32_e32 v230, v129
	v_cvt_pk_bf16_f32 v232, v230, v230
	global_store_short v28, v232, s[0:1]
	s_add_u32 s0, s0, 0x400
	s_addc_u32 s1, s1, 0
	s_waitcnt lgkmcnt(8)
	v_pk_fma_f32 v[130:131], v[54:55], v[230:231], v[130:131] op_sel_hi:[1,0,1] neg_lo:[0,1,0] neg_hi:[0,1,0]
	v_pk_fma_f32 v[132:133], v[56:57], v[230:231], v[132:133] op_sel_hi:[1,0,1] neg_lo:[0,1,0] neg_hi:[0,1,0]
	ds_read_b128 v[54:57], v233 offset:6624
	v_pk_fma_f32 v[134:135], v[58:59], v[230:231], v[134:135] op_sel_hi:[1,0,1] neg_lo:[0,1,0] neg_hi:[0,1,0]
	v_pk_fma_f32 v[136:137], v[60:61], v[230:231], v[136:137] op_sel_hi:[1,0,1] neg_lo:[0,1,0] neg_hi:[0,1,0]
	ds_read_b128 v[58:61], v233 offset:6640
	s_waitcnt lgkmcnt(8)
	v_pk_fma_f32 v[138:139], v[62:63], v[230:231], v[138:139] op_sel_hi:[1,0,1] neg_lo:[0,1,0] neg_hi:[0,1,0]
	v_pk_fma_f32 v[140:141], v[64:65], v[230:231], v[140:141] op_sel_hi:[1,0,1] neg_lo:[0,1,0] neg_hi:[0,1,0]
	ds_read_b128 v[62:65], v233 offset:6656
	v_pk_fma_f32 v[142:143], v[66:67], v[230:231], v[142:143] op_sel_hi:[1,0,1] neg_lo:[0,1,0] neg_hi:[0,1,0]
	v_pk_fma_f32 v[144:145], v[68:69], v[230:231], v[144:145] op_sel_hi:[1,0,1] neg_lo:[0,1,0] neg_hi:[0,1,0]
	ds_read_b128 v[66:69], v233 offset:6672
	s_waitcnt lgkmcnt(8)
	v_pk_fma_f32 v[146:147], v[70:71], v[230:231], v[146:147] op_sel_hi:[1,0,1] neg_lo:[0,1,0] neg_hi:[0,1,0]
	v_pk_fma_f32 v[148:149], v[72:73], v[230:231], v[148:149] op_sel_hi:[1,0,1] neg_lo:[0,1,0] neg_hi:[0,1,0]
	ds_read_b128 v[70:73], v233 offset:6688
	v_pk_fma_f32 v[150:151], v[194:195], v[230:231], v[150:151] op_sel_hi:[1,0,1] neg_lo:[0,1,0] neg_hi:[0,1,0]
	v_pk_fma_f32 v[152:153], v[196:197], v[230:231], v[152:153] op_sel_hi:[1,0,1] neg_lo:[0,1,0] neg_hi:[0,1,0]
	ds_read_b128 v[194:197], v233 offset:6704
	s_waitcnt lgkmcnt(8)
	v_pk_fma_f32 v[154:155], v[198:199], v[230:231], v[154:155] op_sel_hi:[1,0,1] neg_lo:[0,1,0] neg_hi:[0,1,0]
	v_pk_fma_f32 v[180:181], v[200:201], v[230:231], v[180:181] op_sel_hi:[1,0,1] neg_lo:[0,1,0] neg_hi:[0,1,0]
	ds_read_b128 v[198:201], v233 offset:6720
	v_pk_fma_f32 v[182:183], v[202:203], v[230:231], v[182:183] op_sel_hi:[1,0,1] neg_lo:[0,1,0] neg_hi:[0,1,0]
	v_pk_fma_f32 v[184:185], v[204:205], v[230:231], v[184:185] op_sel_hi:[1,0,1] neg_lo:[0,1,0] neg_hi:[0,1,0]
	ds_read_b128 v[202:205], v233 offset:6736
	s_waitcnt lgkmcnt(8)
	v_pk_fma_f32 v[186:187], v[206:207], v[230:231], v[186:187] op_sel_hi:[1,0,1] neg_lo:[0,1,0] neg_hi:[0,1,0]
	v_pk_fma_f32 v[188:189], v[208:209], v[230:231], v[188:189] op_sel_hi:[1,0,1] neg_lo:[0,1,0] neg_hi:[0,1,0]
	ds_read_b128 v[206:209], v233 offset:6752
	v_pk_fma_f32 v[190:191], v[226:227], v[230:231], v[190:191] op_sel_hi:[1,0,1] neg_lo:[0,1,0] neg_hi:[0,1,0]
	v_pk_fma_f32 v[192:193], v[228:229], v[230:231], v[192:193] op_sel_hi:[1,0,1] neg_lo:[0,1,0] neg_hi:[0,1,0]
	ds_read_b128 v[226:229], v233 offset:6768
	s_nop 0
	v_mov_b32_e32 v230, v130
	v_cvt_pk_bf16_f32 v232, v230, v230
	global_store_short v28, v232, s[0:1]
	s_add_u32 s0, s0, 0x400
	s_addc_u32 s1, s1, 0
	s_waitcnt lgkmcnt(8)
	v_pk_fma_f32 v[130:131], v[54:55], v[230:231], v[130:131] op_sel_hi:[1,0,1] neg_lo:[0,1,0] neg_hi:[0,1,0]
	v_pk_fma_f32 v[132:133], v[56:57], v[230:231], v[132:133] op_sel_hi:[1,0,1] neg_lo:[0,1,0] neg_hi:[0,1,0]
	ds_read_b128 v[54:57], v233 offset:6896
	v_pk_fma_f32 v[134:135], v[58:59], v[230:231], v[134:135] op_sel_hi:[1,0,1] neg_lo:[0,1,0] neg_hi:[0,1,0]
	v_pk_fma_f32 v[136:137], v[60:61], v[230:231], v[136:137] op_sel_hi:[1,0,1] neg_lo:[0,1,0] neg_hi:[0,1,0]
	ds_read_b128 v[58:61], v233 offset:6912
	s_waitcnt lgkmcnt(8)
	v_pk_fma_f32 v[138:139], v[62:63], v[230:231], v[138:139] op_sel_hi:[1,0,1] neg_lo:[0,1,0] neg_hi:[0,1,0]
	v_pk_fma_f32 v[140:141], v[64:65], v[230:231], v[140:141] op_sel_hi:[1,0,1] neg_lo:[0,1,0] neg_hi:[0,1,0]
	ds_read_b128 v[62:65], v233 offset:6928
	v_pk_fma_f32 v[142:143], v[66:67], v[230:231], v[142:143] op_sel_hi:[1,0,1] neg_lo:[0,1,0] neg_hi:[0,1,0]
	v_pk_fma_f32 v[144:145], v[68:69], v[230:231], v[144:145] op_sel_hi:[1,0,1] neg_lo:[0,1,0] neg_hi:[0,1,0]
	ds_read_b128 v[66:69], v233 offset:6944
	s_waitcnt lgkmcnt(8)
	v_pk_fma_f32 v[146:147], v[70:71], v[230:231], v[146:147] op_sel_hi:[1,0,1] neg_lo:[0,1,0] neg_hi:[0,1,0]
	v_pk_fma_f32 v[148:149], v[72:73], v[230:231], v[148:149] op_sel_hi:[1,0,1] neg_lo:[0,1,0] neg_hi:[0,1,0]
	ds_read_b128 v[70:73], v233 offset:6960
	v_pk_fma_f32 v[150:151], v[194:195], v[230:231], v[150:151] op_sel_hi:[1,0,1] neg_lo:[0,1,0] neg_hi:[0,1,0]
	v_pk_fma_f32 v[152:153], v[196:197], v[230:231], v[152:153] op_sel_hi:[1,0,1] neg_lo:[0,1,0] neg_hi:[0,1,0]
	ds_read_b128 v[194:197], v233 offset:6976
	s_waitcnt lgkmcnt(8)
	v_pk_fma_f32 v[154:155], v[198:199], v[230:231], v[154:155] op_sel_hi:[1,0,1] neg_lo:[0,1,0] neg_hi:[0,1,0]
	v_pk_fma_f32 v[180:181], v[200:201], v[230:231], v[180:181] op_sel_hi:[1,0,1] neg_lo:[0,1,0] neg_hi:[0,1,0]
	ds_read_b128 v[198:201], v233 offset:6992
	v_pk_fma_f32 v[182:183], v[202:203], v[230:231], v[182:183] op_sel_hi:[1,0,1] neg_lo:[0,1,0] neg_hi:[0,1,0]
	v_pk_fma_f32 v[184:185], v[204:205], v[230:231], v[184:185] op_sel_hi:[1,0,1] neg_lo:[0,1,0] neg_hi:[0,1,0]
	ds_read_b128 v[202:205], v233 offset:7008
	s_waitcnt lgkmcnt(8)
	v_pk_fma_f32 v[186:187], v[206:207], v[230:231], v[186:187] op_sel_hi:[1,0,1] neg_lo:[0,1,0] neg_hi:[0,1,0]
	v_pk_fma_f32 v[188:189], v[208:209], v[230:231], v[188:189] op_sel_hi:[1,0,1] neg_lo:[0,1,0] neg_hi:[0,1,0]
	ds_read_b128 v[206:209], v233 offset:7024
	v_pk_fma_f32 v[190:191], v[226:227], v[230:231], v[190:191] op_sel_hi:[1,0,1] neg_lo:[0,1,0] neg_hi:[0,1,0]
	v_pk_fma_f32 v[192:193], v[228:229], v[230:231], v[192:193] op_sel_hi:[1,0,1] neg_lo:[0,1,0] neg_hi:[0,1,0]
	ds_read_b128 v[226:229], v233 offset:7040
	s_nop 0
	v_mov_b32_e32 v230, v131
	v_cvt_pk_bf16_f32 v232, v230, v230
	global_store_short v28, v232, s[0:1]
	s_add_u32 s0, s0, 0x400
	s_addc_u32 s1, s1, 0
	s_waitcnt lgkmcnt(8)
	v_pk_fma_f32 v[132:133], v[56:57], v[230:231], v[132:133] op_sel_hi:[1,0,1] neg_lo:[0,1,0] neg_hi:[0,1,0]
	ds_read_b128 v[54:57], v233 offset:7168
	v_pk_fma_f32 v[134:135], v[58:59], v[230:231], v[134:135] op_sel_hi:[1,0,1] neg_lo:[0,1,0] neg_hi:[0,1,0]
	v_pk_fma_f32 v[136:137], v[60:61], v[230:231], v[136:137] op_sel_hi:[1,0,1] neg_lo:[0,1,0] neg_hi:[0,1,0]
	ds_read_b128 v[58:61], v233 offset:7184
	s_waitcnt lgkmcnt(8)
	v_pk_fma_f32 v[138:139], v[62:63], v[230:231], v[138:139] op_sel_hi:[1,0,1] neg_lo:[0,1,0] neg_hi:[0,1,0]
	v_pk_fma_f32 v[140:141], v[64:65], v[230:231], v[140:141] op_sel_hi:[1,0,1] neg_lo:[0,1,0] neg_hi:[0,1,0]
	ds_read_b128 v[62:65], v233 offset:7200
	v_pk_fma_f32 v[142:143], v[66:67], v[230:231], v[142:143] op_sel_hi:[1,0,1] neg_lo:[0,1,0] neg_hi:[0,1,0]
	v_pk_fma_f32 v[144:145], v[68:69], v[230:231], v[144:145] op_sel_hi:[1,0,1] neg_lo:[0,1,0] neg_hi:[0,1,0]
	ds_read_b128 v[66:69], v233 offset:7216
	s_waitcnt lgkmcnt(8)
	v_pk_fma_f32 v[146:147], v[70:71], v[230:231], v[146:147] op_sel_hi:[1,0,1] neg_lo:[0,1,0] neg_hi:[0,1,0]
	v_pk_fma_f32 v[148:149], v[72:73], v[230:231], v[148:149] op_sel_hi:[1,0,1] neg_lo:[0,1,0] neg_hi:[0,1,0]
	ds_read_b128 v[70:73], v233 offset:7232
	v_pk_fma_f32 v[150:151], v[194:195], v[230:231], v[150:151] op_sel_hi:[1,0,1] neg_lo:[0,1,0] neg_hi:[0,1,0]
	v_pk_fma_f32 v[152:153], v[196:197], v[230:231], v[152:153] op_sel_hi:[1,0,1] neg_lo:[0,1,0] neg_hi:[0,1,0]
	ds_read_b128 v[194:197], v233 offset:7248
	s_waitcnt lgkmcnt(8)
	v_pk_fma_f32 v[154:155], v[198:199], v[230:231], v[154:155] op_sel_hi:[1,0,1] neg_lo:[0,1,0] neg_hi:[0,1,0]
	v_pk_fma_f32 v[180:181], v[200:201], v[230:231], v[180:181] op_sel_hi:[1,0,1] neg_lo:[0,1,0] neg_hi:[0,1,0]
	ds_read_b128 v[198:201], v233 offset:7264
	v_pk_fma_f32 v[182:183], v[202:203], v[230:231], v[182:183] op_sel_hi:[1,0,1] neg_lo:[0,1,0] neg_hi:[0,1,0]
	v_pk_fma_f32 v[184:185], v[204:205], v[230:231], v[184:185] op_sel_hi:[1,0,1] neg_lo:[0,1,0] neg_hi:[0,1,0]
	ds_read_b128 v[202:205], v233 offset:7280
	s_waitcnt lgkmcnt(8)
	v_pk_fma_f32 v[186:187], v[206:207], v[230:231], v[186:187] op_sel_hi:[1,0,1] neg_lo:[0,1,0] neg_hi:[0,1,0]
	v_pk_fma_f32 v[188:189], v[208:209], v[230:231], v[188:189] op_sel_hi:[1,0,1] neg_lo:[0,1,0] neg_hi:[0,1,0]
	ds_read_b128 v[206:209], v233 offset:7296
	v_pk_fma_f32 v[190:191], v[226:227], v[230:231], v[190:191] op_sel_hi:[1,0,1] neg_lo:[0,1,0] neg_hi:[0,1,0]
	v_pk_fma_f32 v[192:193], v[228:229], v[230:231], v[192:193] op_sel_hi:[1,0,1] neg_lo:[0,1,0] neg_hi:[0,1,0]
	ds_read_b128 v[226:229], v233 offset:7312
	s_nop 0
	v_mov_b32_e32 v230, v132
	v_cvt_pk_bf16_f32 v232, v230, v230
	global_store_short v28, v232, s[0:1]
	s_add_u32 s0, s0, 0x400
	s_addc_u32 s1, s1, 0
	s_waitcnt lgkmcnt(8)
	v_pk_fma_f32 v[132:133], v[56:57], v[230:231], v[132:133] op_sel_hi:[1,0,1] neg_lo:[0,1,0] neg_hi:[0,1,0]
	v_pk_fma_f32 v[134:135], v[58:59], v[230:231], v[134:135] op_sel_hi:[1,0,1] neg_lo:[0,1,0] neg_hi:[0,1,0]
	v_pk_fma_f32 v[136:137], v[60:61], v[230:231], v[136:137] op_sel_hi:[1,0,1] neg_lo:[0,1,0] neg_hi:[0,1,0]
	ds_read_b128 v[58:61], v233 offset:7456
	s_waitcnt lgkmcnt(7)
	v_pk_fma_f32 v[138:139], v[62:63], v[230:231], v[138:139] op_sel_hi:[1,0,1] neg_lo:[0,1,0] neg_hi:[0,1,0]
	v_pk_fma_f32 v[140:141], v[64:65], v[230:231], v[140:141] op_sel_hi:[1,0,1] neg_lo:[0,1,0] neg_hi:[0,1,0]
	ds_read_b128 v[62:65], v233 offset:7472
	v_pk_fma_f32 v[142:143], v[66:67], v[230:231], v[142:143] op_sel_hi:[1,0,1] neg_lo:[0,1,0] neg_hi:[0,1,0]
	v_pk_fma_f32 v[144:145], v[68:69], v[230:231], v[144:145] op_sel_hi:[1,0,1] neg_lo:[0,1,0] neg_hi:[0,1,0]
	ds_read_b128 v[66:69], v233 offset:7488
	s_waitcnt lgkmcnt(7)
	v_pk_fma_f32 v[146:147], v[70:71], v[230:231], v[146:147] op_sel_hi:[1,0,1] neg_lo:[0,1,0] neg_hi:[0,1,0]
	v_pk_fma_f32 v[148:149], v[72:73], v[230:231], v[148:149] op_sel_hi:[1,0,1] neg_lo:[0,1,0] neg_hi:[0,1,0]
	ds_read_b128 v[70:73], v233 offset:7504
	v_pk_fma_f32 v[150:151], v[194:195], v[230:231], v[150:151] op_sel_hi:[1,0,1] neg_lo:[0,1,0] neg_hi:[0,1,0]
	v_pk_fma_f32 v[152:153], v[196:197], v[230:231], v[152:153] op_sel_hi:[1,0,1] neg_lo:[0,1,0] neg_hi:[0,1,0]
	ds_read_b128 v[194:197], v233 offset:7520
	s_waitcnt lgkmcnt(7)
	v_pk_fma_f32 v[154:155], v[198:199], v[230:231], v[154:155] op_sel_hi:[1,0,1] neg_lo:[0,1,0] neg_hi:[0,1,0]
	v_pk_fma_f32 v[180:181], v[200:201], v[230:231], v[180:181] op_sel_hi:[1,0,1] neg_lo:[0,1,0] neg_hi:[0,1,0]
	ds_read_b128 v[198:201], v233 offset:7536
	v_pk_fma_f32 v[182:183], v[202:203], v[230:231], v[182:183] op_sel_hi:[1,0,1] neg_lo:[0,1,0] neg_hi:[0,1,0]
	v_pk_fma_f32 v[184:185], v[204:205], v[230:231], v[184:185] op_sel_hi:[1,0,1] neg_lo:[0,1,0] neg_hi:[0,1,0]
	ds_read_b128 v[202:205], v233 offset:7552
	s_waitcnt lgkmcnt(7)
	v_pk_fma_f32 v[186:187], v[206:207], v[230:231], v[186:187] op_sel_hi:[1,0,1] neg_lo:[0,1,0] neg_hi:[0,1,0]
	v_pk_fma_f32 v[188:189], v[208:209], v[230:231], v[188:189] op_sel_hi:[1,0,1] neg_lo:[0,1,0] neg_hi:[0,1,0]
	ds_read_b128 v[206:209], v233 offset:7568
	v_pk_fma_f32 v[190:191], v[226:227], v[230:231], v[190:191] op_sel_hi:[1,0,1] neg_lo:[0,1,0] neg_hi:[0,1,0]
	v_pk_fma_f32 v[192:193], v[228:229], v[230:231], v[192:193] op_sel_hi:[1,0,1] neg_lo:[0,1,0] neg_hi:[0,1,0]
	ds_read_b128 v[226:229], v233 offset:7584
	s_nop 0
	v_mov_b32_e32 v230, v133
	v_cvt_pk_bf16_f32 v232, v230, v230
	global_store_short v28, v232, s[0:1]
	s_add_u32 s0, s0, 0x400
	s_addc_u32 s1, s1, 0
	s_waitcnt lgkmcnt(7)
	v_pk_fma_f32 v[134:135], v[58:59], v[230:231], v[134:135] op_sel_hi:[1,0,1] neg_lo:[0,1,0] neg_hi:[0,1,0]
	v_pk_fma_f32 v[136:137], v[60:61], v[230:231], v[136:137] op_sel_hi:[1,0,1] neg_lo:[0,1,0] neg_hi:[0,1,0]
	ds_read_b128 v[58:61], v233 offset:7728
	v_pk_fma_f32 v[138:139], v[62:63], v[230:231], v[138:139] op_sel_hi:[1,0,1] neg_lo:[0,1,0] neg_hi:[0,1,0]
	v_pk_fma_f32 v[140:141], v[64:65], v[230:231], v[140:141] op_sel_hi:[1,0,1] neg_lo:[0,1,0] neg_hi:[0,1,0]
	ds_read_b128 v[62:65], v233 offset:7744
	s_waitcnt lgkmcnt(7)
	v_pk_fma_f32 v[142:143], v[66:67], v[230:231], v[142:143] op_sel_hi:[1,0,1] neg_lo:[0,1,0] neg_hi:[0,1,0]
	v_pk_fma_f32 v[144:145], v[68:69], v[230:231], v[144:145] op_sel_hi:[1,0,1] neg_lo:[0,1,0] neg_hi:[0,1,0]
	ds_read_b128 v[66:69], v233 offset:7760
	v_pk_fma_f32 v[146:147], v[70:71], v[230:231], v[146:147] op_sel_hi:[1,0,1] neg_lo:[0,1,0] neg_hi:[0,1,0]
	v_pk_fma_f32 v[148:149], v[72:73], v[230:231], v[148:149] op_sel_hi:[1,0,1] neg_lo:[0,1,0] neg_hi:[0,1,0]
	ds_read_b128 v[70:73], v233 offset:7776
	s_waitcnt lgkmcnt(7)
	v_pk_fma_f32 v[150:151], v[194:195], v[230:231], v[150:151] op_sel_hi:[1,0,1] neg_lo:[0,1,0] neg_hi:[0,1,0]
	v_pk_fma_f32 v[152:153], v[196:197], v[230:231], v[152:153] op_sel_hi:[1,0,1] neg_lo:[0,1,0] neg_hi:[0,1,0]
	ds_read_b128 v[194:197], v233 offset:7792
	v_pk_fma_f32 v[154:155], v[198:199], v[230:231], v[154:155] op_sel_hi:[1,0,1] neg_lo:[0,1,0] neg_hi:[0,1,0]
	v_pk_fma_f32 v[180:181], v[200:201], v[230:231], v[180:181] op_sel_hi:[1,0,1] neg_lo:[0,1,0] neg_hi:[0,1,0]
	ds_read_b128 v[198:201], v233 offset:7808
	s_waitcnt lgkmcnt(7)
	v_pk_fma_f32 v[182:183], v[202:203], v[230:231], v[182:183] op_sel_hi:[1,0,1] neg_lo:[0,1,0] neg_hi:[0,1,0]
	v_pk_fma_f32 v[184:185], v[204:205], v[230:231], v[184:185] op_sel_hi:[1,0,1] neg_lo:[0,1,0] neg_hi:[0,1,0]
	ds_read_b128 v[202:205], v233 offset:7824
	v_pk_fma_f32 v[186:187], v[206:207], v[230:231], v[186:187] op_sel_hi:[1,0,1] neg_lo:[0,1,0] neg_hi:[0,1,0]
	v_pk_fma_f32 v[188:189], v[208:209], v[230:231], v[188:189] op_sel_hi:[1,0,1] neg_lo:[0,1,0] neg_hi:[0,1,0]
	ds_read_b128 v[206:209], v233 offset:7840
	s_waitcnt lgkmcnt(8)
	v_pk_fma_f32 v[190:191], v[226:227], v[230:231], v[190:191] op_sel_hi:[1,0,1] neg_lo:[0,1,0] neg_hi:[0,1,0]
	v_pk_fma_f32 v[192:193], v[228:229], v[230:231], v[192:193] op_sel_hi:[1,0,1] neg_lo:[0,1,0] neg_hi:[0,1,0]
	ds_read_b128 v[226:229], v233 offset:7856
	s_nop 0
	v_mov_b32_e32 v230, v134
	v_cvt_pk_bf16_f32 v232, v230, v230
	global_store_short v28, v232, s[0:1]
	s_add_u32 s0, s0, 0x400
	s_addc_u32 s1, s1, 0
	s_waitcnt lgkmcnt(7)
	v_pk_fma_f32 v[134:135], v[58:59], v[230:231], v[134:135] op_sel_hi:[1,0,1] neg_lo:[0,1,0] neg_hi:[0,1,0]
	v_pk_fma_f32 v[136:137], v[60:61], v[230:231], v[136:137] op_sel_hi:[1,0,1] neg_lo:[0,1,0] neg_hi:[0,1,0]
	ds_read_b128 v[58:61], v233 offset:8000
	v_pk_fma_f32 v[138:139], v[62:63], v[230:231], v[138:139] op_sel_hi:[1,0,1] neg_lo:[0,1,0] neg_hi:[0,1,0]
	v_pk_fma_f32 v[140:141], v[64:65], v[230:231], v[140:141] op_sel_hi:[1,0,1] neg_lo:[0,1,0] neg_hi:[0,1,0]
	ds_read_b128 v[62:65], v233 offset:8016
	s_waitcnt lgkmcnt(7)
	v_pk_fma_f32 v[142:143], v[66:67], v[230:231], v[142:143] op_sel_hi:[1,0,1] neg_lo:[0,1,0] neg_hi:[0,1,0]
	v_pk_fma_f32 v[144:145], v[68:69], v[230:231], v[144:145] op_sel_hi:[1,0,1] neg_lo:[0,1,0] neg_hi:[0,1,0]
	ds_read_b128 v[66:69], v233 offset:8032
	v_pk_fma_f32 v[146:147], v[70:71], v[230:231], v[146:147] op_sel_hi:[1,0,1] neg_lo:[0,1,0] neg_hi:[0,1,0]
	v_pk_fma_f32 v[148:149], v[72:73], v[230:231], v[148:149] op_sel_hi:[1,0,1] neg_lo:[0,1,0] neg_hi:[0,1,0]
	ds_read_b128 v[70:73], v233 offset:8048
	s_waitcnt lgkmcnt(7)
	v_pk_fma_f32 v[150:151], v[194:195], v[230:231], v[150:151] op_sel_hi:[1,0,1] neg_lo:[0,1,0] neg_hi:[0,1,0]
	v_pk_fma_f32 v[152:153], v[196:197], v[230:231], v[152:153] op_sel_hi:[1,0,1] neg_lo:[0,1,0] neg_hi:[0,1,0]
	ds_read_b128 v[194:197], v233 offset:8064
	v_pk_fma_f32 v[154:155], v[198:199], v[230:231], v[154:155] op_sel_hi:[1,0,1] neg_lo:[0,1,0] neg_hi:[0,1,0]
	v_pk_fma_f32 v[180:181], v[200:201], v[230:231], v[180:181] op_sel_hi:[1,0,1] neg_lo:[0,1,0] neg_hi:[0,1,0]
	ds_read_b128 v[198:201], v233 offset:8080
	s_waitcnt lgkmcnt(7)
	v_pk_fma_f32 v[182:183], v[202:203], v[230:231], v[182:183] op_sel_hi:[1,0,1] neg_lo:[0,1,0] neg_hi:[0,1,0]
	v_pk_fma_f32 v[184:185], v[204:205], v[230:231], v[184:185] op_sel_hi:[1,0,1] neg_lo:[0,1,0] neg_hi:[0,1,0]
	ds_read_b128 v[202:205], v233 offset:8096
	v_pk_fma_f32 v[186:187], v[206:207], v[230:231], v[186:187] op_sel_hi:[1,0,1] neg_lo:[0,1,0] neg_hi:[0,1,0]
	v_pk_fma_f32 v[188:189], v[208:209], v[230:231], v[188:189] op_sel_hi:[1,0,1] neg_lo:[0,1,0] neg_hi:[0,1,0]
	ds_read_b128 v[206:209], v233 offset:8112
	s_waitcnt lgkmcnt(8)
	v_pk_fma_f32 v[190:191], v[226:227], v[230:231], v[190:191] op_sel_hi:[1,0,1] neg_lo:[0,1,0] neg_hi:[0,1,0]
	v_pk_fma_f32 v[192:193], v[228:229], v[230:231], v[192:193] op_sel_hi:[1,0,1] neg_lo:[0,1,0] neg_hi:[0,1,0]
	ds_read_b128 v[226:229], v233 offset:8128
	s_nop 0
	v_mov_b32_e32 v230, v135
	v_cvt_pk_bf16_f32 v232, v230, v230
	global_store_short v28, v232, s[0:1]
	s_add_u32 s0, s0, 0x400
	s_addc_u32 s1, s1, 0
	s_waitcnt lgkmcnt(7)
	v_pk_fma_f32 v[136:137], v[60:61], v[230:231], v[136:137] op_sel_hi:[1,0,1] neg_lo:[0,1,0] neg_hi:[0,1,0]
	ds_read_b128 v[58:61], v233 offset:8272
	v_pk_fma_f32 v[138:139], v[62:63], v[230:231], v[138:139] op_sel_hi:[1,0,1] neg_lo:[0,1,0] neg_hi:[0,1,0]
	v_pk_fma_f32 v[140:141], v[64:65], v[230:231], v[140:141] op_sel_hi:[1,0,1] neg_lo:[0,1,0] neg_hi:[0,1,0]
	ds_read_b128 v[62:65], v233 offset:8288
	s_waitcnt lgkmcnt(7)
	v_pk_fma_f32 v[142:143], v[66:67], v[230:231], v[142:143] op_sel_hi:[1,0,1] neg_lo:[0,1,0] neg_hi:[0,1,0]
	v_pk_fma_f32 v[144:145], v[68:69], v[230:231], v[144:145] op_sel_hi:[1,0,1] neg_lo:[0,1,0] neg_hi:[0,1,0]
	ds_read_b128 v[66:69], v233 offset:8304
	v_pk_fma_f32 v[146:147], v[70:71], v[230:231], v[146:147] op_sel_hi:[1,0,1] neg_lo:[0,1,0] neg_hi:[0,1,0]
	v_pk_fma_f32 v[148:149], v[72:73], v[230:231], v[148:149] op_sel_hi:[1,0,1] neg_lo:[0,1,0] neg_hi:[0,1,0]
	ds_read_b128 v[70:73], v233 offset:8320
	s_waitcnt lgkmcnt(7)
	v_pk_fma_f32 v[150:151], v[194:195], v[230:231], v[150:151] op_sel_hi:[1,0,1] neg_lo:[0,1,0] neg_hi:[0,1,0]
	v_pk_fma_f32 v[152:153], v[196:197], v[230:231], v[152:153] op_sel_hi:[1,0,1] neg_lo:[0,1,0] neg_hi:[0,1,0]
	ds_read_b128 v[194:197], v233 offset:8336
	v_pk_fma_f32 v[154:155], v[198:199], v[230:231], v[154:155] op_sel_hi:[1,0,1] neg_lo:[0,1,0] neg_hi:[0,1,0]
	v_pk_fma_f32 v[180:181], v[200:201], v[230:231], v[180:181] op_sel_hi:[1,0,1] neg_lo:[0,1,0] neg_hi:[0,1,0]
	ds_read_b128 v[198:201], v233 offset:8352
	s_waitcnt lgkmcnt(7)
	v_pk_fma_f32 v[182:183], v[202:203], v[230:231], v[182:183] op_sel_hi:[1,0,1] neg_lo:[0,1,0] neg_hi:[0,1,0]
	v_pk_fma_f32 v[184:185], v[204:205], v[230:231], v[184:185] op_sel_hi:[1,0,1] neg_lo:[0,1,0] neg_hi:[0,1,0]
	ds_read_b128 v[202:205], v233 offset:8368
	v_pk_fma_f32 v[186:187], v[206:207], v[230:231], v[186:187] op_sel_hi:[1,0,1] neg_lo:[0,1,0] neg_hi:[0,1,0]
	v_pk_fma_f32 v[188:189], v[208:209], v[230:231], v[188:189] op_sel_hi:[1,0,1] neg_lo:[0,1,0] neg_hi:[0,1,0]
	ds_read_b128 v[206:209], v233 offset:8384
	s_waitcnt lgkmcnt(8)
	v_pk_fma_f32 v[190:191], v[226:227], v[230:231], v[190:191] op_sel_hi:[1,0,1] neg_lo:[0,1,0] neg_hi:[0,1,0]
	v_pk_fma_f32 v[192:193], v[228:229], v[230:231], v[192:193] op_sel_hi:[1,0,1] neg_lo:[0,1,0] neg_hi:[0,1,0]
	ds_read_b128 v[226:229], v233 offset:8400
	s_nop 0
	v_mov_b32_e32 v230, v136
	v_cvt_pk_bf16_f32 v232, v230, v230
	global_store_short v28, v232, s[0:1]
	s_add_u32 s0, s0, 0x400
	s_addc_u32 s1, s1, 0
	s_waitcnt lgkmcnt(7)
	v_pk_fma_f32 v[136:137], v[60:61], v[230:231], v[136:137] op_sel_hi:[1,0,1] neg_lo:[0,1,0] neg_hi:[0,1,0]
	v_pk_fma_f32 v[138:139], v[62:63], v[230:231], v[138:139] op_sel_hi:[1,0,1] neg_lo:[0,1,0] neg_hi:[0,1,0]
	v_pk_fma_f32 v[140:141], v[64:65], v[230:231], v[140:141] op_sel_hi:[1,0,1] neg_lo:[0,1,0] neg_hi:[0,1,0]
	ds_read_b128 v[62:65], v233 offset:8560
	s_waitcnt lgkmcnt(6)
	v_pk_fma_f32 v[142:143], v[66:67], v[230:231], v[142:143] op_sel_hi:[1,0,1] neg_lo:[0,1,0] neg_hi:[0,1,0]
	v_pk_fma_f32 v[144:145], v[68:69], v[230:231], v[144:145] op_sel_hi:[1,0,1] neg_lo:[0,1,0] neg_hi:[0,1,0]
	ds_read_b128 v[66:69], v233 offset:8576
	v_pk_fma_f32 v[146:147], v[70:71], v[230:231], v[146:147] op_sel_hi:[1,0,1] neg_lo:[0,1,0] neg_hi:[0,1,0]
	v_pk_fma_f32 v[148:149], v[72:73], v[230:231], v[148:149] op_sel_hi:[1,0,1] neg_lo:[0,1,0] neg_hi:[0,1,0]
	ds_read_b128 v[70:73], v233 offset:8592
	s_waitcnt lgkmcnt(6)
	v_pk_fma_f32 v[150:151], v[194:195], v[230:231], v[150:151] op_sel_hi:[1,0,1] neg_lo:[0,1,0] neg_hi:[0,1,0]
	v_pk_fma_f32 v[152:153], v[196:197], v[230:231], v[152:153] op_sel_hi:[1,0,1] neg_lo:[0,1,0] neg_hi:[0,1,0]
	ds_read_b128 v[194:197], v233 offset:8608
	v_pk_fma_f32 v[154:155], v[198:199], v[230:231], v[154:155] op_sel_hi:[1,0,1] neg_lo:[0,1,0] neg_hi:[0,1,0]
	v_pk_fma_f32 v[180:181], v[200:201], v[230:231], v[180:181] op_sel_hi:[1,0,1] neg_lo:[0,1,0] neg_hi:[0,1,0]
	ds_read_b128 v[198:201], v233 offset:8624
	s_waitcnt lgkmcnt(6)
	v_pk_fma_f32 v[182:183], v[202:203], v[230:231], v[182:183] op_sel_hi:[1,0,1] neg_lo:[0,1,0] neg_hi:[0,1,0]
	v_pk_fma_f32 v[184:185], v[204:205], v[230:231], v[184:185] op_sel_hi:[1,0,1] neg_lo:[0,1,0] neg_hi:[0,1,0]
	ds_read_b128 v[202:205], v233 offset:8640
	v_pk_fma_f32 v[186:187], v[206:207], v[230:231], v[186:187] op_sel_hi:[1,0,1] neg_lo:[0,1,0] neg_hi:[0,1,0]
	v_pk_fma_f32 v[188:189], v[208:209], v[230:231], v[188:189] op_sel_hi:[1,0,1] neg_lo:[0,1,0] neg_hi:[0,1,0]
	ds_read_b128 v[206:209], v233 offset:8656
	s_waitcnt lgkmcnt(7)
	v_pk_fma_f32 v[190:191], v[226:227], v[230:231], v[190:191] op_sel_hi:[1,0,1] neg_lo:[0,1,0] neg_hi:[0,1,0]
	v_pk_fma_f32 v[192:193], v[228:229], v[230:231], v[192:193] op_sel_hi:[1,0,1] neg_lo:[0,1,0] neg_hi:[0,1,0]
	ds_read_b128 v[226:229], v233 offset:8672
	s_nop 0
	v_mov_b32_e32 v230, v137
	v_cvt_pk_bf16_f32 v232, v230, v230
	global_store_short v28, v232, s[0:1]
	s_add_u32 s0, s0, 0x400
	s_addc_u32 s1, s1, 0
	s_waitcnt lgkmcnt(6)
	v_pk_fma_f32 v[138:139], v[62:63], v[230:231], v[138:139] op_sel_hi:[1,0,1] neg_lo:[0,1,0] neg_hi:[0,1,0]
	v_pk_fma_f32 v[140:141], v[64:65], v[230:231], v[140:141] op_sel_hi:[1,0,1] neg_lo:[0,1,0] neg_hi:[0,1,0]
	ds_read_b128 v[62:65], v233 offset:8832
	v_pk_fma_f32 v[142:143], v[66:67], v[230:231], v[142:143] op_sel_hi:[1,0,1] neg_lo:[0,1,0] neg_hi:[0,1,0]
	v_pk_fma_f32 v[144:145], v[68:69], v[230:231], v[144:145] op_sel_hi:[1,0,1] neg_lo:[0,1,0] neg_hi:[0,1,0]
	ds_read_b128 v[66:69], v233 offset:8848
	s_waitcnt lgkmcnt(6)
	v_pk_fma_f32 v[146:147], v[70:71], v[230:231], v[146:147] op_sel_hi:[1,0,1] neg_lo:[0,1,0] neg_hi:[0,1,0]
	v_pk_fma_f32 v[148:149], v[72:73], v[230:231], v[148:149] op_sel_hi:[1,0,1] neg_lo:[0,1,0] neg_hi:[0,1,0]
	ds_read_b128 v[70:73], v233 offset:8864
	v_pk_fma_f32 v[150:151], v[194:195], v[230:231], v[150:151] op_sel_hi:[1,0,1] neg_lo:[0,1,0] neg_hi:[0,1,0]
	v_pk_fma_f32 v[152:153], v[196:197], v[230:231], v[152:153] op_sel_hi:[1,0,1] neg_lo:[0,1,0] neg_hi:[0,1,0]
	ds_read_b128 v[194:197], v233 offset:8880
	s_waitcnt lgkmcnt(6)
	v_pk_fma_f32 v[154:155], v[198:199], v[230:231], v[154:155] op_sel_hi:[1,0,1] neg_lo:[0,1,0] neg_hi:[0,1,0]
	v_pk_fma_f32 v[180:181], v[200:201], v[230:231], v[180:181] op_sel_hi:[1,0,1] neg_lo:[0,1,0] neg_hi:[0,1,0]
	ds_read_b128 v[198:201], v233 offset:8896
	v_pk_fma_f32 v[182:183], v[202:203], v[230:231], v[182:183] op_sel_hi:[1,0,1] neg_lo:[0,1,0] neg_hi:[0,1,0]
	v_pk_fma_f32 v[184:185], v[204:205], v[230:231], v[184:185] op_sel_hi:[1,0,1] neg_lo:[0,1,0] neg_hi:[0,1,0]
	ds_read_b128 v[202:205], v233 offset:8912
	s_waitcnt lgkmcnt(6)
	v_pk_fma_f32 v[186:187], v[206:207], v[230:231], v[186:187] op_sel_hi:[1,0,1] neg_lo:[0,1,0] neg_hi:[0,1,0]
	v_pk_fma_f32 v[188:189], v[208:209], v[230:231], v[188:189] op_sel_hi:[1,0,1] neg_lo:[0,1,0] neg_hi:[0,1,0]
	ds_read_b128 v[206:209], v233 offset:8928
	v_pk_fma_f32 v[190:191], v[226:227], v[230:231], v[190:191] op_sel_hi:[1,0,1] neg_lo:[0,1,0] neg_hi:[0,1,0]
	v_pk_fma_f32 v[192:193], v[228:229], v[230:231], v[192:193] op_sel_hi:[1,0,1] neg_lo:[0,1,0] neg_hi:[0,1,0]
	ds_read_b128 v[226:229], v233 offset:8944
	s_nop 0
	v_mov_b32_e32 v230, v138
	v_cvt_pk_bf16_f32 v232, v230, v230
	global_store_short v28, v232, s[0:1]
	s_add_u32 s0, s0, 0x400
	s_addc_u32 s1, s1, 0
	s_waitcnt lgkmcnt(6)
	v_pk_fma_f32 v[138:139], v[62:63], v[230:231], v[138:139] op_sel_hi:[1,0,1] neg_lo:[0,1,0] neg_hi:[0,1,0]
	v_pk_fma_f32 v[140:141], v[64:65], v[230:231], v[140:141] op_sel_hi:[1,0,1] neg_lo:[0,1,0] neg_hi:[0,1,0]
	ds_read_b128 v[62:65], v233 offset:9104
	v_pk_fma_f32 v[142:143], v[66:67], v[230:231], v[142:143] op_sel_hi:[1,0,1] neg_lo:[0,1,0] neg_hi:[0,1,0]
	v_pk_fma_f32 v[144:145], v[68:69], v[230:231], v[144:145] op_sel_hi:[1,0,1] neg_lo:[0,1,0] neg_hi:[0,1,0]
	ds_read_b128 v[66:69], v233 offset:9120
	s_waitcnt lgkmcnt(6)
	v_pk_fma_f32 v[146:147], v[70:71], v[230:231], v[146:147] op_sel_hi:[1,0,1] neg_lo:[0,1,0] neg_hi:[0,1,0]
	v_pk_fma_f32 v[148:149], v[72:73], v[230:231], v[148:149] op_sel_hi:[1,0,1] neg_lo:[0,1,0] neg_hi:[0,1,0]
	ds_read_b128 v[70:73], v233 offset:9136
	v_pk_fma_f32 v[150:151], v[194:195], v[230:231], v[150:151] op_sel_hi:[1,0,1] neg_lo:[0,1,0] neg_hi:[0,1,0]
	v_pk_fma_f32 v[152:153], v[196:197], v[230:231], v[152:153] op_sel_hi:[1,0,1] neg_lo:[0,1,0] neg_hi:[0,1,0]
	ds_read_b128 v[194:197], v233 offset:9152
	s_waitcnt lgkmcnt(6)
	v_pk_fma_f32 v[154:155], v[198:199], v[230:231], v[154:155] op_sel_hi:[1,0,1] neg_lo:[0,1,0] neg_hi:[0,1,0]
	v_pk_fma_f32 v[180:181], v[200:201], v[230:231], v[180:181] op_sel_hi:[1,0,1] neg_lo:[0,1,0] neg_hi:[0,1,0]
	ds_read_b128 v[198:201], v233 offset:9168
	v_pk_fma_f32 v[182:183], v[202:203], v[230:231], v[182:183] op_sel_hi:[1,0,1] neg_lo:[0,1,0] neg_hi:[0,1,0]
	v_pk_fma_f32 v[184:185], v[204:205], v[230:231], v[184:185] op_sel_hi:[1,0,1] neg_lo:[0,1,0] neg_hi:[0,1,0]
	ds_read_b128 v[202:205], v233 offset:9184
	s_waitcnt lgkmcnt(6)
	v_pk_fma_f32 v[186:187], v[206:207], v[230:231], v[186:187] op_sel_hi:[1,0,1] neg_lo:[0,1,0] neg_hi:[0,1,0]
	v_pk_fma_f32 v[188:189], v[208:209], v[230:231], v[188:189] op_sel_hi:[1,0,1] neg_lo:[0,1,0] neg_hi:[0,1,0]
	ds_read_b128 v[206:209], v233 offset:9200
	v_pk_fma_f32 v[190:191], v[226:227], v[230:231], v[190:191] op_sel_hi:[1,0,1] neg_lo:[0,1,0] neg_hi:[0,1,0]
	v_pk_fma_f32 v[192:193], v[228:229], v[230:231], v[192:193] op_sel_hi:[1,0,1] neg_lo:[0,1,0] neg_hi:[0,1,0]
	ds_read_b128 v[226:229], v233 offset:9216
	s_nop 0
	v_mov_b32_e32 v230, v139
	v_cvt_pk_bf16_f32 v232, v230, v230
	global_store_short v28, v232, s[0:1]
	s_add_u32 s0, s0, 0x400
	s_addc_u32 s1, s1, 0
	s_waitcnt lgkmcnt(6)
	v_pk_fma_f32 v[140:141], v[64:65], v[230:231], v[140:141] op_sel_hi:[1,0,1] neg_lo:[0,1,0] neg_hi:[0,1,0]
	ds_read_b128 v[62:65], v233 offset:9376
	v_pk_fma_f32 v[142:143], v[66:67], v[230:231], v[142:143] op_sel_hi:[1,0,1] neg_lo:[0,1,0] neg_hi:[0,1,0]
	v_pk_fma_f32 v[144:145], v[68:69], v[230:231], v[144:145] op_sel_hi:[1,0,1] neg_lo:[0,1,0] neg_hi:[0,1,0]
	ds_read_b128 v[66:69], v233 offset:9392
	s_waitcnt lgkmcnt(6)
	v_pk_fma_f32 v[146:147], v[70:71], v[230:231], v[146:147] op_sel_hi:[1,0,1] neg_lo:[0,1,0] neg_hi:[0,1,0]
	v_pk_fma_f32 v[148:149], v[72:73], v[230:231], v[148:149] op_sel_hi:[1,0,1] neg_lo:[0,1,0] neg_hi:[0,1,0]
	ds_read_b128 v[70:73], v233 offset:9408
	v_pk_fma_f32 v[150:151], v[194:195], v[230:231], v[150:151] op_sel_hi:[1,0,1] neg_lo:[0,1,0] neg_hi:[0,1,0]
	v_pk_fma_f32 v[152:153], v[196:197], v[230:231], v[152:153] op_sel_hi:[1,0,1] neg_lo:[0,1,0] neg_hi:[0,1,0]
	ds_read_b128 v[194:197], v233 offset:9424
	s_waitcnt lgkmcnt(6)
	v_pk_fma_f32 v[154:155], v[198:199], v[230:231], v[154:155] op_sel_hi:[1,0,1] neg_lo:[0,1,0] neg_hi:[0,1,0]
	v_pk_fma_f32 v[180:181], v[200:201], v[230:231], v[180:181] op_sel_hi:[1,0,1] neg_lo:[0,1,0] neg_hi:[0,1,0]
	ds_read_b128 v[198:201], v233 offset:9440
	v_pk_fma_f32 v[182:183], v[202:203], v[230:231], v[182:183] op_sel_hi:[1,0,1] neg_lo:[0,1,0] neg_hi:[0,1,0]
	v_pk_fma_f32 v[184:185], v[204:205], v[230:231], v[184:185] op_sel_hi:[1,0,1] neg_lo:[0,1,0] neg_hi:[0,1,0]
	ds_read_b128 v[202:205], v233 offset:9456
	s_waitcnt lgkmcnt(6)
	v_pk_fma_f32 v[186:187], v[206:207], v[230:231], v[186:187] op_sel_hi:[1,0,1] neg_lo:[0,1,0] neg_hi:[0,1,0]
	v_pk_fma_f32 v[188:189], v[208:209], v[230:231], v[188:189] op_sel_hi:[1,0,1] neg_lo:[0,1,0] neg_hi:[0,1,0]
	ds_read_b128 v[206:209], v233 offset:9472
	v_pk_fma_f32 v[190:191], v[226:227], v[230:231], v[190:191] op_sel_hi:[1,0,1] neg_lo:[0,1,0] neg_hi:[0,1,0]
	v_pk_fma_f32 v[192:193], v[228:229], v[230:231], v[192:193] op_sel_hi:[1,0,1] neg_lo:[0,1,0] neg_hi:[0,1,0]
	ds_read_b128 v[226:229], v233 offset:9488
	s_nop 0
	v_mov_b32_e32 v230, v140
	v_cvt_pk_bf16_f32 v232, v230, v230
	global_store_short v28, v232, s[0:1]
	s_add_u32 s0, s0, 0x400
	s_addc_u32 s1, s1, 0
	s_waitcnt lgkmcnt(6)
	v_pk_fma_f32 v[140:141], v[64:65], v[230:231], v[140:141] op_sel_hi:[1,0,1] neg_lo:[0,1,0] neg_hi:[0,1,0]
	v_pk_fma_f32 v[142:143], v[66:67], v[230:231], v[142:143] op_sel_hi:[1,0,1] neg_lo:[0,1,0] neg_hi:[0,1,0]
	v_pk_fma_f32 v[144:145], v[68:69], v[230:231], v[144:145] op_sel_hi:[1,0,1] neg_lo:[0,1,0] neg_hi:[0,1,0]
	ds_read_b128 v[66:69], v233 offset:9664
	s_waitcnt lgkmcnt(5)
	v_pk_fma_f32 v[146:147], v[70:71], v[230:231], v[146:147] op_sel_hi:[1,0,1] neg_lo:[0,1,0] neg_hi:[0,1,0]
	v_pk_fma_f32 v[148:149], v[72:73], v[230:231], v[148:149] op_sel_hi:[1,0,1] neg_lo:[0,1,0] neg_hi:[0,1,0]
	ds_read_b128 v[70:73], v233 offset:9680
	v_pk_fma_f32 v[150:151], v[194:195], v[230:231], v[150:151] op_sel_hi:[1,0,1] neg_lo:[0,1,0] neg_hi:[0,1,0]
	v_pk_fma_f32 v[152:153], v[196:197], v[230:231], v[152:153] op_sel_hi:[1,0,1] neg_lo:[0,1,0] neg_hi:[0,1,0]
	ds_read_b128 v[194:197], v233 offset:9696
	s_waitcnt lgkmcnt(5)
	v_pk_fma_f32 v[154:155], v[198:199], v[230:231], v[154:155] op_sel_hi:[1,0,1] neg_lo:[0,1,0] neg_hi:[0,1,0]
	v_pk_fma_f32 v[180:181], v[200:201], v[230:231], v[180:181] op_sel_hi:[1,0,1] neg_lo:[0,1,0] neg_hi:[0,1,0]
	ds_read_b128 v[198:201], v233 offset:9712
	v_pk_fma_f32 v[182:183], v[202:203], v[230:231], v[182:183] op_sel_hi:[1,0,1] neg_lo:[0,1,0] neg_hi:[0,1,0]
	v_pk_fma_f32 v[184:185], v[204:205], v[230:231], v[184:185] op_sel_hi:[1,0,1] neg_lo:[0,1,0] neg_hi:[0,1,0]
	ds_read_b128 v[202:205], v233 offset:9728
	s_waitcnt lgkmcnt(5)
	v_pk_fma_f32 v[186:187], v[206:207], v[230:231], v[186:187] op_sel_hi:[1,0,1] neg_lo:[0,1,0] neg_hi:[0,1,0]
	v_pk_fma_f32 v[188:189], v[208:209], v[230:231], v[188:189] op_sel_hi:[1,0,1] neg_lo:[0,1,0] neg_hi:[0,1,0]
	ds_read_b128 v[206:209], v233 offset:9744
	v_pk_fma_f32 v[190:191], v[226:227], v[230:231], v[190:191] op_sel_hi:[1,0,1] neg_lo:[0,1,0] neg_hi:[0,1,0]
	v_pk_fma_f32 v[192:193], v[228:229], v[230:231], v[192:193] op_sel_hi:[1,0,1] neg_lo:[0,1,0] neg_hi:[0,1,0]
	ds_read_b128 v[226:229], v233 offset:9760
	s_nop 0
	v_mov_b32_e32 v230, v141
	v_cvt_pk_bf16_f32 v232, v230, v230
	global_store_short v28, v232, s[0:1]
	s_add_u32 s0, s0, 0x400
	s_addc_u32 s1, s1, 0
	s_waitcnt lgkmcnt(5)
	v_pk_fma_f32 v[142:143], v[66:67], v[230:231], v[142:143] op_sel_hi:[1,0,1] neg_lo:[0,1,0] neg_hi:[0,1,0]
	v_pk_fma_f32 v[144:145], v[68:69], v[230:231], v[144:145] op_sel_hi:[1,0,1] neg_lo:[0,1,0] neg_hi:[0,1,0]
	ds_read_b128 v[66:69], v233 offset:9936
	v_pk_fma_f32 v[146:147], v[70:71], v[230:231], v[146:147] op_sel_hi:[1,0,1] neg_lo:[0,1,0] neg_hi:[0,1,0]
	v_pk_fma_f32 v[148:149], v[72:73], v[230:231], v[148:149] op_sel_hi:[1,0,1] neg_lo:[0,1,0] neg_hi:[0,1,0]
	ds_read_b128 v[70:73], v233 offset:9952
	s_waitcnt lgkmcnt(5)
	v_pk_fma_f32 v[150:151], v[194:195], v[230:231], v[150:151] op_sel_hi:[1,0,1] neg_lo:[0,1,0] neg_hi:[0,1,0]
	v_pk_fma_f32 v[152:153], v[196:197], v[230:231], v[152:153] op_sel_hi:[1,0,1] neg_lo:[0,1,0] neg_hi:[0,1,0]
	ds_read_b128 v[194:197], v233 offset:9968
	v_pk_fma_f32 v[154:155], v[198:199], v[230:231], v[154:155] op_sel_hi:[1,0,1] neg_lo:[0,1,0] neg_hi:[0,1,0]
	v_pk_fma_f32 v[180:181], v[200:201], v[230:231], v[180:181] op_sel_hi:[1,0,1] neg_lo:[0,1,0] neg_hi:[0,1,0]
	ds_read_b128 v[198:201], v233 offset:9984
	s_waitcnt lgkmcnt(5)
	v_pk_fma_f32 v[182:183], v[202:203], v[230:231], v[182:183] op_sel_hi:[1,0,1] neg_lo:[0,1,0] neg_hi:[0,1,0]
	v_pk_fma_f32 v[184:185], v[204:205], v[230:231], v[184:185] op_sel_hi:[1,0,1] neg_lo:[0,1,0] neg_hi:[0,1,0]
	ds_read_b128 v[202:205], v233 offset:10000
	v_pk_fma_f32 v[186:187], v[206:207], v[230:231], v[186:187] op_sel_hi:[1,0,1] neg_lo:[0,1,0] neg_hi:[0,1,0]
	v_pk_fma_f32 v[188:189], v[208:209], v[230:231], v[188:189] op_sel_hi:[1,0,1] neg_lo:[0,1,0] neg_hi:[0,1,0]
	ds_read_b128 v[206:209], v233 offset:10016
	s_waitcnt lgkmcnt(6)
	v_pk_fma_f32 v[190:191], v[226:227], v[230:231], v[190:191] op_sel_hi:[1,0,1] neg_lo:[0,1,0] neg_hi:[0,1,0]
	v_pk_fma_f32 v[192:193], v[228:229], v[230:231], v[192:193] op_sel_hi:[1,0,1] neg_lo:[0,1,0] neg_hi:[0,1,0]
	ds_read_b128 v[226:229], v233 offset:10032
	s_nop 0
	v_mov_b32_e32 v230, v142
	v_cvt_pk_bf16_f32 v232, v230, v230
	global_store_short v28, v232, s[0:1]
	s_add_u32 s0, s0, 0x400
	s_addc_u32 s1, s1, 0
	s_waitcnt lgkmcnt(5)
	v_pk_fma_f32 v[142:143], v[66:67], v[230:231], v[142:143] op_sel_hi:[1,0,1] neg_lo:[0,1,0] neg_hi:[0,1,0]
	v_pk_fma_f32 v[144:145], v[68:69], v[230:231], v[144:145] op_sel_hi:[1,0,1] neg_lo:[0,1,0] neg_hi:[0,1,0]
	ds_read_b128 v[66:69], v233 offset:10208
	v_pk_fma_f32 v[146:147], v[70:71], v[230:231], v[146:147] op_sel_hi:[1,0,1] neg_lo:[0,1,0] neg_hi:[0,1,0]
	v_pk_fma_f32 v[148:149], v[72:73], v[230:231], v[148:149] op_sel_hi:[1,0,1] neg_lo:[0,1,0] neg_hi:[0,1,0]
	ds_read_b128 v[70:73], v233 offset:10224
	s_waitcnt lgkmcnt(5)
	v_pk_fma_f32 v[150:151], v[194:195], v[230:231], v[150:151] op_sel_hi:[1,0,1] neg_lo:[0,1,0] neg_hi:[0,1,0]
	v_pk_fma_f32 v[152:153], v[196:197], v[230:231], v[152:153] op_sel_hi:[1,0,1] neg_lo:[0,1,0] neg_hi:[0,1,0]
	ds_read_b128 v[194:197], v233 offset:10240
	v_pk_fma_f32 v[154:155], v[198:199], v[230:231], v[154:155] op_sel_hi:[1,0,1] neg_lo:[0,1,0] neg_hi:[0,1,0]
	v_pk_fma_f32 v[180:181], v[200:201], v[230:231], v[180:181] op_sel_hi:[1,0,1] neg_lo:[0,1,0] neg_hi:[0,1,0]
	ds_read_b128 v[198:201], v233 offset:10256
	s_waitcnt lgkmcnt(5)
	v_pk_fma_f32 v[182:183], v[202:203], v[230:231], v[182:183] op_sel_hi:[1,0,1] neg_lo:[0,1,0] neg_hi:[0,1,0]
	v_pk_fma_f32 v[184:185], v[204:205], v[230:231], v[184:185] op_sel_hi:[1,0,1] neg_lo:[0,1,0] neg_hi:[0,1,0]
	ds_read_b128 v[202:205], v233 offset:10272
	v_pk_fma_f32 v[186:187], v[206:207], v[230:231], v[186:187] op_sel_hi:[1,0,1] neg_lo:[0,1,0] neg_hi:[0,1,0]
	v_pk_fma_f32 v[188:189], v[208:209], v[230:231], v[188:189] op_sel_hi:[1,0,1] neg_lo:[0,1,0] neg_hi:[0,1,0]
	ds_read_b128 v[206:209], v233 offset:10288
	s_waitcnt lgkmcnt(6)
	v_pk_fma_f32 v[190:191], v[226:227], v[230:231], v[190:191] op_sel_hi:[1,0,1] neg_lo:[0,1,0] neg_hi:[0,1,0]
	v_pk_fma_f32 v[192:193], v[228:229], v[230:231], v[192:193] op_sel_hi:[1,0,1] neg_lo:[0,1,0] neg_hi:[0,1,0]
	ds_read_b128 v[226:229], v233 offset:10304
	s_nop 0
	v_mov_b32_e32 v230, v143
	v_cvt_pk_bf16_f32 v232, v230, v230
	global_store_short v28, v232, s[0:1]
	s_add_u32 s0, s0, 0x400
	s_addc_u32 s1, s1, 0
	s_waitcnt lgkmcnt(5)
	v_pk_fma_f32 v[144:145], v[68:69], v[230:231], v[144:145] op_sel_hi:[1,0,1] neg_lo:[0,1,0] neg_hi:[0,1,0]
	ds_read_b128 v[66:69], v233 offset:10480
	v_pk_fma_f32 v[146:147], v[70:71], v[230:231], v[146:147] op_sel_hi:[1,0,1] neg_lo:[0,1,0] neg_hi:[0,1,0]
	v_pk_fma_f32 v[148:149], v[72:73], v[230:231], v[148:149] op_sel_hi:[1,0,1] neg_lo:[0,1,0] neg_hi:[0,1,0]
	ds_read_b128 v[70:73], v233 offset:10496
	s_waitcnt lgkmcnt(5)
	v_pk_fma_f32 v[150:151], v[194:195], v[230:231], v[150:151] op_sel_hi:[1,0,1] neg_lo:[0,1,0] neg_hi:[0,1,0]
	v_pk_fma_f32 v[152:153], v[196:197], v[230:231], v[152:153] op_sel_hi:[1,0,1] neg_lo:[0,1,0] neg_hi:[0,1,0]
	ds_read_b128 v[194:197], v233 offset:10512
	v_pk_fma_f32 v[154:155], v[198:199], v[230:231], v[154:155] op_sel_hi:[1,0,1] neg_lo:[0,1,0] neg_hi:[0,1,0]
	v_pk_fma_f32 v[180:181], v[200:201], v[230:231], v[180:181] op_sel_hi:[1,0,1] neg_lo:[0,1,0] neg_hi:[0,1,0]
	ds_read_b128 v[198:201], v233 offset:10528
	s_waitcnt lgkmcnt(5)
	v_pk_fma_f32 v[182:183], v[202:203], v[230:231], v[182:183] op_sel_hi:[1,0,1] neg_lo:[0,1,0] neg_hi:[0,1,0]
	v_pk_fma_f32 v[184:185], v[204:205], v[230:231], v[184:185] op_sel_hi:[1,0,1] neg_lo:[0,1,0] neg_hi:[0,1,0]
	ds_read_b128 v[202:205], v233 offset:10544
	v_pk_fma_f32 v[186:187], v[206:207], v[230:231], v[186:187] op_sel_hi:[1,0,1] neg_lo:[0,1,0] neg_hi:[0,1,0]
	v_pk_fma_f32 v[188:189], v[208:209], v[230:231], v[188:189] op_sel_hi:[1,0,1] neg_lo:[0,1,0] neg_hi:[0,1,0]
	ds_read_b128 v[206:209], v233 offset:10560
	s_waitcnt lgkmcnt(6)
	v_pk_fma_f32 v[190:191], v[226:227], v[230:231], v[190:191] op_sel_hi:[1,0,1] neg_lo:[0,1,0] neg_hi:[0,1,0]
	v_pk_fma_f32 v[192:193], v[228:229], v[230:231], v[192:193] op_sel_hi:[1,0,1] neg_lo:[0,1,0] neg_hi:[0,1,0]
	ds_read_b128 v[226:229], v233 offset:10576
	s_nop 0
	v_mov_b32_e32 v230, v144
	v_cvt_pk_bf16_f32 v232, v230, v230
	global_store_short v28, v232, s[0:1]
	s_add_u32 s0, s0, 0x400
	s_addc_u32 s1, s1, 0
	s_waitcnt lgkmcnt(5)
	v_pk_fma_f32 v[144:145], v[68:69], v[230:231], v[144:145] op_sel_hi:[1,0,1] neg_lo:[0,1,0] neg_hi:[0,1,0]
	v_pk_fma_f32 v[146:147], v[70:71], v[230:231], v[146:147] op_sel_hi:[1,0,1] neg_lo:[0,1,0] neg_hi:[0,1,0]
	v_pk_fma_f32 v[148:149], v[72:73], v[230:231], v[148:149] op_sel_hi:[1,0,1] neg_lo:[0,1,0] neg_hi:[0,1,0]
	ds_read_b128 v[70:73], v233 offset:10768
	s_waitcnt lgkmcnt(4)
	v_pk_fma_f32 v[150:151], v[194:195], v[230:231], v[150:151] op_sel_hi:[1,0,1] neg_lo:[0,1,0] neg_hi:[0,1,0]
	v_pk_fma_f32 v[152:153], v[196:197], v[230:231], v[152:153] op_sel_hi:[1,0,1] neg_lo:[0,1,0] neg_hi:[0,1,0]
	ds_read_b128 v[194:197], v233 offset:10784
	v_pk_fma_f32 v[154:155], v[198:199], v[230:231], v[154:155] op_sel_hi:[1,0,1] neg_lo:[0,1,0] neg_hi:[0,1,0]
	v_pk_fma_f32 v[180:181], v[200:201], v[230:231], v[180:181] op_sel_hi:[1,0,1] neg_lo:[0,1,0] neg_hi:[0,1,0]
	ds_read_b128 v[198:201], v233 offset:10800
	s_waitcnt lgkmcnt(4)
	v_pk_fma_f32 v[182:183], v[202:203], v[230:231], v[182:183] op_sel_hi:[1,0,1] neg_lo:[0,1,0] neg_hi:[0,1,0]
	v_pk_fma_f32 v[184:185], v[204:205], v[230:231], v[184:185] op_sel_hi:[1,0,1] neg_lo:[0,1,0] neg_hi:[0,1,0]
	ds_read_b128 v[202:205], v233 offset:10816
	v_pk_fma_f32 v[186:187], v[206:207], v[230:231], v[186:187] op_sel_hi:[1,0,1] neg_lo:[0,1,0] neg_hi:[0,1,0]
	v_pk_fma_f32 v[188:189], v[208:209], v[230:231], v[188:189] op_sel_hi:[1,0,1] neg_lo:[0,1,0] neg_hi:[0,1,0]
	ds_read_b128 v[206:209], v233 offset:10832
	s_waitcnt lgkmcnt(5)
	v_pk_fma_f32 v[190:191], v[226:227], v[230:231], v[190:191] op_sel_hi:[1,0,1] neg_lo:[0,1,0] neg_hi:[0,1,0]
	v_pk_fma_f32 v[192:193], v[228:229], v[230:231], v[192:193] op_sel_hi:[1,0,1] neg_lo:[0,1,0] neg_hi:[0,1,0]
	ds_read_b128 v[226:229], v233 offset:10848
	s_nop 0
	v_mov_b32_e32 v230, v145
	v_cvt_pk_bf16_f32 v232, v230, v230
	global_store_short v28, v232, s[0:1]
	s_add_u32 s0, s0, 0x400
	s_addc_u32 s1, s1, 0
	s_waitcnt lgkmcnt(4)
	v_pk_fma_f32 v[146:147], v[70:71], v[230:231], v[146:147] op_sel_hi:[1,0,1] neg_lo:[0,1,0] neg_hi:[0,1,0]
	v_pk_fma_f32 v[148:149], v[72:73], v[230:231], v[148:149] op_sel_hi:[1,0,1] neg_lo:[0,1,0] neg_hi:[0,1,0]
	ds_read_b128 v[70:73], v233 offset:11040
	v_pk_fma_f32 v[150:151], v[194:195], v[230:231], v[150:151] op_sel_hi:[1,0,1] neg_lo:[0,1,0] neg_hi:[0,1,0]
	v_pk_fma_f32 v[152:153], v[196:197], v[230:231], v[152:153] op_sel_hi:[1,0,1] neg_lo:[0,1,0] neg_hi:[0,1,0]
	ds_read_b128 v[194:197], v233 offset:11056
	s_waitcnt lgkmcnt(4)
	v_pk_fma_f32 v[154:155], v[198:199], v[230:231], v[154:155] op_sel_hi:[1,0,1] neg_lo:[0,1,0] neg_hi:[0,1,0]
	v_pk_fma_f32 v[180:181], v[200:201], v[230:231], v[180:181] op_sel_hi:[1,0,1] neg_lo:[0,1,0] neg_hi:[0,1,0]
	ds_read_b128 v[198:201], v233 offset:11072
	v_pk_fma_f32 v[182:183], v[202:203], v[230:231], v[182:183] op_sel_hi:[1,0,1] neg_lo:[0,1,0] neg_hi:[0,1,0]
	v_pk_fma_f32 v[184:185], v[204:205], v[230:231], v[184:185] op_sel_hi:[1,0,1] neg_lo:[0,1,0] neg_hi:[0,1,0]
	ds_read_b128 v[202:205], v233 offset:11088
	s_waitcnt lgkmcnt(4)
	v_pk_fma_f32 v[186:187], v[206:207], v[230:231], v[186:187] op_sel_hi:[1,0,1] neg_lo:[0,1,0] neg_hi:[0,1,0]
	v_pk_fma_f32 v[188:189], v[208:209], v[230:231], v[188:189] op_sel_hi:[1,0,1] neg_lo:[0,1,0] neg_hi:[0,1,0]
	ds_read_b128 v[206:209], v233 offset:11104
	v_pk_fma_f32 v[190:191], v[226:227], v[230:231], v[190:191] op_sel_hi:[1,0,1] neg_lo:[0,1,0] neg_hi:[0,1,0]
	v_pk_fma_f32 v[192:193], v[228:229], v[230:231], v[192:193] op_sel_hi:[1,0,1] neg_lo:[0,1,0] neg_hi:[0,1,0]
	ds_read_b128 v[226:229], v233 offset:11120
	s_nop 0
	v_mov_b32_e32 v230, v146
	v_cvt_pk_bf16_f32 v232, v230, v230
	global_store_short v28, v232, s[0:1]
	s_add_u32 s0, s0, 0x400
	s_addc_u32 s1, s1, 0
	s_waitcnt lgkmcnt(4)
	v_pk_fma_f32 v[146:147], v[70:71], v[230:231], v[146:147] op_sel_hi:[1,0,1] neg_lo:[0,1,0] neg_hi:[0,1,0]
	v_pk_fma_f32 v[148:149], v[72:73], v[230:231], v[148:149] op_sel_hi:[1,0,1] neg_lo:[0,1,0] neg_hi:[0,1,0]
	ds_read_b128 v[70:73], v233 offset:11312
	v_pk_fma_f32 v[150:151], v[194:195], v[230:231], v[150:151] op_sel_hi:[1,0,1] neg_lo:[0,1,0] neg_hi:[0,1,0]
	v_pk_fma_f32 v[152:153], v[196:197], v[230:231], v[152:153] op_sel_hi:[1,0,1] neg_lo:[0,1,0] neg_hi:[0,1,0]
	ds_read_b128 v[194:197], v233 offset:11328
	s_waitcnt lgkmcnt(4)
	v_pk_fma_f32 v[154:155], v[198:199], v[230:231], v[154:155] op_sel_hi:[1,0,1] neg_lo:[0,1,0] neg_hi:[0,1,0]
	v_pk_fma_f32 v[180:181], v[200:201], v[230:231], v[180:181] op_sel_hi:[1,0,1] neg_lo:[0,1,0] neg_hi:[0,1,0]
	ds_read_b128 v[198:201], v233 offset:11344
	v_pk_fma_f32 v[182:183], v[202:203], v[230:231], v[182:183] op_sel_hi:[1,0,1] neg_lo:[0,1,0] neg_hi:[0,1,0]
	v_pk_fma_f32 v[184:185], v[204:205], v[230:231], v[184:185] op_sel_hi:[1,0,1] neg_lo:[0,1,0] neg_hi:[0,1,0]
	ds_read_b128 v[202:205], v233 offset:11360
	s_waitcnt lgkmcnt(4)
	v_pk_fma_f32 v[186:187], v[206:207], v[230:231], v[186:187] op_sel_hi:[1,0,1] neg_lo:[0,1,0] neg_hi:[0,1,0]
	v_pk_fma_f32 v[188:189], v[208:209], v[230:231], v[188:189] op_sel_hi:[1,0,1] neg_lo:[0,1,0] neg_hi:[0,1,0]
	ds_read_b128 v[206:209], v233 offset:11376
	v_pk_fma_f32 v[190:191], v[226:227], v[230:231], v[190:191] op_sel_hi:[1,0,1] neg_lo:[0,1,0] neg_hi:[0,1,0]
	v_pk_fma_f32 v[192:193], v[228:229], v[230:231], v[192:193] op_sel_hi:[1,0,1] neg_lo:[0,1,0] neg_hi:[0,1,0]
	ds_read_b128 v[226:229], v233 offset:11392
	s_nop 0
	v_mov_b32_e32 v230, v147
	v_cvt_pk_bf16_f32 v232, v230, v230
	global_store_short v28, v232, s[0:1]
	s_add_u32 s0, s0, 0x400
	s_addc_u32 s1, s1, 0
	s_waitcnt lgkmcnt(4)
	v_pk_fma_f32 v[148:149], v[72:73], v[230:231], v[148:149] op_sel_hi:[1,0,1] neg_lo:[0,1,0] neg_hi:[0,1,0]
	ds_read_b128 v[70:73], v233 offset:11584
	v_pk_fma_f32 v[150:151], v[194:195], v[230:231], v[150:151] op_sel_hi:[1,0,1] neg_lo:[0,1,0] neg_hi:[0,1,0]
	v_pk_fma_f32 v[152:153], v[196:197], v[230:231], v[152:153] op_sel_hi:[1,0,1] neg_lo:[0,1,0] neg_hi:[0,1,0]
	ds_read_b128 v[194:197], v233 offset:11600
	s_waitcnt lgkmcnt(4)
	v_pk_fma_f32 v[154:155], v[198:199], v[230:231], v[154:155] op_sel_hi:[1,0,1] neg_lo:[0,1,0] neg_hi:[0,1,0]
	v_pk_fma_f32 v[180:181], v[200:201], v[230:231], v[180:181] op_sel_hi:[1,0,1] neg_lo:[0,1,0] neg_hi:[0,1,0]
	ds_read_b128 v[198:201], v233 offset:11616
	v_pk_fma_f32 v[182:183], v[202:203], v[230:231], v[182:183] op_sel_hi:[1,0,1] neg_lo:[0,1,0] neg_hi:[0,1,0]
	v_pk_fma_f32 v[184:185], v[204:205], v[230:231], v[184:185] op_sel_hi:[1,0,1] neg_lo:[0,1,0] neg_hi:[0,1,0]
	ds_read_b128 v[202:205], v233 offset:11632
	s_waitcnt lgkmcnt(4)
	v_pk_fma_f32 v[186:187], v[206:207], v[230:231], v[186:187] op_sel_hi:[1,0,1] neg_lo:[0,1,0] neg_hi:[0,1,0]
	v_pk_fma_f32 v[188:189], v[208:209], v[230:231], v[188:189] op_sel_hi:[1,0,1] neg_lo:[0,1,0] neg_hi:[0,1,0]
	ds_read_b128 v[206:209], v233 offset:11648
	v_pk_fma_f32 v[190:191], v[226:227], v[230:231], v[190:191] op_sel_hi:[1,0,1] neg_lo:[0,1,0] neg_hi:[0,1,0]
	v_pk_fma_f32 v[192:193], v[228:229], v[230:231], v[192:193] op_sel_hi:[1,0,1] neg_lo:[0,1,0] neg_hi:[0,1,0]
	ds_read_b128 v[226:229], v233 offset:11664
	s_nop 0
	v_mov_b32_e32 v230, v148
	v_cvt_pk_bf16_f32 v232, v230, v230
	global_store_short v28, v232, s[0:1]
	s_add_u32 s0, s0, 0x400
	s_addc_u32 s1, s1, 0
	s_waitcnt lgkmcnt(4)
	v_pk_fma_f32 v[148:149], v[72:73], v[230:231], v[148:149] op_sel_hi:[1,0,1] neg_lo:[0,1,0] neg_hi:[0,1,0]
	v_pk_fma_f32 v[150:151], v[194:195], v[230:231], v[150:151] op_sel_hi:[1,0,1] neg_lo:[0,1,0] neg_hi:[0,1,0]
	v_pk_fma_f32 v[152:153], v[196:197], v[230:231], v[152:153] op_sel_hi:[1,0,1] neg_lo:[0,1,0] neg_hi:[0,1,0]
	ds_read_b128 v[194:197], v233 offset:11872
	s_waitcnt lgkmcnt(3)
	v_pk_fma_f32 v[154:155], v[198:199], v[230:231], v[154:155] op_sel_hi:[1,0,1] neg_lo:[0,1,0] neg_hi:[0,1,0]
	v_pk_fma_f32 v[180:181], v[200:201], v[230:231], v[180:181] op_sel_hi:[1,0,1] neg_lo:[0,1,0] neg_hi:[0,1,0]
	ds_read_b128 v[198:201], v233 offset:11888
	v_pk_fma_f32 v[182:183], v[202:203], v[230:231], v[182:183] op_sel_hi:[1,0,1] neg_lo:[0,1,0] neg_hi:[0,1,0]
	v_pk_fma_f32 v[184:185], v[204:205], v[230:231], v[184:185] op_sel_hi:[1,0,1] neg_lo:[0,1,0] neg_hi:[0,1,0]
	ds_read_b128 v[202:205], v233 offset:11904
	s_waitcnt lgkmcnt(3)
	v_pk_fma_f32 v[186:187], v[206:207], v[230:231], v[186:187] op_sel_hi:[1,0,1] neg_lo:[0,1,0] neg_hi:[0,1,0]
	v_pk_fma_f32 v[188:189], v[208:209], v[230:231], v[188:189] op_sel_hi:[1,0,1] neg_lo:[0,1,0] neg_hi:[0,1,0]
	ds_read_b128 v[206:209], v233 offset:11920
	v_pk_fma_f32 v[190:191], v[226:227], v[230:231], v[190:191] op_sel_hi:[1,0,1] neg_lo:[0,1,0] neg_hi:[0,1,0]
	v_pk_fma_f32 v[192:193], v[228:229], v[230:231], v[192:193] op_sel_hi:[1,0,1] neg_lo:[0,1,0] neg_hi:[0,1,0]
	ds_read_b128 v[226:229], v233 offset:11936
	s_nop 0
	v_mov_b32_e32 v230, v149
	v_cvt_pk_bf16_f32 v232, v230, v230
	global_store_short v28, v232, s[0:1]
	s_add_u32 s0, s0, 0x400
	s_addc_u32 s1, s1, 0
	s_waitcnt lgkmcnt(3)
	v_pk_fma_f32 v[150:151], v[194:195], v[230:231], v[150:151] op_sel_hi:[1,0,1] neg_lo:[0,1,0] neg_hi:[0,1,0]
	v_pk_fma_f32 v[152:153], v[196:197], v[230:231], v[152:153] op_sel_hi:[1,0,1] neg_lo:[0,1,0] neg_hi:[0,1,0]
	ds_read_b128 v[194:197], v233 offset:12144
	v_pk_fma_f32 v[154:155], v[198:199], v[230:231], v[154:155] op_sel_hi:[1,0,1] neg_lo:[0,1,0] neg_hi:[0,1,0]
	v_pk_fma_f32 v[180:181], v[200:201], v[230:231], v[180:181] op_sel_hi:[1,0,1] neg_lo:[0,1,0] neg_hi:[0,1,0]
	ds_read_b128 v[198:201], v233 offset:12160
	s_waitcnt lgkmcnt(3)
	v_pk_fma_f32 v[182:183], v[202:203], v[230:231], v[182:183] op_sel_hi:[1,0,1] neg_lo:[0,1,0] neg_hi:[0,1,0]
	v_pk_fma_f32 v[184:185], v[204:205], v[230:231], v[184:185] op_sel_hi:[1,0,1] neg_lo:[0,1,0] neg_hi:[0,1,0]
	ds_read_b128 v[202:205], v233 offset:12176
	v_pk_fma_f32 v[186:187], v[206:207], v[230:231], v[186:187] op_sel_hi:[1,0,1] neg_lo:[0,1,0] neg_hi:[0,1,0]
	v_pk_fma_f32 v[188:189], v[208:209], v[230:231], v[188:189] op_sel_hi:[1,0,1] neg_lo:[0,1,0] neg_hi:[0,1,0]
	ds_read_b128 v[206:209], v233 offset:12192
	s_waitcnt lgkmcnt(4)
	v_pk_fma_f32 v[190:191], v[226:227], v[230:231], v[190:191] op_sel_hi:[1,0,1] neg_lo:[0,1,0] neg_hi:[0,1,0]
	v_pk_fma_f32 v[192:193], v[228:229], v[230:231], v[192:193] op_sel_hi:[1,0,1] neg_lo:[0,1,0] neg_hi:[0,1,0]
	ds_read_b128 v[226:229], v233 offset:12208
	s_nop 0
	v_mov_b32_e32 v230, v150
	v_cvt_pk_bf16_f32 v232, v230, v230
	global_store_short v28, v232, s[0:1]
	s_add_u32 s0, s0, 0x400
	s_addc_u32 s1, s1, 0
	s_waitcnt lgkmcnt(3)
	v_pk_fma_f32 v[150:151], v[194:195], v[230:231], v[150:151] op_sel_hi:[1,0,1] neg_lo:[0,1,0] neg_hi:[0,1,0]
	v_pk_fma_f32 v[152:153], v[196:197], v[230:231], v[152:153] op_sel_hi:[1,0,1] neg_lo:[0,1,0] neg_hi:[0,1,0]
	ds_read_b128 v[194:197], v233 offset:12416
	v_pk_fma_f32 v[154:155], v[198:199], v[230:231], v[154:155] op_sel_hi:[1,0,1] neg_lo:[0,1,0] neg_hi:[0,1,0]
	v_pk_fma_f32 v[180:181], v[200:201], v[230:231], v[180:181] op_sel_hi:[1,0,1] neg_lo:[0,1,0] neg_hi:[0,1,0]
	ds_read_b128 v[198:201], v233 offset:12432
	s_waitcnt lgkmcnt(3)
	v_pk_fma_f32 v[182:183], v[202:203], v[230:231], v[182:183] op_sel_hi:[1,0,1] neg_lo:[0,1,0] neg_hi:[0,1,0]
	v_pk_fma_f32 v[184:185], v[204:205], v[230:231], v[184:185] op_sel_hi:[1,0,1] neg_lo:[0,1,0] neg_hi:[0,1,0]
	ds_read_b128 v[202:205], v233 offset:12448
	v_pk_fma_f32 v[186:187], v[206:207], v[230:231], v[186:187] op_sel_hi:[1,0,1] neg_lo:[0,1,0] neg_hi:[0,1,0]
	v_pk_fma_f32 v[188:189], v[208:209], v[230:231], v[188:189] op_sel_hi:[1,0,1] neg_lo:[0,1,0] neg_hi:[0,1,0]
	ds_read_b128 v[206:209], v233 offset:12464
	s_waitcnt lgkmcnt(4)
	v_pk_fma_f32 v[190:191], v[226:227], v[230:231], v[190:191] op_sel_hi:[1,0,1] neg_lo:[0,1,0] neg_hi:[0,1,0]
	v_pk_fma_f32 v[192:193], v[228:229], v[230:231], v[192:193] op_sel_hi:[1,0,1] neg_lo:[0,1,0] neg_hi:[0,1,0]
	ds_read_b128 v[226:229], v233 offset:12480
	s_nop 0
	v_mov_b32_e32 v230, v151
	v_cvt_pk_bf16_f32 v232, v230, v230
	global_store_short v28, v232, s[0:1]
	s_add_u32 s0, s0, 0x400
	s_addc_u32 s1, s1, 0
	s_waitcnt lgkmcnt(3)
	v_pk_fma_f32 v[152:153], v[196:197], v[230:231], v[152:153] op_sel_hi:[1,0,1] neg_lo:[0,1,0] neg_hi:[0,1,0]
	ds_read_b128 v[194:197], v233 offset:12688
	v_pk_fma_f32 v[154:155], v[198:199], v[230:231], v[154:155] op_sel_hi:[1,0,1] neg_lo:[0,1,0] neg_hi:[0,1,0]
	v_pk_fma_f32 v[180:181], v[200:201], v[230:231], v[180:181] op_sel_hi:[1,0,1] neg_lo:[0,1,0] neg_hi:[0,1,0]
	ds_read_b128 v[198:201], v233 offset:12704
	s_waitcnt lgkmcnt(3)
	v_pk_fma_f32 v[182:183], v[202:203], v[230:231], v[182:183] op_sel_hi:[1,0,1] neg_lo:[0,1,0] neg_hi:[0,1,0]
	v_pk_fma_f32 v[184:185], v[204:205], v[230:231], v[184:185] op_sel_hi:[1,0,1] neg_lo:[0,1,0] neg_hi:[0,1,0]
	ds_read_b128 v[202:205], v233 offset:12720
	v_pk_fma_f32 v[186:187], v[206:207], v[230:231], v[186:187] op_sel_hi:[1,0,1] neg_lo:[0,1,0] neg_hi:[0,1,0]
	v_pk_fma_f32 v[188:189], v[208:209], v[230:231], v[188:189] op_sel_hi:[1,0,1] neg_lo:[0,1,0] neg_hi:[0,1,0]
	ds_read_b128 v[206:209], v233 offset:12736
	s_waitcnt lgkmcnt(4)
	v_pk_fma_f32 v[190:191], v[226:227], v[230:231], v[190:191] op_sel_hi:[1,0,1] neg_lo:[0,1,0] neg_hi:[0,1,0]
	v_pk_fma_f32 v[192:193], v[228:229], v[230:231], v[192:193] op_sel_hi:[1,0,1] neg_lo:[0,1,0] neg_hi:[0,1,0]
	ds_read_b128 v[226:229], v233 offset:12752
	s_nop 0
	v_mov_b32_e32 v230, v152
	v_cvt_pk_bf16_f32 v232, v230, v230
	global_store_short v28, v232, s[0:1]
	s_add_u32 s0, s0, 0x400
	s_addc_u32 s1, s1, 0
	s_waitcnt lgkmcnt(3)
	v_pk_fma_f32 v[152:153], v[196:197], v[230:231], v[152:153] op_sel_hi:[1,0,1] neg_lo:[0,1,0] neg_hi:[0,1,0]
	v_pk_fma_f32 v[154:155], v[198:199], v[230:231], v[154:155] op_sel_hi:[1,0,1] neg_lo:[0,1,0] neg_hi:[0,1,0]
	v_pk_fma_f32 v[180:181], v[200:201], v[230:231], v[180:181] op_sel_hi:[1,0,1] neg_lo:[0,1,0] neg_hi:[0,1,0]
	ds_read_b128 v[198:201], v233 offset:12976
	s_waitcnt lgkmcnt(2)
	v_pk_fma_f32 v[182:183], v[202:203], v[230:231], v[182:183] op_sel_hi:[1,0,1] neg_lo:[0,1,0] neg_hi:[0,1,0]
	v_pk_fma_f32 v[184:185], v[204:205], v[230:231], v[184:185] op_sel_hi:[1,0,1] neg_lo:[0,1,0] neg_hi:[0,1,0]
	ds_read_b128 v[202:205], v233 offset:12992
	v_pk_fma_f32 v[186:187], v[206:207], v[230:231], v[186:187] op_sel_hi:[1,0,1] neg_lo:[0,1,0] neg_hi:[0,1,0]
	v_pk_fma_f32 v[188:189], v[208:209], v[230:231], v[188:189] op_sel_hi:[1,0,1] neg_lo:[0,1,0] neg_hi:[0,1,0]
	ds_read_b128 v[206:209], v233 offset:13008
	s_waitcnt lgkmcnt(3)
	v_pk_fma_f32 v[190:191], v[226:227], v[230:231], v[190:191] op_sel_hi:[1,0,1] neg_lo:[0,1,0] neg_hi:[0,1,0]
	v_pk_fma_f32 v[192:193], v[228:229], v[230:231], v[192:193] op_sel_hi:[1,0,1] neg_lo:[0,1,0] neg_hi:[0,1,0]
	ds_read_b128 v[226:229], v233 offset:13024
	s_nop 0
	v_mov_b32_e32 v230, v153
	v_cvt_pk_bf16_f32 v232, v230, v230
	global_store_short v28, v232, s[0:1]
	s_add_u32 s0, s0, 0x400
	s_addc_u32 s1, s1, 0
	s_waitcnt lgkmcnt(2)
	v_pk_fma_f32 v[154:155], v[198:199], v[230:231], v[154:155] op_sel_hi:[1,0,1] neg_lo:[0,1,0] neg_hi:[0,1,0]
	v_pk_fma_f32 v[180:181], v[200:201], v[230:231], v[180:181] op_sel_hi:[1,0,1] neg_lo:[0,1,0] neg_hi:[0,1,0]
	ds_read_b128 v[198:201], v233 offset:13248
	v_pk_fma_f32 v[182:183], v[202:203], v[230:231], v[182:183] op_sel_hi:[1,0,1] neg_lo:[0,1,0] neg_hi:[0,1,0]
	v_pk_fma_f32 v[184:185], v[204:205], v[230:231], v[184:185] op_sel_hi:[1,0,1] neg_lo:[0,1,0] neg_hi:[0,1,0]
	ds_read_b128 v[202:205], v233 offset:13264
	s_waitcnt lgkmcnt(2)
	v_pk_fma_f32 v[186:187], v[206:207], v[230:231], v[186:187] op_sel_hi:[1,0,1] neg_lo:[0,1,0] neg_hi:[0,1,0]
	v_pk_fma_f32 v[188:189], v[208:209], v[230:231], v[188:189] op_sel_hi:[1,0,1] neg_lo:[0,1,0] neg_hi:[0,1,0]
	ds_read_b128 v[206:209], v233 offset:13280
	v_pk_fma_f32 v[190:191], v[226:227], v[230:231], v[190:191] op_sel_hi:[1,0,1] neg_lo:[0,1,0] neg_hi:[0,1,0]
	v_pk_fma_f32 v[192:193], v[228:229], v[230:231], v[192:193] op_sel_hi:[1,0,1] neg_lo:[0,1,0] neg_hi:[0,1,0]
	ds_read_b128 v[226:229], v233 offset:13296
	s_nop 0
	v_mov_b32_e32 v230, v154
	v_cvt_pk_bf16_f32 v232, v230, v230
	global_store_short v28, v232, s[0:1]
	s_add_u32 s0, s0, 0x400
	s_addc_u32 s1, s1, 0
	s_waitcnt lgkmcnt(2)
	v_pk_fma_f32 v[154:155], v[198:199], v[230:231], v[154:155] op_sel_hi:[1,0,1] neg_lo:[0,1,0] neg_hi:[0,1,0]
	v_pk_fma_f32 v[180:181], v[200:201], v[230:231], v[180:181] op_sel_hi:[1,0,1] neg_lo:[0,1,0] neg_hi:[0,1,0]
	ds_read_b128 v[198:201], v233 offset:13520
	v_pk_fma_f32 v[182:183], v[202:203], v[230:231], v[182:183] op_sel_hi:[1,0,1] neg_lo:[0,1,0] neg_hi:[0,1,0]
	v_pk_fma_f32 v[184:185], v[204:205], v[230:231], v[184:185] op_sel_hi:[1,0,1] neg_lo:[0,1,0] neg_hi:[0,1,0]
	ds_read_b128 v[202:205], v233 offset:13536
	s_waitcnt lgkmcnt(2)
	v_pk_fma_f32 v[186:187], v[206:207], v[230:231], v[186:187] op_sel_hi:[1,0,1] neg_lo:[0,1,0] neg_hi:[0,1,0]
	v_pk_fma_f32 v[188:189], v[208:209], v[230:231], v[188:189] op_sel_hi:[1,0,1] neg_lo:[0,1,0] neg_hi:[0,1,0]
	ds_read_b128 v[206:209], v233 offset:13552
	v_pk_fma_f32 v[190:191], v[226:227], v[230:231], v[190:191] op_sel_hi:[1,0,1] neg_lo:[0,1,0] neg_hi:[0,1,0]
	v_pk_fma_f32 v[192:193], v[228:229], v[230:231], v[192:193] op_sel_hi:[1,0,1] neg_lo:[0,1,0] neg_hi:[0,1,0]
	ds_read_b128 v[226:229], v233 offset:13568
	s_nop 0
	v_mov_b32_e32 v230, v155
	v_cvt_pk_bf16_f32 v232, v230, v230
	global_store_short v28, v232, s[0:1]
	s_add_u32 s0, s0, 0x400
	s_addc_u32 s1, s1, 0
	s_waitcnt lgkmcnt(2)
	v_pk_fma_f32 v[180:181], v[200:201], v[230:231], v[180:181] op_sel_hi:[1,0,1] neg_lo:[0,1,0] neg_hi:[0,1,0]
	ds_read_b128 v[198:201], v233 offset:13792
	v_pk_fma_f32 v[182:183], v[202:203], v[230:231], v[182:183] op_sel_hi:[1,0,1] neg_lo:[0,1,0] neg_hi:[0,1,0]
	v_pk_fma_f32 v[184:185], v[204:205], v[230:231], v[184:185] op_sel_hi:[1,0,1] neg_lo:[0,1,0] neg_hi:[0,1,0]
	ds_read_b128 v[202:205], v233 offset:13808
	s_waitcnt lgkmcnt(2)
	v_pk_fma_f32 v[186:187], v[206:207], v[230:231], v[186:187] op_sel_hi:[1,0,1] neg_lo:[0,1,0] neg_hi:[0,1,0]
	v_pk_fma_f32 v[188:189], v[208:209], v[230:231], v[188:189] op_sel_hi:[1,0,1] neg_lo:[0,1,0] neg_hi:[0,1,0]
	ds_read_b128 v[206:209], v233 offset:13824
	v_pk_fma_f32 v[190:191], v[226:227], v[230:231], v[190:191] op_sel_hi:[1,0,1] neg_lo:[0,1,0] neg_hi:[0,1,0]
	v_pk_fma_f32 v[192:193], v[228:229], v[230:231], v[192:193] op_sel_hi:[1,0,1] neg_lo:[0,1,0] neg_hi:[0,1,0]
	ds_read_b128 v[226:229], v233 offset:13840
	s_nop 0
	v_mov_b32_e32 v230, v180
	v_cvt_pk_bf16_f32 v232, v230, v230
	global_store_short v28, v232, s[0:1]
	s_add_u32 s0, s0, 0x400
	s_addc_u32 s1, s1, 0
	s_waitcnt lgkmcnt(2)
	v_pk_fma_f32 v[180:181], v[200:201], v[230:231], v[180:181] op_sel_hi:[1,0,1] neg_lo:[0,1,0] neg_hi:[0,1,0]
	v_pk_fma_f32 v[182:183], v[202:203], v[230:231], v[182:183] op_sel_hi:[1,0,1] neg_lo:[0,1,0] neg_hi:[0,1,0]
	v_pk_fma_f32 v[184:185], v[204:205], v[230:231], v[184:185] op_sel_hi:[1,0,1] neg_lo:[0,1,0] neg_hi:[0,1,0]
	ds_read_b128 v[202:205], v233 offset:14080
	s_waitcnt lgkmcnt(1)
	v_pk_fma_f32 v[186:187], v[206:207], v[230:231], v[186:187] op_sel_hi:[1,0,1] neg_lo:[0,1,0] neg_hi:[0,1,0]
	v_pk_fma_f32 v[188:189], v[208:209], v[230:231], v[188:189] op_sel_hi:[1,0,1] neg_lo:[0,1,0] neg_hi:[0,1,0]
	ds_read_b128 v[206:209], v233 offset:14096
	v_pk_fma_f32 v[190:191], v[226:227], v[230:231], v[190:191] op_sel_hi:[1,0,1] neg_lo:[0,1,0] neg_hi:[0,1,0]
	v_pk_fma_f32 v[192:193], v[228:229], v[230:231], v[192:193] op_sel_hi:[1,0,1] neg_lo:[0,1,0] neg_hi:[0,1,0]
	ds_read_b128 v[226:229], v233 offset:14112
	s_nop 0
	v_mov_b32_e32 v230, v181
	v_cvt_pk_bf16_f32 v232, v230, v230
	global_store_short v28, v232, s[0:1]
	s_add_u32 s0, s0, 0x400
	s_addc_u32 s1, s1, 0
	s_waitcnt lgkmcnt(1)
	v_pk_fma_f32 v[182:183], v[202:203], v[230:231], v[182:183] op_sel_hi:[1,0,1] neg_lo:[0,1,0] neg_hi:[0,1,0]
	v_pk_fma_f32 v[184:185], v[204:205], v[230:231], v[184:185] op_sel_hi:[1,0,1] neg_lo:[0,1,0] neg_hi:[0,1,0]
	ds_read_b128 v[202:205], v233 offset:14352
	v_pk_fma_f32 v[186:187], v[206:207], v[230:231], v[186:187] op_sel_hi:[1,0,1] neg_lo:[0,1,0] neg_hi:[0,1,0]
	v_pk_fma_f32 v[188:189], v[208:209], v[230:231], v[188:189] op_sel_hi:[1,0,1] neg_lo:[0,1,0] neg_hi:[0,1,0]
	ds_read_b128 v[206:209], v233 offset:14368
	s_waitcnt lgkmcnt(2)
	v_pk_fma_f32 v[190:191], v[226:227], v[230:231], v[190:191] op_sel_hi:[1,0,1] neg_lo:[0,1,0] neg_hi:[0,1,0]
	v_pk_fma_f32 v[192:193], v[228:229], v[230:231], v[192:193] op_sel_hi:[1,0,1] neg_lo:[0,1,0] neg_hi:[0,1,0]
	ds_read_b128 v[226:229], v233 offset:14384
	s_nop 0
	v_mov_b32_e32 v230, v182
	v_cvt_pk_bf16_f32 v232, v230, v230
	global_store_short v28, v232, s[0:1]
	s_add_u32 s0, s0, 0x400
	s_addc_u32 s1, s1, 0
	s_waitcnt lgkmcnt(1)
	v_pk_fma_f32 v[182:183], v[202:203], v[230:231], v[182:183] op_sel_hi:[1,0,1] neg_lo:[0,1,0] neg_hi:[0,1,0]
	v_pk_fma_f32 v[184:185], v[204:205], v[230:231], v[184:185] op_sel_hi:[1,0,1] neg_lo:[0,1,0] neg_hi:[0,1,0]
	ds_read_b128 v[202:205], v233 offset:14624
	v_pk_fma_f32 v[186:187], v[206:207], v[230:231], v[186:187] op_sel_hi:[1,0,1] neg_lo:[0,1,0] neg_hi:[0,1,0]
	v_pk_fma_f32 v[188:189], v[208:209], v[230:231], v[188:189] op_sel_hi:[1,0,1] neg_lo:[0,1,0] neg_hi:[0,1,0]
	ds_read_b128 v[206:209], v233 offset:14640
	s_waitcnt lgkmcnt(2)
	v_pk_fma_f32 v[190:191], v[226:227], v[230:231], v[190:191] op_sel_hi:[1,0,1] neg_lo:[0,1,0] neg_hi:[0,1,0]
	v_pk_fma_f32 v[192:193], v[228:229], v[230:231], v[192:193] op_sel_hi:[1,0,1] neg_lo:[0,1,0] neg_hi:[0,1,0]
	ds_read_b128 v[226:229], v233 offset:14656
	s_nop 0
	v_mov_b32_e32 v230, v183
	v_cvt_pk_bf16_f32 v232, v230, v230
	global_store_short v28, v232, s[0:1]
	s_add_u32 s0, s0, 0x400
	s_addc_u32 s1, s1, 0
	s_waitcnt lgkmcnt(1)
	v_pk_fma_f32 v[184:185], v[204:205], v[230:231], v[184:185] op_sel_hi:[1,0,1] neg_lo:[0,1,0] neg_hi:[0,1,0]
	ds_read_b128 v[202:205], v233 offset:14896
	v_pk_fma_f32 v[186:187], v[206:207], v[230:231], v[186:187] op_sel_hi:[1,0,1] neg_lo:[0,1,0] neg_hi:[0,1,0]
	v_pk_fma_f32 v[188:189], v[208:209], v[230:231], v[188:189] op_sel_hi:[1,0,1] neg_lo:[0,1,0] neg_hi:[0,1,0]
	ds_read_b128 v[206:209], v233 offset:14912
	s_waitcnt lgkmcnt(2)
	v_pk_fma_f32 v[190:191], v[226:227], v[230:231], v[190:191] op_sel_hi:[1,0,1] neg_lo:[0,1,0] neg_hi:[0,1,0]
	v_pk_fma_f32 v[192:193], v[228:229], v[230:231], v[192:193] op_sel_hi:[1,0,1] neg_lo:[0,1,0] neg_hi:[0,1,0]
	ds_read_b128 v[226:229], v233 offset:14928
	s_nop 0
	v_mov_b32_e32 v230, v184
	v_cvt_pk_bf16_f32 v232, v230, v230
	global_store_short v28, v232, s[0:1]
	s_add_u32 s0, s0, 0x400
	s_addc_u32 s1, s1, 0
	s_waitcnt lgkmcnt(1)
	v_pk_fma_f32 v[184:185], v[204:205], v[230:231], v[184:185] op_sel_hi:[1,0,1] neg_lo:[0,1,0] neg_hi:[0,1,0]
	v_pk_fma_f32 v[186:187], v[206:207], v[230:231], v[186:187] op_sel_hi:[1,0,1] neg_lo:[0,1,0] neg_hi:[0,1,0]
	v_pk_fma_f32 v[188:189], v[208:209], v[230:231], v[188:189] op_sel_hi:[1,0,1] neg_lo:[0,1,0] neg_hi:[0,1,0]
	ds_read_b128 v[206:209], v233 offset:15184
	s_waitcnt lgkmcnt(1)
	v_pk_fma_f32 v[190:191], v[226:227], v[230:231], v[190:191] op_sel_hi:[1,0,1] neg_lo:[0,1,0] neg_hi:[0,1,0]
	v_pk_fma_f32 v[192:193], v[228:229], v[230:231], v[192:193] op_sel_hi:[1,0,1] neg_lo:[0,1,0] neg_hi:[0,1,0]
	ds_read_b128 v[226:229], v233 offset:15200
	s_nop 0
	v_mov_b32_e32 v230, v185
	v_cvt_pk_bf16_f32 v232, v230, v230
	global_store_short v28, v232, s[0:1]
	s_add_u32 s0, s0, 0x400
	s_addc_u32 s1, s1, 0
	s_waitcnt lgkmcnt(0)
	v_pk_fma_f32 v[186:187], v[206:207], v[230:231], v[186:187] op_sel_hi:[1,0,1] neg_lo:[0,1,0] neg_hi:[0,1,0]
	v_pk_fma_f32 v[188:189], v[208:209], v[230:231], v[188:189] op_sel_hi:[1,0,1] neg_lo:[0,1,0] neg_hi:[0,1,0]
	ds_read_b128 v[206:209], v233 offset:15456
	v_pk_fma_f32 v[190:191], v[226:227], v[230:231], v[190:191] op_sel_hi:[1,0,1] neg_lo:[0,1,0] neg_hi:[0,1,0]
	v_pk_fma_f32 v[192:193], v[228:229], v[230:231], v[192:193] op_sel_hi:[1,0,1] neg_lo:[0,1,0] neg_hi:[0,1,0]
	ds_read_b128 v[226:229], v233 offset:15472
	s_nop 0
	v_mov_b32_e32 v230, v186
	v_cvt_pk_bf16_f32 v232, v230, v230
	global_store_short v28, v232, s[0:1]
	s_add_u32 s0, s0, 0x400
	s_addc_u32 s1, s1, 0
	s_waitcnt lgkmcnt(0)
	v_pk_fma_f32 v[186:187], v[206:207], v[230:231], v[186:187] op_sel_hi:[1,0,1] neg_lo:[0,1,0] neg_hi:[0,1,0]
	v_pk_fma_f32 v[188:189], v[208:209], v[230:231], v[188:189] op_sel_hi:[1,0,1] neg_lo:[0,1,0] neg_hi:[0,1,0]
	ds_read_b128 v[206:209], v233 offset:15728
	v_pk_fma_f32 v[190:191], v[226:227], v[230:231], v[190:191] op_sel_hi:[1,0,1] neg_lo:[0,1,0] neg_hi:[0,1,0]
	v_pk_fma_f32 v[192:193], v[228:229], v[230:231], v[192:193] op_sel_hi:[1,0,1] neg_lo:[0,1,0] neg_hi:[0,1,0]
	ds_read_b128 v[226:229], v233 offset:15744
	s_nop 0
	v_mov_b32_e32 v230, v187
	v_cvt_pk_bf16_f32 v232, v230, v230
	global_store_short v28, v232, s[0:1]
	s_add_u32 s0, s0, 0x400
	s_addc_u32 s1, s1, 0
	s_waitcnt lgkmcnt(0)
	v_pk_fma_f32 v[188:189], v[208:209], v[230:231], v[188:189] op_sel_hi:[1,0,1] neg_lo:[0,1,0] neg_hi:[0,1,0]
	ds_read_b128 v[206:209], v233 offset:16000
	v_pk_fma_f32 v[190:191], v[226:227], v[230:231], v[190:191] op_sel_hi:[1,0,1] neg_lo:[0,1,0] neg_hi:[0,1,0]
	v_pk_fma_f32 v[192:193], v[228:229], v[230:231], v[192:193] op_sel_hi:[1,0,1] neg_lo:[0,1,0] neg_hi:[0,1,0]
	ds_read_b128 v[226:229], v233 offset:16016
	s_nop 0
	v_mov_b32_e32 v230, v188
	v_cvt_pk_bf16_f32 v232, v230, v230
	global_store_short v28, v232, s[0:1]
	s_add_u32 s0, s0, 0x400
	s_addc_u32 s1, s1, 0
	s_waitcnt lgkmcnt(0)
	v_pk_fma_f32 v[188:189], v[208:209], v[230:231], v[188:189] op_sel_hi:[1,0,1] neg_lo:[0,1,0] neg_hi:[0,1,0]
	v_pk_fma_f32 v[190:191], v[226:227], v[230:231], v[190:191] op_sel_hi:[1,0,1] neg_lo:[0,1,0] neg_hi:[0,1,0]
	v_pk_fma_f32 v[192:193], v[228:229], v[230:231], v[192:193] op_sel_hi:[1,0,1] neg_lo:[0,1,0] neg_hi:[0,1,0]
	ds_read_b128 v[226:229], v233 offset:16288
	s_nop 0
	v_mov_b32_e32 v230, v189
	v_cvt_pk_bf16_f32 v232, v230, v230
	global_store_short v28, v232, s[0:1]
	s_add_u32 s0, s0, 0x400
	s_addc_u32 s1, s1, 0
	s_waitcnt lgkmcnt(0)
	v_pk_fma_f32 v[190:191], v[226:227], v[230:231], v[190:191] op_sel_hi:[1,0,1] neg_lo:[0,1,0] neg_hi:[0,1,0]
	v_pk_fma_f32 v[192:193], v[228:229], v[230:231], v[192:193] op_sel_hi:[1,0,1] neg_lo:[0,1,0] neg_hi:[0,1,0]
	ds_read_b128 v[226:229], v233 offset:16560
	s_nop 0
	v_mov_b32_e32 v230, v190
	v_cvt_pk_bf16_f32 v232, v230, v230
	global_store_short v28, v232, s[0:1]
	s_add_u32 s0, s0, 0x400
	s_addc_u32 s1, s1, 0
	s_waitcnt lgkmcnt(0)
	v_pk_fma_f32 v[190:191], v[226:227], v[230:231], v[190:191] op_sel_hi:[1,0,1] neg_lo:[0,1,0] neg_hi:[0,1,0]
	v_pk_fma_f32 v[192:193], v[228:229], v[230:231], v[192:193] op_sel_hi:[1,0,1] neg_lo:[0,1,0] neg_hi:[0,1,0]
	ds_read_b128 v[226:229], v233 offset:16832
	s_nop 0
	v_mov_b32_e32 v230, v191
	v_cvt_pk_bf16_f32 v232, v230, v230
	global_store_short v28, v232, s[0:1]
	s_add_u32 s0, s0, 0x400
	s_addc_u32 s1, s1, 0
	s_waitcnt lgkmcnt(0)
	v_pk_fma_f32 v[192:193], v[228:229], v[230:231], v[192:193] op_sel_hi:[1,0,1] neg_lo:[0,1,0] neg_hi:[0,1,0]
	ds_read_b128 v[226:229], v233 offset:17104
	s_nop 0
	v_mov_b32_e32 v230, v192
	v_cvt_pk_bf16_f32 v232, v230, v230
	global_store_short v28, v232, s[0:1]
	s_add_u32 s0, s0, 0x400
	s_addc_u32 s1, s1, 0
	s_waitcnt lgkmcnt(0)
	v_pk_fma_f32 v[192:193], v[228:229], v[230:231], v[192:193] op_sel_hi:[1,0,1] neg_lo:[0,1,0] neg_hi:[0,1,0]
	s_nop 0
	v_cvt_pk_bf16_f32 v232, v193, v193
	global_store_short v28, v232, s[0:1]
